# K-loops: scalar/address arithmetic behind each segment's closing barrier moved in front of the s_setprio 0 / s_barrier pair (back-edge rotation, docs 7.11)
# baseline (speedup 1.0000x reference)
; #define PG8_STAGE(bufoff, gbase, voff) do { _Pragma("unroll") for (int _i = 0; _i < 2; ++_i) \
;         __builtin_amdgcn_global_load_lds((const unsigned*)((const char*)(gbase) + (voff)[_i]), (PG8_LAS unsigned*)(lds + (bufoff) + ldsw + _i * 8192), 16, 0, 0); } while (0)
; #define PG8_LDA(dst, b, h) do { _Pragma("unroll") for (int m = 0; m < 4; ++m) _Pragma("unroll") for (int k = 0; k < 2; ++k) dst[m][k] = *(const PG8_LAS bf16x8*)(lds + PG8_SA(b, h) + aoff + m * 2048 + k * 1024); } while (0)
; #define PG8_LDB(dst, b, h) do { _Pragma("unroll") for (int n = 0; n < 2; ++n) _Pragma("unroll") for (int k = 0; k < 2; ++k) dst[n][k] = *(const PG8_LAS bf16x8*)(lds + PG8_SB(b, h) + boff + n * 2048 + k * 1024); } while (0)
; #define PG8_MMA(ai, bj, At, Bt) do { __builtin_amdgcn_s_setprio(1); _Pragma("unroll") for (int m = 0; m < 4; ++m) _Pragma("unroll") for (int n = 0; n < 2; ++n) _Pragma("unroll") for (int k = 0; k < 2; ++k) \
;         acc[ai][bj][m][n] = __builtin_amdgcn_mfma_f32_16x16x32_bf16(Bt[n][k], At[m][k], acc[ai][bj][m][n], 0, 0, 0); __builtin_amdgcn_s_setprio(0); } while (0)
; #define PG8_WAIT_V(n) asm volatile("s_waitcnt vmcnt(" #n ")" ::: "memory")
; #define PG8_BAR __builtin_amdgcn_s_barrier()
; template <class Epi, class Sched, bool ALIGN_EPI = false, bool SP2 = false>
; __device__ __forceinline__ void gemm_phase(PG8_LAS unsigned char* lds, const Gemm g, const Sched& S, const Epi& E) {
;     ...
;         for (int t = 0; t < nt; t += 2) {
;             const bool last = (t == nt - 2);
;             const char* a1 = cA + (size_t)(t + 1) * kstep;
;             const char* a2 = last ? nA : cA + (size_t)(t + 2) * kstep; const char* b2 = last ? nB : cB + (size_t)(t + 2) * kstep;
;             const char* a3 = a2 + kstep; const char* b3 = b2 + kstep;
;             if (last && has_next) S.a_ready(nxt);
;             if constexpr (SP2) {
;             PG8_LDB(B0, 0, 0); PG8_LDB(B1, 0, 1); PG8_SCHED; PG8_LDA(At, 0, 0); PG8_STAGE(PG8_SA(1, 1), a1 + hstep, voffA);
;             PG8_WAIT_V(8); PG8_WAIT_L(0); PG8_BAR; PG8_MMA(0, 0, At, B0); PG8_MMA(0, 1, At, B1); PG8_BAR; PG8_SCHED;
;             PG8_LDA(At, 0, 1); PG8_STAGE(PG8_SB(0, 0), b2, voffB); PG8_STAGE(PG8_SB(0, 1), b2 + hstep, voffB); PG8_STAGE(PG8_SA(0, 0), a2, voffA);
;             PG8_WAIT_V(8); PG8_WAIT_L(0); PG8_BAR; PG8_MMA(1, 0, At, B0); PG8_MMA(1, 1, At, B1); PG8_BAR; PG8_SCHED;
.LBB0_96:
	ds_read_b128 v[128:131], v178
	ds_read_b128 v[132:135], v178 offset:1024
	ds_read_b128 v[136:139], v178 offset:2048
	ds_read_b128 v[140:143], v178 offset:3072
	ds_read_b128 v[166:169], v179
	ds_read_b128 v[170:173], v179 offset:1024
	ds_read_b128 v[190:193], v179 offset:2048
	ds_read_b128 v[194:197], v179 offset:3072
	s_add_u32 s36, s80, 0xfffc0080
	s_addc_u32 s37, s81, -1
	s_cmp_eq_u32 s35, 12
	s_cselect_b32 s87, s8, s37
	s_cselect_b32 s86, s55, s36
	s_cselect_b32 s83, s49, s34
	s_cselect_b32 s82, vcc_lo, vcc_hi
	s_add_i32 m0, s93, 0xc000
	ds_read_b128 v[198:201], v181
	ds_read_b128 v[202:205], v181 offset:1024
	ds_read_b128 v[206:209], v181 offset:2048
	ds_read_b128 v[210:213], v181 offset:3072
	ds_read_b128 v[214:217], v181 offset:4096
	ds_read_b128 v[218:221], v181 offset:5120
	ds_read_b128 v[222:225], v181 offset:6144
	ds_read_b128 v[226:229], v181 offset:7168
	global_load_lds_dwordx4 v158, s[80:81]
	s_add_i32 m0, s93, 0xe000
	s_nop 0
	global_load_lds_dwordx4 v160, s[80:81]
	s_waitcnt vmcnt(8)
	s_waitcnt lgkmcnt(0)
	s_barrier
	s_setprio 1
	v_mfma_f32_16x16x32_bf16 v[124:127], v[128:131], v[198:201], v[124:127]
	v_mfma_f32_16x16x32_bf16 v[120:123], v[136:139], v[198:201], v[120:123]
	v_mfma_f32_16x16x32_bf16 v[108:111], v[128:131], v[206:209], v[108:111]
	v_mfma_f32_16x16x32_bf16 v[104:107], v[136:139], v[206:209], v[104:107]
	v_mfma_f32_16x16x32_bf16 v[92:95], v[128:131], v[214:217], v[92:95]
	v_mfma_f32_16x16x32_bf16 v[88:91], v[136:139], v[214:217], v[88:91]
	v_mfma_f32_16x16x32_bf16 v[76:79], v[128:131], v[222:225], v[76:79]
	v_mfma_f32_16x16x32_bf16 v[72:75], v[136:139], v[222:225], v[72:75]
	v_mfma_f32_16x16x32_bf16 v[124:127], v[132:135], v[202:205], v[124:127]
	v_mfma_f32_16x16x32_bf16 v[120:123], v[140:143], v[202:205], v[120:123]
	v_mfma_f32_16x16x32_bf16 v[108:111], v[132:135], v[210:213], v[108:111]
	v_mfma_f32_16x16x32_bf16 v[104:107], v[140:143], v[210:213], v[104:107]
	v_mfma_f32_16x16x32_bf16 v[92:95], v[132:135], v[218:221], v[92:95]
	v_mfma_f32_16x16x32_bf16 v[88:91], v[140:143], v[218:221], v[88:91]
	v_mfma_f32_16x16x32_bf16 v[76:79], v[132:135], v[226:229], v[76:79]
	v_mfma_f32_16x16x32_bf16 v[72:75], v[140:143], v[226:229], v[72:75]
	v_mfma_f32_16x16x32_bf16 v[116:119], v[166:169], v[198:201], v[116:119]
	v_mfma_f32_16x16x32_bf16 v[112:115], v[190:193], v[198:201], v[112:115]
	v_mfma_f32_16x16x32_bf16 v[100:103], v[166:169], v[206:209], v[100:103]
	v_mfma_f32_16x16x32_bf16 v[96:99], v[190:193], v[206:209], v[96:99]
	v_mfma_f32_16x16x32_bf16 v[84:87], v[166:169], v[214:217], v[84:87]
	v_mfma_f32_16x16x32_bf16 v[80:83], v[190:193], v[214:217], v[80:83]
	v_mfma_f32_16x16x32_bf16 v[68:71], v[166:169], v[222:225], v[68:71]
	v_mfma_f32_16x16x32_bf16 v[64:67], v[190:193], v[222:225], v[64:67]
	v_mfma_f32_16x16x32_bf16 v[116:119], v[170:173], v[202:205], v[116:119]
	v_mfma_f32_16x16x32_bf16 v[112:115], v[194:197], v[202:205], v[112:115]
	v_mfma_f32_16x16x32_bf16 v[100:103], v[170:173], v[210:213], v[100:103]
	v_mfma_f32_16x16x32_bf16 v[96:99], v[194:197], v[210:213], v[96:99]
	v_mfma_f32_16x16x32_bf16 v[84:87], v[170:173], v[218:221], v[84:87]
	v_mfma_f32_16x16x32_bf16 v[80:83], v[194:197], v[218:221], v[80:83]
	v_mfma_f32_16x16x32_bf16 v[68:71], v[170:173], v[226:229], v[68:71]
	v_mfma_f32_16x16x32_bf16 v[64:67], v[194:197], v[226:229], v[64:67]
	s_add_i32 s36, s23, s90
	v_lshl_add_u64 v[174:175], s[82:83], 0, v[148:149]
	s_setprio 0
	s_barrier
	s_mov_b32 m0, s36
	ds_read_b128 v[198:201], v181 offset:16384
	ds_read_b128 v[202:205], v181 offset:17408
	ds_read_b128 v[206:209], v181 offset:18432
	ds_read_b128 v[210:213], v181 offset:19456
	ds_read_b128 v[214:217], v181 offset:20480
	ds_read_b128 v[218:221], v181 offset:21504
	ds_read_b128 v[222:225], v181 offset:22528
	ds_read_b128 v[226:229], v181 offset:23552
	global_load_lds_dwordx4 v[174:175], off
	s_add_i32 m0, s36, 0x2000
	s_add_u32 s36, s82, 0x40000
	v_lshl_add_u64 v[186:187], s[82:83], 0, v[144:145]
	s_addc_u32 s37, s83, 0
	s_add_i32 s20, s41, s90
	global_load_lds_dwordx4 v[186:187], off
	s_mov_b32 m0, s20
	v_lshl_add_u64 v[232:233], s[86:87], 0, v[146:147]
	global_load_lds_dwordx4 v148, s[36:37]
	s_add_i32 m0, s20, 0x2000
	s_nop 0
	global_load_lds_dwordx4 v144, s[36:37]
	v_lshl_add_u64 v[230:231], s[86:87], 0, v[150:151]
	s_mov_b32 m0, s93
	s_nop 0
	global_load_lds_dwordx4 v[230:231], off
	s_mov_b32 m0, s94
	s_nop 0
	global_load_lds_dwordx4 v[232:233], off
	s_waitcnt vmcnt(8)
	s_waitcnt lgkmcnt(0)
	s_barrier
; #define PG8_STAGE(bufoff, gbase, voff) do { _Pragma("unroll") for (int _i = 0; _i < 2; ++_i) \
;         __builtin_amdgcn_global_load_lds((const unsigned*)((const char*)(gbase) + (voff)[_i]), (PG8_LAS unsigned*)(lds + (bufoff) + ldsw + _i * 8192), 16, 0, 0); } while (0)
; #define PG8_LDA(dst, b, h) do { _Pragma("unroll") for (int m = 0; m < 4; ++m) _Pragma("unroll") for (int k = 0; k < 2; ++k) dst[m][k] = *(const PG8_LAS bf16x8*)(lds + PG8_SA(b, h) + aoff + m * 2048 + k * 1024); } while (0)
; #define PG8_LDB(dst, b, h) do { _Pragma("unroll") for (int n = 0; n < 2; ++n) _Pragma("unroll") for (int k = 0; k < 2; ++k) dst[n][k] = *(const PG8_LAS bf16x8*)(lds + PG8_SB(b, h) + boff + n * 2048 + k * 1024); } while (0)
; #define PG8_MMA(ai, bj, At, Bt) do { __builtin_amdgcn_s_setprio(1); _Pragma("unroll") for (int m = 0; m < 4; ++m) _Pragma("unroll") for (int n = 0; n < 2; ++n) _Pragma("unroll") for (int k = 0; k < 2; ++k) \
;         acc[ai][bj][m][n] = __builtin_amdgcn_mfma_f32_16x16x32_bf16(Bt[n][k], At[m][k], acc[ai][bj][m][n], 0, 0, 0); __builtin_amdgcn_s_setprio(0); } while (0)
; #define PG8_WAIT_V(n) asm volatile("s_waitcnt vmcnt(" #n ")" ::: "memory")
; #define PG8_WAIT_L(n) asm volatile("s_waitcnt lgkmcnt(" #n ")" ::: "memory")
; #define PG8_BAR __builtin_amdgcn_s_barrier()
; #define PG8_SCHED __builtin_amdgcn_sched_barrier(0)
; template <class Epi, class Sched, bool ALIGN_EPI = false, bool SP2 = false>
; __device__ __forceinline__ void gemm_phase(PG8_LAS unsigned char* lds, const Gemm g, const Sched& S, const Epi& E) {
;     ...
;             PG8_LDA(At, 0, 1); PG8_STAGE(PG8_SB(0, 0), b2, voffB); PG8_STAGE(PG8_SB(0, 1), b2 + hstep, voffB); PG8_STAGE(PG8_SA(0, 0), a2, voffA);
;             PG8_WAIT_V(8); PG8_WAIT_L(0); PG8_BAR; PG8_MMA(1, 0, At, B0); PG8_MMA(1, 1, At, B1); PG8_BAR; PG8_SCHED;
;             PG8_LDB(B0, 1, 0); PG8_LDB(B1, 1, 1); PG8_SCHED; PG8_LDA(At, 1, 0); PG8_STAGE(PG8_SA(0, 1), a2 + hstep, voffA);
;             PG8_WAIT_V(8); PG8_WAIT_L(0); PG8_BAR; PG8_MMA(0, 0, At, B0); PG8_MMA(0, 1, At, B1); PG8_BAR; PG8_SCHED;
;             PG8_LDA(At, 1, 1); PG8_STAGE(PG8_SB(1, 0), b3, voffB); PG8_STAGE(PG8_SB(1, 1), b3 + hstep, voffB); PG8_STAGE(PG8_SA(1, 0), a3, voffA);
;             PG8_WAIT_V(8); PG8_WAIT_L(0); PG8_BAR; PG8_MMA(1, 0, At, B0); PG8_MMA(1, 1, At, B1); PG8_BAR; PG8_SCHED;
	s_setprio 1
	v_mfma_f32_16x16x32_bf16 v[60:63], v[128:131], v[198:201], v[60:63]
	v_mfma_f32_16x16x32_bf16 v[56:59], v[136:139], v[198:201], v[56:59]
	v_mfma_f32_16x16x32_bf16 v[44:47], v[128:131], v[206:209], v[44:47]
	v_mfma_f32_16x16x32_bf16 v[40:43], v[136:139], v[206:209], v[40:43]
	v_mfma_f32_16x16x32_bf16 v[28:31], v[128:131], v[214:217], v[28:31]
	v_mfma_f32_16x16x32_bf16 v[24:27], v[136:139], v[214:217], v[24:27]
	v_mfma_f32_16x16x32_bf16 v[12:15], v[128:131], v[222:225], v[12:15]
	v_mfma_f32_16x16x32_bf16 v[8:11], v[136:139], v[222:225], v[8:11]
	v_mfma_f32_16x16x32_bf16 v[60:63], v[132:135], v[202:205], v[60:63]
	v_mfma_f32_16x16x32_bf16 v[56:59], v[140:143], v[202:205], v[56:59]
	v_mfma_f32_16x16x32_bf16 v[44:47], v[132:135], v[210:213], v[44:47]
	v_mfma_f32_16x16x32_bf16 v[40:43], v[140:143], v[210:213], v[40:43]
	v_mfma_f32_16x16x32_bf16 v[28:31], v[132:135], v[218:221], v[28:31]
	v_mfma_f32_16x16x32_bf16 v[24:27], v[140:143], v[218:221], v[24:27]
	v_mfma_f32_16x16x32_bf16 v[12:15], v[132:135], v[226:229], v[12:15]
	v_mfma_f32_16x16x32_bf16 v[8:11], v[140:143], v[226:229], v[8:11]
	v_mfma_f32_16x16x32_bf16 v[52:55], v[166:169], v[198:201], v[52:55]
	v_mfma_f32_16x16x32_bf16 v[48:51], v[190:193], v[198:201], v[48:51]
	v_mfma_f32_16x16x32_bf16 v[36:39], v[166:169], v[206:209], v[36:39]
	v_mfma_f32_16x16x32_bf16 v[32:35], v[190:193], v[206:209], v[32:35]
	v_mfma_f32_16x16x32_bf16 v[20:23], v[166:169], v[214:217], v[20:23]
	v_mfma_f32_16x16x32_bf16 v[16:19], v[190:193], v[214:217], v[16:19]
	v_mfma_f32_16x16x32_bf16 v[4:7], v[166:169], v[222:225], v[4:7]
	v_mfma_f32_16x16x32_bf16 v[0:3], v[190:193], v[222:225], v[0:3]
	v_mfma_f32_16x16x32_bf16 v[52:55], v[170:173], v[202:205], v[52:55]
	v_mfma_f32_16x16x32_bf16 v[48:51], v[194:197], v[202:205], v[48:51]
	v_mfma_f32_16x16x32_bf16 v[36:39], v[170:173], v[210:213], v[36:39]
	v_mfma_f32_16x16x32_bf16 v[32:35], v[194:197], v[210:213], v[32:35]
	v_mfma_f32_16x16x32_bf16 v[20:23], v[170:173], v[218:221], v[20:23]
	v_mfma_f32_16x16x32_bf16 v[16:19], v[194:197], v[218:221], v[16:19]
	v_mfma_f32_16x16x32_bf16 v[4:7], v[170:173], v[226:229], v[4:7]
	v_mfma_f32_16x16x32_bf16 v[0:3], v[194:197], v[226:229], v[0:3]
	s_add_i32 s20, 0, 0x18000
	s_add_i32 s21, 0, 0x1c000
	v_add_u32_e32 v140, s20, v176
	v_add_u32_e32 v152, s21, v176
	s_setprio 0
	s_barrier
	ds_read_b128 v[128:131], v140
	ds_read_b128 v[132:135], v140 offset:1024
	ds_read_b128 v[136:139], v140 offset:2048
	ds_read_b128 v[140:143], v140 offset:3072
	ds_read_b128 v[166:169], v152
	ds_read_b128 v[170:173], v152 offset:1024
	ds_read_b128 v[190:193], v152 offset:2048
	ds_read_b128 v[194:197], v152 offset:3072
	s_add_u32 s36, s86, 0x40000
	s_addc_u32 s37, s87, 0
	s_mov_b32 m0, s95
	ds_read_b128 v[198:201], v181 offset:32768
	ds_read_b128 v[202:205], v181 offset:33792
	ds_read_b128 v[206:209], v181 offset:34816
	ds_read_b128 v[210:213], v181 offset:35840
	ds_read_b128 v[214:217], v181 offset:36864
	ds_read_b128 v[218:221], v181 offset:37888
	ds_read_b128 v[222:225], v181 offset:38912
	ds_read_b128 v[226:229], v181 offset:39936
	global_load_lds_dwordx4 v150, s[36:37]
	s_mov_b32 m0, s97
	s_nop 0
	global_load_lds_dwordx4 v146, s[36:37]
	s_waitcnt vmcnt(8)
	s_waitcnt lgkmcnt(0)
	s_barrier
	s_setprio 1
	v_mfma_f32_16x16x32_bf16 v[124:127], v[128:131], v[198:201], v[124:127]
	v_mfma_f32_16x16x32_bf16 v[120:123], v[136:139], v[198:201], v[120:123]
	v_mfma_f32_16x16x32_bf16 v[108:111], v[128:131], v[206:209], v[108:111]
	v_mfma_f32_16x16x32_bf16 v[104:107], v[136:139], v[206:209], v[104:107]
	v_mfma_f32_16x16x32_bf16 v[92:95], v[128:131], v[214:217], v[92:95]
	v_mfma_f32_16x16x32_bf16 v[88:91], v[136:139], v[214:217], v[88:91]
	v_mfma_f32_16x16x32_bf16 v[76:79], v[128:131], v[222:225], v[76:79]
	v_mfma_f32_16x16x32_bf16 v[72:75], v[136:139], v[222:225], v[72:75]
	v_mfma_f32_16x16x32_bf16 v[124:127], v[132:135], v[202:205], v[124:127]
	v_mfma_f32_16x16x32_bf16 v[120:123], v[140:143], v[202:205], v[120:123]
	v_mfma_f32_16x16x32_bf16 v[108:111], v[132:135], v[210:213], v[108:111]
	v_mfma_f32_16x16x32_bf16 v[104:107], v[140:143], v[210:213], v[104:107]
	v_mfma_f32_16x16x32_bf16 v[92:95], v[132:135], v[218:221], v[92:95]
	v_mfma_f32_16x16x32_bf16 v[88:91], v[140:143], v[218:221], v[88:91]
	v_mfma_f32_16x16x32_bf16 v[76:79], v[132:135], v[226:229], v[76:79]
	v_mfma_f32_16x16x32_bf16 v[72:75], v[140:143], v[226:229], v[72:75]
	v_mfma_f32_16x16x32_bf16 v[116:119], v[166:169], v[198:201], v[116:119]
	v_mfma_f32_16x16x32_bf16 v[112:115], v[190:193], v[198:201], v[112:115]
	v_mfma_f32_16x16x32_bf16 v[100:103], v[166:169], v[206:209], v[100:103]
	v_mfma_f32_16x16x32_bf16 v[96:99], v[190:193], v[206:209], v[96:99]
	v_mfma_f32_16x16x32_bf16 v[84:87], v[166:169], v[214:217], v[84:87]
	v_mfma_f32_16x16x32_bf16 v[80:83], v[190:193], v[214:217], v[80:83]
	v_mfma_f32_16x16x32_bf16 v[68:71], v[166:169], v[222:225], v[68:71]
	v_mfma_f32_16x16x32_bf16 v[64:67], v[190:193], v[222:225], v[64:67]
	v_mfma_f32_16x16x32_bf16 v[116:119], v[170:173], v[202:205], v[116:119]
	v_mfma_f32_16x16x32_bf16 v[112:115], v[194:197], v[202:205], v[112:115]
	v_mfma_f32_16x16x32_bf16 v[100:103], v[170:173], v[210:213], v[100:103]
	v_mfma_f32_16x16x32_bf16 v[96:99], v[194:197], v[210:213], v[96:99]
	v_mfma_f32_16x16x32_bf16 v[84:87], v[170:173], v[218:221], v[84:87]
	v_mfma_f32_16x16x32_bf16 v[80:83], v[194:197], v[218:221], v[80:83]
	v_mfma_f32_16x16x32_bf16 v[68:71], v[170:173], v[226:229], v[68:71]
	v_mfma_f32_16x16x32_bf16 v[64:67], v[194:197], v[226:229], v[64:67]
	s_add_i32 s20, s20, s90
	v_lshl_add_u64 v[174:175], v[174:175], 0, s[26:27]
	s_setprio 0
	s_barrier
; #define PG8_STAGE(bufoff, gbase, voff) do { _Pragma("unroll") for (int _i = 0; _i < 2; ++_i) \
;         __builtin_amdgcn_global_load_lds((const unsigned*)((const char*)(gbase) + (voff)[_i]), (PG8_LAS unsigned*)(lds + (bufoff) + ldsw + _i * 8192), 16, 0, 0); } while (0)
; #define PG8_LDA(dst, b, h) do { _Pragma("unroll") for (int m = 0; m < 4; ++m) _Pragma("unroll") for (int k = 0; k < 2; ++k) dst[m][k] = *(const PG8_LAS bf16x8*)(lds + PG8_SA(b, h) + aoff + m * 2048 + k * 1024); } while (0)
; #define PG8_MMA(ai, bj, At, Bt) do { __builtin_amdgcn_s_setprio(1); _Pragma("unroll") for (int m = 0; m < 4; ++m) _Pragma("unroll") for (int n = 0; n < 2; ++n) _Pragma("unroll") for (int k = 0; k < 2; ++k) \
;         acc[ai][bj][m][n] = __builtin_amdgcn_mfma_f32_16x16x32_bf16(Bt[n][k], At[m][k], acc[ai][bj][m][n], 0, 0, 0); __builtin_amdgcn_s_setprio(0); } while (0)
; #define PG8_WAIT_V(n) asm volatile("s_waitcnt vmcnt(" #n ")" ::: "memory")
; #define PG8_WAIT_L(n) asm volatile("s_waitcnt lgkmcnt(" #n ")" ::: "memory")
; #define PG8_BAR __builtin_amdgcn_s_barrier()
; #define PG8_SCHED __builtin_amdgcn_sched_barrier(0)
; template <class Epi, class Sched, bool ALIGN_EPI = false, bool SP2 = false>
; __device__ __forceinline__ void gemm_phase(PG8_LAS unsigned char* lds, const Gemm g, const Sched& S, const Epi& E) {
;     ...
;         for (int t = 0; t < nt; t += 2) {
;             const bool last = (t == nt - 2);
;             const char* a1 = cA + (size_t)(t + 1) * kstep;
;             const char* a2 = last ? nA : cA + (size_t)(t + 2) * kstep; const char* b2 = last ? nB : cB + (size_t)(t + 2) * kstep;
;             const char* a3 = a2 + kstep; const char* b3 = b2 + kstep;
;     ...
;             PG8_LDA(At, 1, 1); PG8_STAGE(PG8_SB(1, 0), b3, voffB); PG8_STAGE(PG8_SB(1, 1), b3 + hstep, voffB); PG8_STAGE(PG8_SA(1, 0), a3, voffA);
;             PG8_WAIT_V(8); PG8_WAIT_L(0); PG8_BAR; PG8_MMA(1, 0, At, B0); PG8_MMA(1, 1, At, B1); PG8_BAR; PG8_SCHED;
	s_mov_b32 m0, s20
	ds_read_b128 v[198:201], v181 offset:49152
	ds_read_b128 v[202:205], v181 offset:50176
	ds_read_b128 v[206:209], v181 offset:51200
	ds_read_b128 v[210:213], v181 offset:52224
	ds_read_b128 v[214:217], v181 offset:53248
	ds_read_b128 v[218:221], v181 offset:54272
	ds_read_b128 v[222:225], v181 offset:55296
	ds_read_b128 v[226:229], v181 offset:56320
	global_load_lds_dwordx4 v[174:175], off
	s_add_i32 m0, s20, 0x2000
	s_add_u32 s36, s82, 0x40080
	v_lshl_add_u64 v[174:175], v[186:187], 0, s[26:27]
	s_addc_u32 s37, s83, 0
	s_add_i32 s20, s21, s90
	global_load_lds_dwordx4 v[174:175], off
	s_mov_b32 m0, s20
	s_nop 0
	global_load_lds_dwordx4 v148, s[36:37]
	s_add_i32 m0, s20, 0x2000
	s_nop 0
	global_load_lds_dwordx4 v144, s[36:37]
	v_lshl_add_u64 v[174:175], v[230:231], 0, s[26:27]
	s_mov_b32 m0, s42
	s_nop 0
	global_load_lds_dwordx4 v[174:175], off
	v_lshl_add_u64 v[174:175], v[232:233], 0, s[26:27]
	s_mov_b32 m0, s43
	s_nop 0
	global_load_lds_dwordx4 v[174:175], off
	s_waitcnt vmcnt(8)
	s_waitcnt lgkmcnt(0)
	s_barrier
	s_setprio 1
	v_mfma_f32_16x16x32_bf16 v[60:63], v[128:131], v[198:201], v[60:63]
	v_mfma_f32_16x16x32_bf16 v[56:59], v[136:139], v[198:201], v[56:59]
	v_mfma_f32_16x16x32_bf16 v[44:47], v[128:131], v[206:209], v[44:47]
	v_mfma_f32_16x16x32_bf16 v[40:43], v[136:139], v[206:209], v[40:43]
	v_mfma_f32_16x16x32_bf16 v[28:31], v[128:131], v[214:217], v[28:31]
	v_mfma_f32_16x16x32_bf16 v[24:27], v[136:139], v[214:217], v[24:27]
	v_mfma_f32_16x16x32_bf16 v[12:15], v[128:131], v[222:225], v[12:15]
	v_mfma_f32_16x16x32_bf16 v[8:11], v[136:139], v[222:225], v[8:11]
	v_mfma_f32_16x16x32_bf16 v[60:63], v[132:135], v[202:205], v[60:63]
	v_mfma_f32_16x16x32_bf16 v[56:59], v[140:143], v[202:205], v[56:59]
	v_mfma_f32_16x16x32_bf16 v[44:47], v[132:135], v[210:213], v[44:47]
	v_mfma_f32_16x16x32_bf16 v[40:43], v[140:143], v[210:213], v[40:43]
	v_mfma_f32_16x16x32_bf16 v[28:31], v[132:135], v[218:221], v[28:31]
	v_mfma_f32_16x16x32_bf16 v[24:27], v[140:143], v[218:221], v[24:27]
	v_mfma_f32_16x16x32_bf16 v[12:15], v[132:135], v[226:229], v[12:15]
	v_mfma_f32_16x16x32_bf16 v[8:11], v[140:143], v[226:229], v[8:11]
	v_mfma_f32_16x16x32_bf16 v[52:55], v[166:169], v[198:201], v[52:55]
	v_mfma_f32_16x16x32_bf16 v[48:51], v[190:193], v[198:201], v[48:51]
	v_mfma_f32_16x16x32_bf16 v[36:39], v[166:169], v[206:209], v[36:39]
	v_mfma_f32_16x16x32_bf16 v[32:35], v[190:193], v[206:209], v[32:35]
	v_mfma_f32_16x16x32_bf16 v[20:23], v[166:169], v[214:217], v[20:23]
	v_mfma_f32_16x16x32_bf16 v[16:19], v[190:193], v[214:217], v[16:19]
	v_mfma_f32_16x16x32_bf16 v[4:7], v[166:169], v[222:225], v[4:7]
	v_mfma_f32_16x16x32_bf16 v[0:3], v[190:193], v[222:225], v[0:3]
	v_mfma_f32_16x16x32_bf16 v[52:55], v[170:173], v[202:205], v[52:55]
	v_mfma_f32_16x16x32_bf16 v[48:51], v[194:197], v[202:205], v[48:51]
	v_mfma_f32_16x16x32_bf16 v[36:39], v[170:173], v[210:213], v[36:39]
	v_mfma_f32_16x16x32_bf16 v[32:35], v[194:197], v[210:213], v[32:35]
	v_mfma_f32_16x16x32_bf16 v[20:23], v[170:173], v[218:221], v[20:23]
	v_mfma_f32_16x16x32_bf16 v[16:19], v[194:197], v[218:221], v[16:19]
	v_mfma_f32_16x16x32_bf16 v[4:7], v[170:173], v[226:229], v[4:7]
	v_mfma_f32_16x16x32_bf16 v[0:3], v[194:197], v[226:229], v[0:3]
	s_add_i32 s35, s35, 2
	s_add_u32 s80, s80, 0x100
	s_addc_u32 s81, s81, 0
	s_add_u32 vcc_hi, vcc_hi, 0x100
	s_addc_u32 s34, s34, 0
	s_cmp_gt_u32 s35, 13
	s_setprio 0
	s_barrier
	s_cbranch_scc0 .LBB0_96
	s_and_b64 vcc, exec, s[28:29]
	s_cbranch_vccz .LBB0_99
	s_barrier

; #define PG8_STAGE(bufoff, gbase, voff) do { _Pragma("unroll") for (int _i = 0; _i < 2; ++_i) \
;         __builtin_amdgcn_global_load_lds((const unsigned*)((const char*)(gbase) + (voff)[_i]), (PG8_LAS unsigned*)(lds + (bufoff) + ldsw + _i * 8192), 16, 0, 0); } while (0)
; #define PG8_LDA(dst, b, h) do { _Pragma("unroll") for (int m = 0; m < 4; ++m) _Pragma("unroll") for (int k = 0; k < 2; ++k) dst[m][k] = *(const PG8_LAS bf16x8*)(lds + PG8_SA(b, h) + aoff + m * 2048 + k * 1024); } while (0)
; #define PG8_LDB(dst, b, h) do { _Pragma("unroll") for (int n = 0; n < 2; ++n) _Pragma("unroll") for (int k = 0; k < 2; ++k) dst[n][k] = *(const PG8_LAS bf16x8*)(lds + PG8_SB(b, h) + boff + n * 2048 + k * 1024); } while (0)
; #define PG8_MMA(ai, bj, At, Bt) do { __builtin_amdgcn_s_setprio(1); _Pragma("unroll") for (int m = 0; m < 4; ++m) _Pragma("unroll") for (int n = 0; n < 2; ++n) _Pragma("unroll") for (int k = 0; k < 2; ++k) \
;         acc[ai][bj][m][n] = __builtin_amdgcn_mfma_f32_16x16x32_bf16(Bt[n][k], At[m][k], acc[ai][bj][m][n], 0, 0, 0); __builtin_amdgcn_s_setprio(0); } while (0)
; #define PG8_WAIT_V(n) asm volatile("s_waitcnt vmcnt(" #n ")" ::: "memory")
; #define PG8_BAR __builtin_amdgcn_s_barrier()
; template <class Epi, class Sched, bool ALIGN_EPI = false, bool SP2 = false>
; __device__ __forceinline__ void gemm_phase(PG8_LAS unsigned char* lds, const Gemm g, const Sched& S, const Epi& E) {
;     ...
;         for (int t = 0; t < nt; t += 2) {
;             const bool last = (t == nt - 2);
;             const char* a1 = cA + (size_t)(t + 1) * kstep;
;             const char* a2 = last ? nA : cA + (size_t)(t + 2) * kstep; const char* b2 = last ? nB : cB + (size_t)(t + 2) * kstep;
;             const char* a3 = a2 + kstep; const char* b3 = b2 + kstep;
;             if (last && has_next) S.a_ready(nxt);
;             if constexpr (SP2) {
;             PG8_LDB(B0, 0, 0); PG8_LDB(B1, 0, 1); PG8_SCHED; PG8_LDA(At, 0, 0); PG8_STAGE(PG8_SA(1, 1), a1 + hstep, voffA);
;             PG8_WAIT_V(8); PG8_WAIT_L(0); PG8_BAR; PG8_MMA(0, 0, At, B0); PG8_MMA(0, 1, At, B1); PG8_BAR; PG8_SCHED;
;             PG8_LDA(At, 0, 1); PG8_STAGE(PG8_SB(0, 0), b2, voffB); PG8_STAGE(PG8_SB(0, 1), b2 + hstep, voffB); PG8_STAGE(PG8_SA(0, 0), a2, voffA);
;             PG8_WAIT_V(8); PG8_WAIT_L(0); PG8_BAR; PG8_MMA(1, 0, At, B0); PG8_MMA(1, 1, At, B1); PG8_BAR; PG8_SCHED;
.LBB0_150:
	s_add_u32 s24, s22, 0xfffc0080
	s_addc_u32 s25, s23, -1
	s_waitcnt lgkmcnt(0)
	s_add_i32 s54, 0, 0x10000
	v_add_u32_e32 v147, s54, v152
	ds_read_b128 v[156:159], v147
	ds_read_b128 v[160:163], v147 offset:1024
	ds_read_b128 v[164:167], v147 offset:2048
	ds_read_b128 v[168:171], v147 offset:3072
	ds_read_b128 v[172:175], v154
	ds_read_b128 v[176:179], v154 offset:1024
	ds_read_b128 v[182:185], v154 offset:2048
	ds_read_b128 v[190:193], v154 offset:3072
	s_cmp_eq_u32 s49, 12
	s_cselect_b32 s27, s17, s25
	s_cselect_b32 s26, s45, s24
	s_cselect_b32 s25, s15, s48
	s_cselect_b32 s24, s46, s47
	s_add_i32 m0, s13, 0xc000
	ds_read_b128 v[194:197], v155
	ds_read_b128 v[198:201], v155 offset:1024
	ds_read_b128 v[202:205], v155 offset:2048
	ds_read_b128 v[206:209], v155 offset:3072
	ds_read_b128 v[210:213], v155 offset:4096
	ds_read_b128 v[214:217], v155 offset:5120
	ds_read_b128 v[218:221], v155 offset:6144
	ds_read_b128 v[222:225], v155 offset:7168
	global_load_lds_dwordx4 v138, s[22:23]
	s_add_i32 m0, s13, 0xe000
	s_nop 0
	global_load_lds_dwordx4 v140, s[22:23]
	s_waitcnt vmcnt(8)
	s_waitcnt lgkmcnt(0)
	s_barrier
	s_setprio 1
	v_mfma_f32_16x16x32_bf16 v[124:127], v[156:159], v[194:197], v[124:127]
	v_mfma_f32_16x16x32_bf16 v[120:123], v[164:167], v[194:197], v[120:123]
	v_mfma_f32_16x16x32_bf16 v[116:119], v[156:159], v[202:205], v[116:119]
	v_mfma_f32_16x16x32_bf16 v[112:115], v[164:167], v[202:205], v[112:115]
	v_mfma_f32_16x16x32_bf16 v[100:103], v[156:159], v[210:213], v[100:103]
	v_mfma_f32_16x16x32_bf16 v[96:99], v[164:167], v[210:213], v[96:99]
	v_mfma_f32_16x16x32_bf16 v[84:87], v[156:159], v[218:221], v[84:87]
	v_mfma_f32_16x16x32_bf16 v[80:83], v[164:167], v[218:221], v[80:83]
	v_mfma_f32_16x16x32_bf16 v[124:127], v[160:163], v[198:201], v[124:127]
	v_mfma_f32_16x16x32_bf16 v[120:123], v[168:171], v[198:201], v[120:123]
	v_mfma_f32_16x16x32_bf16 v[116:119], v[160:163], v[206:209], v[116:119]
	v_mfma_f32_16x16x32_bf16 v[112:115], v[168:171], v[206:209], v[112:115]
	v_mfma_f32_16x16x32_bf16 v[100:103], v[160:163], v[214:217], v[100:103]
	v_mfma_f32_16x16x32_bf16 v[96:99], v[168:171], v[214:217], v[96:99]
	v_mfma_f32_16x16x32_bf16 v[84:87], v[160:163], v[222:225], v[84:87]
	v_mfma_f32_16x16x32_bf16 v[80:83], v[168:171], v[222:225], v[80:83]
	v_mfma_f32_16x16x32_bf16 v[108:111], v[172:175], v[194:197], v[108:111]
	v_mfma_f32_16x16x32_bf16 v[104:107], v[182:185], v[194:197], v[104:107]
	v_mfma_f32_16x16x32_bf16 v[92:95], v[172:175], v[202:205], v[92:95]
	v_mfma_f32_16x16x32_bf16 v[88:91], v[182:185], v[202:205], v[88:91]
	v_mfma_f32_16x16x32_bf16 v[76:79], v[172:175], v[210:213], v[76:79]
	v_mfma_f32_16x16x32_bf16 v[72:75], v[182:185], v[210:213], v[72:75]
	v_mfma_f32_16x16x32_bf16 v[68:71], v[172:175], v[218:221], v[68:71]
	v_mfma_f32_16x16x32_bf16 v[64:67], v[182:185], v[218:221], v[64:67]
	v_mfma_f32_16x16x32_bf16 v[108:111], v[176:179], v[198:201], v[108:111]
	v_mfma_f32_16x16x32_bf16 v[104:107], v[190:193], v[198:201], v[104:107]
	v_mfma_f32_16x16x32_bf16 v[92:95], v[176:179], v[206:209], v[92:95]
	v_mfma_f32_16x16x32_bf16 v[88:91], v[190:193], v[206:209], v[88:91]
	v_mfma_f32_16x16x32_bf16 v[76:79], v[176:179], v[214:217], v[76:79]
	v_mfma_f32_16x16x32_bf16 v[72:75], v[190:193], v[214:217], v[72:75]
	v_mfma_f32_16x16x32_bf16 v[68:71], v[176:179], v[222:225], v[68:71]
	v_mfma_f32_16x16x32_bf16 v[64:67], v[190:193], v[222:225], v[64:67]
	s_add_i32 s54, s54, s31
	v_lshl_add_u64 v[186:187], s[24:25], 0, v[130:131]
	s_setprio 0
	s_barrier
	s_mov_b32 m0, s54
	ds_read_b128 v[194:197], v155 offset:16384
	ds_read_b128 v[198:201], v155 offset:17408
	ds_read_b128 v[202:205], v155 offset:18432
	ds_read_b128 v[206:209], v155 offset:19456
	ds_read_b128 v[210:213], v155 offset:20480
	ds_read_b128 v[214:217], v155 offset:21504
	ds_read_b128 v[218:221], v155 offset:22528
	ds_read_b128 v[222:225], v155 offset:23552
	global_load_lds_dwordx4 v[186:187], off
	s_add_i32 m0, s54, 0x2000
	s_add_u32 s54, s24, 0x40000
	v_lshl_add_u64 v[226:227], s[24:25], 0, v[134:135]
	s_addc_u32 s55, s25, 0
	s_add_i32 s76, s43, s31
	global_load_lds_dwordx4 v[226:227], off
	s_mov_b32 m0, s76
	v_lshl_add_u64 v[230:231], s[26:27], 0, v[132:133]
	global_load_lds_dwordx4 v130, s[54:55]
	s_add_i32 m0, s76, 0x2000
	s_nop 0
	global_load_lds_dwordx4 v134, s[54:55]
	v_lshl_add_u64 v[228:229], s[26:27], 0, v[128:129]
	s_mov_b32 m0, s13
	s_nop 0
	global_load_lds_dwordx4 v[228:229], off
	s_mov_b32 m0, s34
	s_nop 0
	global_load_lds_dwordx4 v[230:231], off
	s_waitcnt vmcnt(8)
	s_waitcnt lgkmcnt(0)
	s_barrier
; #define PG8_STAGE(bufoff, gbase, voff) do { _Pragma("unroll") for (int _i = 0; _i < 2; ++_i) \
;         __builtin_amdgcn_global_load_lds((const unsigned*)((const char*)(gbase) + (voff)[_i]), (PG8_LAS unsigned*)(lds + (bufoff) + ldsw + _i * 8192), 16, 0, 0); } while (0)
; #define PG8_LDA(dst, b, h) do { _Pragma("unroll") for (int m = 0; m < 4; ++m) _Pragma("unroll") for (int k = 0; k < 2; ++k) dst[m][k] = *(const PG8_LAS bf16x8*)(lds + PG8_SA(b, h) + aoff + m * 2048 + k * 1024); } while (0)
; #define PG8_LDB(dst, b, h) do { _Pragma("unroll") for (int n = 0; n < 2; ++n) _Pragma("unroll") for (int k = 0; k < 2; ++k) dst[n][k] = *(const PG8_LAS bf16x8*)(lds + PG8_SB(b, h) + boff + n * 2048 + k * 1024); } while (0)
; #define PG8_MMA(ai, bj, At, Bt) do { __builtin_amdgcn_s_setprio(1); _Pragma("unroll") for (int m = 0; m < 4; ++m) _Pragma("unroll") for (int n = 0; n < 2; ++n) _Pragma("unroll") for (int k = 0; k < 2; ++k) \
;         acc[ai][bj][m][n] = __builtin_amdgcn_mfma_f32_16x16x32_bf16(Bt[n][k], At[m][k], acc[ai][bj][m][n], 0, 0, 0); __builtin_amdgcn_s_setprio(0); } while (0)
; #define PG8_WAIT_V(n) asm volatile("s_waitcnt vmcnt(" #n ")" ::: "memory")
; #define PG8_WAIT_L(n) asm volatile("s_waitcnt lgkmcnt(" #n ")" ::: "memory")
; #define PG8_BAR __builtin_amdgcn_s_barrier()
; #define PG8_SCHED __builtin_amdgcn_sched_barrier(0)
; template <class Epi, class Sched, bool ALIGN_EPI = false, bool SP2 = false>
; __device__ __forceinline__ void gemm_phase(PG8_LAS unsigned char* lds, const Gemm g, const Sched& S, const Epi& E) {
;     ...
;             PG8_LDA(At, 0, 1); PG8_STAGE(PG8_SB(0, 0), b2, voffB); PG8_STAGE(PG8_SB(0, 1), b2 + hstep, voffB); PG8_STAGE(PG8_SA(0, 0), a2, voffA);
;             PG8_WAIT_V(8); PG8_WAIT_L(0); PG8_BAR; PG8_MMA(1, 0, At, B0); PG8_MMA(1, 1, At, B1); PG8_BAR; PG8_SCHED;
;             PG8_LDB(B0, 1, 0); PG8_LDB(B1, 1, 1); PG8_SCHED; PG8_LDA(At, 1, 0); PG8_STAGE(PG8_SA(0, 1), a2 + hstep, voffA);
;             PG8_WAIT_V(8); PG8_WAIT_L(0); PG8_BAR; PG8_MMA(0, 0, At, B0); PG8_MMA(0, 1, At, B1); PG8_BAR; PG8_SCHED;
;             PG8_LDA(At, 1, 1); PG8_STAGE(PG8_SB(1, 0), b3, voffB); PG8_STAGE(PG8_SB(1, 1), b3 + hstep, voffB); PG8_STAGE(PG8_SA(1, 0), a3, voffA);
;             PG8_WAIT_V(8); PG8_WAIT_L(0); PG8_BAR; PG8_MMA(1, 0, At, B0); PG8_MMA(1, 1, At, B1); PG8_BAR; PG8_SCHED;
	s_setprio 1
	v_mfma_f32_16x16x32_bf16 v[60:63], v[156:159], v[194:197], v[60:63]
	v_mfma_f32_16x16x32_bf16 v[56:59], v[164:167], v[194:197], v[56:59]
	v_mfma_f32_16x16x32_bf16 v[52:55], v[156:159], v[202:205], v[52:55]
	v_mfma_f32_16x16x32_bf16 v[48:51], v[164:167], v[202:205], v[48:51]
	v_mfma_f32_16x16x32_bf16 v[36:39], v[156:159], v[210:213], v[36:39]
	v_mfma_f32_16x16x32_bf16 v[32:35], v[164:167], v[210:213], v[32:35]
	v_mfma_f32_16x16x32_bf16 v[20:23], v[156:159], v[218:221], v[20:23]
	v_mfma_f32_16x16x32_bf16 v[16:19], v[164:167], v[218:221], v[16:19]
	v_mfma_f32_16x16x32_bf16 v[60:63], v[160:163], v[198:201], v[60:63]
	v_mfma_f32_16x16x32_bf16 v[56:59], v[168:171], v[198:201], v[56:59]
	v_mfma_f32_16x16x32_bf16 v[52:55], v[160:163], v[206:209], v[52:55]
	v_mfma_f32_16x16x32_bf16 v[48:51], v[168:171], v[206:209], v[48:51]
	v_mfma_f32_16x16x32_bf16 v[36:39], v[160:163], v[214:217], v[36:39]
	v_mfma_f32_16x16x32_bf16 v[32:35], v[168:171], v[214:217], v[32:35]
	v_mfma_f32_16x16x32_bf16 v[20:23], v[160:163], v[222:225], v[20:23]
	v_mfma_f32_16x16x32_bf16 v[16:19], v[168:171], v[222:225], v[16:19]
	v_mfma_f32_16x16x32_bf16 v[44:47], v[172:175], v[194:197], v[44:47]
	v_mfma_f32_16x16x32_bf16 v[40:43], v[182:185], v[194:197], v[40:43]
	v_mfma_f32_16x16x32_bf16 v[28:31], v[172:175], v[202:205], v[28:31]
	v_mfma_f32_16x16x32_bf16 v[24:27], v[182:185], v[202:205], v[24:27]
	v_mfma_f32_16x16x32_bf16 v[12:15], v[172:175], v[210:213], v[12:15]
	v_mfma_f32_16x16x32_bf16 v[8:11], v[182:185], v[210:213], v[8:11]
	v_mfma_f32_16x16x32_bf16 v[4:7], v[172:175], v[218:221], v[4:7]
	v_mfma_f32_16x16x32_bf16 v[0:3], v[182:185], v[218:221], v[0:3]
	v_mfma_f32_16x16x32_bf16 v[44:47], v[176:179], v[198:201], v[44:47]
	v_mfma_f32_16x16x32_bf16 v[40:43], v[190:193], v[198:201], v[40:43]
	v_mfma_f32_16x16x32_bf16 v[28:31], v[176:179], v[206:209], v[28:31]
	v_mfma_f32_16x16x32_bf16 v[24:27], v[190:193], v[206:209], v[24:27]
	v_mfma_f32_16x16x32_bf16 v[12:15], v[176:179], v[214:217], v[12:15]
	v_mfma_f32_16x16x32_bf16 v[8:11], v[190:193], v[214:217], v[8:11]
	v_mfma_f32_16x16x32_bf16 v[4:7], v[176:179], v[222:225], v[4:7]
	v_mfma_f32_16x16x32_bf16 v[0:3], v[190:193], v[222:225], v[0:3]
	s_add_i32 s54, 0, 0x18000
	v_add_u32_e32 v147, s54, v152
	s_add_i32 s55, 0, 0x1c000
	s_setprio 0
	s_barrier
	ds_read_b128 v[156:159], v147
	ds_read_b128 v[160:163], v147 offset:1024
	ds_read_b128 v[164:167], v147 offset:2048
	ds_read_b128 v[168:171], v147 offset:3072
	v_add_u32_e32 v147, s55, v152
	ds_read_b128 v[172:175], v147
	ds_read_b128 v[176:179], v147 offset:1024
	ds_read_b128 v[182:185], v147 offset:2048
	ds_read_b128 v[190:193], v147 offset:3072
	s_add_u32 s26, s26, 0x40000
	s_addc_u32 s27, s27, 0
	s_mov_b32 m0, s35
	ds_read_b128 v[194:197], v155 offset:32768
	ds_read_b128 v[198:201], v155 offset:33792
	ds_read_b128 v[202:205], v155 offset:34816
	ds_read_b128 v[206:209], v155 offset:35840
	ds_read_b128 v[210:213], v155 offset:36864
	ds_read_b128 v[214:217], v155 offset:37888
	ds_read_b128 v[218:221], v155 offset:38912
	ds_read_b128 v[222:225], v155 offset:39936
	global_load_lds_dwordx4 v128, s[26:27]
	s_mov_b32 m0, s36
	s_nop 0
	global_load_lds_dwordx4 v132, s[26:27]
	s_waitcnt vmcnt(8)
	s_waitcnt lgkmcnt(0)
	s_barrier
	s_setprio 1
	v_mfma_f32_16x16x32_bf16 v[124:127], v[156:159], v[194:197], v[124:127]
	v_mfma_f32_16x16x32_bf16 v[120:123], v[164:167], v[194:197], v[120:123]
	v_mfma_f32_16x16x32_bf16 v[116:119], v[156:159], v[202:205], v[116:119]
	v_mfma_f32_16x16x32_bf16 v[112:115], v[164:167], v[202:205], v[112:115]
	v_mfma_f32_16x16x32_bf16 v[100:103], v[156:159], v[210:213], v[100:103]
	v_mfma_f32_16x16x32_bf16 v[96:99], v[164:167], v[210:213], v[96:99]
	v_mfma_f32_16x16x32_bf16 v[84:87], v[156:159], v[218:221], v[84:87]
	v_mfma_f32_16x16x32_bf16 v[80:83], v[164:167], v[218:221], v[80:83]
	v_mfma_f32_16x16x32_bf16 v[124:127], v[160:163], v[198:201], v[124:127]
	v_mfma_f32_16x16x32_bf16 v[120:123], v[168:171], v[198:201], v[120:123]
	v_mfma_f32_16x16x32_bf16 v[116:119], v[160:163], v[206:209], v[116:119]
	v_mfma_f32_16x16x32_bf16 v[112:115], v[168:171], v[206:209], v[112:115]
	v_mfma_f32_16x16x32_bf16 v[100:103], v[160:163], v[214:217], v[100:103]
	v_mfma_f32_16x16x32_bf16 v[96:99], v[168:171], v[214:217], v[96:99]
	v_mfma_f32_16x16x32_bf16 v[84:87], v[160:163], v[222:225], v[84:87]
	v_mfma_f32_16x16x32_bf16 v[80:83], v[168:171], v[222:225], v[80:83]
	v_mfma_f32_16x16x32_bf16 v[108:111], v[172:175], v[194:197], v[108:111]
	v_mfma_f32_16x16x32_bf16 v[104:107], v[182:185], v[194:197], v[104:107]
	v_mfma_f32_16x16x32_bf16 v[92:95], v[172:175], v[202:205], v[92:95]
	v_mfma_f32_16x16x32_bf16 v[88:91], v[182:185], v[202:205], v[88:91]
	v_mfma_f32_16x16x32_bf16 v[76:79], v[172:175], v[210:213], v[76:79]
	v_mfma_f32_16x16x32_bf16 v[72:75], v[182:185], v[210:213], v[72:75]
	v_mfma_f32_16x16x32_bf16 v[68:71], v[172:175], v[218:221], v[68:71]
	v_mfma_f32_16x16x32_bf16 v[64:67], v[182:185], v[218:221], v[64:67]
	v_mfma_f32_16x16x32_bf16 v[108:111], v[176:179], v[198:201], v[108:111]
	v_mfma_f32_16x16x32_bf16 v[104:107], v[190:193], v[198:201], v[104:107]
	v_mfma_f32_16x16x32_bf16 v[92:95], v[176:179], v[206:209], v[92:95]
	v_mfma_f32_16x16x32_bf16 v[88:91], v[190:193], v[206:209], v[88:91]
	v_mfma_f32_16x16x32_bf16 v[76:79], v[176:179], v[214:217], v[76:79]
	v_mfma_f32_16x16x32_bf16 v[72:75], v[190:193], v[214:217], v[72:75]
	v_mfma_f32_16x16x32_bf16 v[68:71], v[176:179], v[222:225], v[68:71]
	v_mfma_f32_16x16x32_bf16 v[64:67], v[190:193], v[222:225], v[64:67]
	s_add_i32 s26, s54, s31
	v_lshl_add_u64 v[186:187], v[186:187], 0, s[8:9]
	s_setprio 0
	s_barrier
; #define PG8_STAGE(bufoff, gbase, voff) do { _Pragma("unroll") for (int _i = 0; _i < 2; ++_i) \
;         __builtin_amdgcn_global_load_lds((const unsigned*)((const char*)(gbase) + (voff)[_i]), (PG8_LAS unsigned*)(lds + (bufoff) + ldsw + _i * 8192), 16, 0, 0); } while (0)
; #define PG8_LDA(dst, b, h) do { _Pragma("unroll") for (int m = 0; m < 4; ++m) _Pragma("unroll") for (int k = 0; k < 2; ++k) dst[m][k] = *(const PG8_LAS bf16x8*)(lds + PG8_SA(b, h) + aoff + m * 2048 + k * 1024); } while (0)
; #define PG8_MMA(ai, bj, At, Bt) do { __builtin_amdgcn_s_setprio(1); _Pragma("unroll") for (int m = 0; m < 4; ++m) _Pragma("unroll") for (int n = 0; n < 2; ++n) _Pragma("unroll") for (int k = 0; k < 2; ++k) \
;         acc[ai][bj][m][n] = __builtin_amdgcn_mfma_f32_16x16x32_bf16(Bt[n][k], At[m][k], acc[ai][bj][m][n], 0, 0, 0); __builtin_amdgcn_s_setprio(0); } while (0)
; #define PG8_WAIT_V(n) asm volatile("s_waitcnt vmcnt(" #n ")" ::: "memory")
; #define PG8_WAIT_L(n) asm volatile("s_waitcnt lgkmcnt(" #n ")" ::: "memory")
; #define PG8_BAR __builtin_amdgcn_s_barrier()
; #define PG8_SCHED __builtin_amdgcn_sched_barrier(0)
; template <class Epi, class Sched, bool ALIGN_EPI = false, bool SP2 = false>
; __device__ __forceinline__ void gemm_phase(PG8_LAS unsigned char* lds, const Gemm g, const Sched& S, const Epi& E) {
;     ...
;         for (int t = 0; t < nt; t += 2) {
;             const bool last = (t == nt - 2);
;             const char* a1 = cA + (size_t)(t + 1) * kstep;
;             const char* a2 = last ? nA : cA + (size_t)(t + 2) * kstep; const char* b2 = last ? nB : cB + (size_t)(t + 2) * kstep;
;             const char* a3 = a2 + kstep; const char* b3 = b2 + kstep;
;     ...
;             PG8_LDA(At, 1, 1); PG8_STAGE(PG8_SB(1, 0), b3, voffB); PG8_STAGE(PG8_SB(1, 1), b3 + hstep, voffB); PG8_STAGE(PG8_SA(1, 0), a3, voffA);
;             PG8_WAIT_V(8); PG8_WAIT_L(0); PG8_BAR; PG8_MMA(1, 0, At, B0); PG8_MMA(1, 1, At, B1); PG8_BAR; PG8_SCHED;
	s_mov_b32 m0, s26
	ds_read_b128 v[194:197], v155 offset:49152
	ds_read_b128 v[198:201], v155 offset:50176
	ds_read_b128 v[202:205], v155 offset:51200
	ds_read_b128 v[206:209], v155 offset:52224
	ds_read_b128 v[210:213], v155 offset:53248
	ds_read_b128 v[214:217], v155 offset:54272
	ds_read_b128 v[218:221], v155 offset:55296
	ds_read_b128 v[222:225], v155 offset:56320
	global_load_lds_dwordx4 v[186:187], off
	s_add_i32 m0, s26, 0x2000
	s_add_u32 s24, s24, 0x40080
	v_lshl_add_u64 v[186:187], v[226:227], 0, s[8:9]
	s_addc_u32 s25, s25, 0
	s_add_i32 s26, s55, s31
	global_load_lds_dwordx4 v[186:187], off
	s_mov_b32 m0, s26
	s_nop 0
	global_load_lds_dwordx4 v130, s[24:25]
	s_add_i32 m0, s26, 0x2000
	s_nop 0
	global_load_lds_dwordx4 v134, s[24:25]
	v_lshl_add_u64 v[186:187], v[228:229], 0, s[8:9]
	s_mov_b32 m0, s39
	s_nop 0
	global_load_lds_dwordx4 v[186:187], off
	v_lshl_add_u64 v[186:187], v[230:231], 0, s[8:9]
	s_mov_b32 m0, s40
	s_nop 0
	global_load_lds_dwordx4 v[186:187], off
	s_waitcnt vmcnt(8)
	s_waitcnt lgkmcnt(0)
	s_barrier
	s_setprio 1
	v_mfma_f32_16x16x32_bf16 v[60:63], v[156:159], v[194:197], v[60:63]
	v_mfma_f32_16x16x32_bf16 v[56:59], v[164:167], v[194:197], v[56:59]
	v_mfma_f32_16x16x32_bf16 v[52:55], v[156:159], v[202:205], v[52:55]
	v_mfma_f32_16x16x32_bf16 v[48:51], v[164:167], v[202:205], v[48:51]
	v_mfma_f32_16x16x32_bf16 v[36:39], v[156:159], v[210:213], v[36:39]
	v_mfma_f32_16x16x32_bf16 v[32:35], v[164:167], v[210:213], v[32:35]
	v_mfma_f32_16x16x32_bf16 v[20:23], v[156:159], v[218:221], v[20:23]
	v_mfma_f32_16x16x32_bf16 v[16:19], v[164:167], v[218:221], v[16:19]
	v_mfma_f32_16x16x32_bf16 v[60:63], v[160:163], v[198:201], v[60:63]
	v_mfma_f32_16x16x32_bf16 v[56:59], v[168:171], v[198:201], v[56:59]
	v_mfma_f32_16x16x32_bf16 v[52:55], v[160:163], v[206:209], v[52:55]
	v_mfma_f32_16x16x32_bf16 v[48:51], v[168:171], v[206:209], v[48:51]
	v_mfma_f32_16x16x32_bf16 v[36:39], v[160:163], v[214:217], v[36:39]
	v_mfma_f32_16x16x32_bf16 v[32:35], v[168:171], v[214:217], v[32:35]
	v_mfma_f32_16x16x32_bf16 v[20:23], v[160:163], v[222:225], v[20:23]
	v_mfma_f32_16x16x32_bf16 v[16:19], v[168:171], v[222:225], v[16:19]
	v_mfma_f32_16x16x32_bf16 v[44:47], v[172:175], v[194:197], v[44:47]
	v_mfma_f32_16x16x32_bf16 v[40:43], v[182:185], v[194:197], v[40:43]
	v_mfma_f32_16x16x32_bf16 v[28:31], v[172:175], v[202:205], v[28:31]
	v_mfma_f32_16x16x32_bf16 v[24:27], v[182:185], v[202:205], v[24:27]
	v_mfma_f32_16x16x32_bf16 v[12:15], v[172:175], v[210:213], v[12:15]
	v_mfma_f32_16x16x32_bf16 v[8:11], v[182:185], v[210:213], v[8:11]
	v_mfma_f32_16x16x32_bf16 v[4:7], v[172:175], v[218:221], v[4:7]
	v_mfma_f32_16x16x32_bf16 v[0:3], v[182:185], v[218:221], v[0:3]
	v_mfma_f32_16x16x32_bf16 v[44:47], v[176:179], v[198:201], v[44:47]
	v_mfma_f32_16x16x32_bf16 v[40:43], v[190:193], v[198:201], v[40:43]
	v_mfma_f32_16x16x32_bf16 v[28:31], v[176:179], v[206:209], v[28:31]
	v_mfma_f32_16x16x32_bf16 v[24:27], v[190:193], v[206:209], v[24:27]
	v_mfma_f32_16x16x32_bf16 v[12:15], v[176:179], v[214:217], v[12:15]
	v_mfma_f32_16x16x32_bf16 v[8:11], v[190:193], v[214:217], v[8:11]
	v_mfma_f32_16x16x32_bf16 v[4:7], v[176:179], v[222:225], v[4:7]
	v_mfma_f32_16x16x32_bf16 v[0:3], v[190:193], v[222:225], v[0:3]
	s_add_i32 s49, s49, 2
	s_add_u32 s22, s22, 0x100
	s_addc_u32 s23, s23, 0
	s_add_u32 s47, s47, 0x100
	s_addc_u32 s48, s48, 0
	s_cmp_gt_u32 s49, 13
	s_setprio 0
	s_barrier
	s_cbranch_scc0 .LBB0_150
	s_and_b64 vcc, exec, s[10:11]
	s_cbranch_vccz .LBB0_153
	s_barrier

; #define PG8_STAGE(bufoff, gbase, voff) do { _Pragma("unroll") for (int _i = 0; _i < 2; ++_i) \
;         __builtin_amdgcn_global_load_lds((const unsigned*)((const char*)(gbase) + (voff)[_i]), (PG8_LAS unsigned*)(lds + (bufoff) + ldsw + _i * 8192), 16, 0, 0); } while (0)
; #define PG8_LDA(dst, b, h) do { _Pragma("unroll") for (int m = 0; m < 4; ++m) _Pragma("unroll") for (int k = 0; k < 2; ++k) dst[m][k] = *(const PG8_LAS bf16x8*)(lds + PG8_SA(b, h) + aoff + m * 2048 + k * 1024); } while (0)
; #define PG8_LDB(dst, b, h) do { _Pragma("unroll") for (int n = 0; n < 2; ++n) _Pragma("unroll") for (int k = 0; k < 2; ++k) dst[n][k] = *(const PG8_LAS bf16x8*)(lds + PG8_SB(b, h) + boff + n * 2048 + k * 1024); } while (0)
; #define PG8_MMA(ai, bj, At, Bt) do { __builtin_amdgcn_s_setprio(1); _Pragma("unroll") for (int m = 0; m < 4; ++m) _Pragma("unroll") for (int n = 0; n < 2; ++n) _Pragma("unroll") for (int k = 0; k < 2; ++k) \
;         acc[ai][bj][m][n] = __builtin_amdgcn_mfma_f32_16x16x32_bf16(Bt[n][k], At[m][k], acc[ai][bj][m][n], 0, 0, 0); __builtin_amdgcn_s_setprio(0); } while (0)
; #define PG8_WAIT_V(n) asm volatile("s_waitcnt vmcnt(" #n ")" ::: "memory")
; #define PG8_BAR __builtin_amdgcn_s_barrier()
; template <class Epi, class Sched, bool ALIGN_EPI = false, bool SP2 = false>
; __device__ __forceinline__ void gemm_phase(PG8_LAS unsigned char* lds, const Gemm g, const Sched& S, const Epi& E) {
;     ...
;         for (int t = 0; t < nt; t += 2) {
;             const bool last = (t == nt - 2);
;             const char* a1 = cA + (size_t)(t + 1) * kstep;
;             const char* a2 = last ? nA : cA + (size_t)(t + 2) * kstep; const char* b2 = last ? nB : cB + (size_t)(t + 2) * kstep;
;             const char* a3 = a2 + kstep; const char* b3 = b2 + kstep;
;             if (last && has_next) S.a_ready(nxt);
;             if constexpr (SP2) {
;             PG8_LDB(B0, 0, 0); PG8_LDB(B1, 0, 1); PG8_SCHED; PG8_LDA(At, 0, 0); PG8_STAGE(PG8_SA(1, 1), a1 + hstep, voffA);
;             PG8_WAIT_V(8); PG8_WAIT_L(0); PG8_BAR; PG8_MMA(0, 0, At, B0); PG8_MMA(0, 1, At, B1); PG8_BAR; PG8_SCHED;
;             PG8_LDA(At, 0, 1); PG8_STAGE(PG8_SB(0, 0), b2, voffB); PG8_STAGE(PG8_SB(0, 1), b2 + hstep, voffB); PG8_STAGE(PG8_SA(0, 0), a2, voffA);
;             PG8_WAIT_V(8); PG8_WAIT_L(0); PG8_BAR; PG8_MMA(1, 0, At, B0); PG8_MMA(1, 1, At, B1); PG8_BAR; PG8_SCHED;
.LBB0_684:
	ds_read_b128 v[128:131], v174
	ds_read_b128 v[132:135], v174 offset:1024
	ds_read_b128 v[136:139], v174 offset:2048
	ds_read_b128 v[140:143], v174 offset:3072
	ds_read_b128 v[162:165], v175
	ds_read_b128 v[166:169], v175 offset:1024
	ds_read_b128 v[180:183], v175 offset:2048
	ds_read_b128 v[184:187], v175 offset:3072
	s_add_u32 s8, s0, 0xfffc0080
	s_addc_u32 s9, s1, -1
	s_cmp_eq_u32 vcc_lo, 12
	s_cselect_b32 s43, s3, s9
	s_cselect_b32 s42, s94, s8
	s_cselect_b32 s41, s5, s97
	s_cselect_b32 s40, s95, s96
	s_add_i32 m0, s47, 0xc000
	ds_read_b128 v[190:193], v176
	ds_read_b128 v[194:197], v176 offset:1024
	ds_read_b128 v[198:201], v176 offset:2048
	ds_read_b128 v[202:205], v176 offset:3072
	ds_read_b128 v[206:209], v176 offset:4096
	ds_read_b128 v[210:213], v176 offset:5120
	ds_read_b128 v[214:217], v176 offset:6144
	ds_read_b128 v[218:221], v176 offset:7168
	global_load_lds_dwordx4 v158, s[0:1]
	s_add_i32 m0, s47, 0xe000
	s_nop 0
	global_load_lds_dwordx4 v160, s[0:1]
	s_waitcnt vmcnt(8)
	s_waitcnt lgkmcnt(0)
	s_barrier
	s_setprio 1
	v_mfma_f32_16x16x32_bf16 v[124:127], v[128:131], v[190:193], v[124:127]
	v_mfma_f32_16x16x32_bf16 v[120:123], v[136:139], v[190:193], v[120:123]
	v_mfma_f32_16x16x32_bf16 v[108:111], v[128:131], v[198:201], v[108:111]
	v_mfma_f32_16x16x32_bf16 v[104:107], v[136:139], v[198:201], v[104:107]
	v_mfma_f32_16x16x32_bf16 v[92:95], v[128:131], v[206:209], v[92:95]
	v_mfma_f32_16x16x32_bf16 v[88:91], v[136:139], v[206:209], v[88:91]
	v_mfma_f32_16x16x32_bf16 v[76:79], v[128:131], v[214:217], v[76:79]
	v_mfma_f32_16x16x32_bf16 v[72:75], v[136:139], v[214:217], v[72:75]
	v_mfma_f32_16x16x32_bf16 v[124:127], v[132:135], v[194:197], v[124:127]
	v_mfma_f32_16x16x32_bf16 v[120:123], v[140:143], v[194:197], v[120:123]
	v_mfma_f32_16x16x32_bf16 v[108:111], v[132:135], v[202:205], v[108:111]
	v_mfma_f32_16x16x32_bf16 v[104:107], v[140:143], v[202:205], v[104:107]
	v_mfma_f32_16x16x32_bf16 v[92:95], v[132:135], v[210:213], v[92:95]
	v_mfma_f32_16x16x32_bf16 v[88:91], v[140:143], v[210:213], v[88:91]
	v_mfma_f32_16x16x32_bf16 v[76:79], v[132:135], v[218:221], v[76:79]
	v_mfma_f32_16x16x32_bf16 v[72:75], v[140:143], v[218:221], v[72:75]
	v_mfma_f32_16x16x32_bf16 v[116:119], v[162:165], v[190:193], v[116:119]
	v_mfma_f32_16x16x32_bf16 v[112:115], v[180:183], v[190:193], v[112:115]
	v_mfma_f32_16x16x32_bf16 v[100:103], v[162:165], v[198:201], v[100:103]
	v_mfma_f32_16x16x32_bf16 v[96:99], v[180:183], v[198:201], v[96:99]
	v_mfma_f32_16x16x32_bf16 v[84:87], v[162:165], v[206:209], v[84:87]
	v_mfma_f32_16x16x32_bf16 v[80:83], v[180:183], v[206:209], v[80:83]
	v_mfma_f32_16x16x32_bf16 v[68:71], v[162:165], v[214:217], v[68:71]
	v_mfma_f32_16x16x32_bf16 v[64:67], v[180:183], v[214:217], v[64:67]
	v_mfma_f32_16x16x32_bf16 v[116:119], v[166:169], v[194:197], v[116:119]
	v_mfma_f32_16x16x32_bf16 v[112:115], v[184:187], v[194:197], v[112:115]
	v_mfma_f32_16x16x32_bf16 v[100:103], v[166:169], v[202:205], v[100:103]
	v_mfma_f32_16x16x32_bf16 v[96:99], v[184:187], v[202:205], v[96:99]
	v_mfma_f32_16x16x32_bf16 v[84:87], v[166:169], v[210:213], v[84:87]
	v_mfma_f32_16x16x32_bf16 v[80:83], v[184:187], v[210:213], v[80:83]
	v_mfma_f32_16x16x32_bf16 v[68:71], v[166:169], v[218:221], v[68:71]
	v_mfma_f32_16x16x32_bf16 v[64:67], v[184:187], v[218:221], v[64:67]
	s_add_i32 s8, s76, s46
	v_lshl_add_u64 v[170:171], s[40:41], 0, v[146:147]
	s_setprio 0
	s_barrier
	s_mov_b32 m0, s8
	ds_read_b128 v[190:193], v176 offset:16384
	ds_read_b128 v[194:197], v176 offset:17408
	ds_read_b128 v[198:201], v176 offset:18432
	ds_read_b128 v[202:205], v176 offset:19456
	ds_read_b128 v[206:209], v176 offset:20480
	ds_read_b128 v[210:213], v176 offset:21504
	ds_read_b128 v[214:217], v176 offset:22528
	ds_read_b128 v[218:221], v176 offset:23552
	global_load_lds_dwordx4 v[170:171], off
	s_add_i32 m0, s8, 0x2000
	s_add_u32 s8, s40, 0x40000
	v_lshl_add_u64 v[222:223], s[40:41], 0, v[150:151]
	s_addc_u32 s9, s41, 0
	s_add_i32 s54, s77, s46
	global_load_lds_dwordx4 v[222:223], off
	s_mov_b32 m0, s54
	v_lshl_add_u64 v[226:227], s[42:43], 0, v[148:149]
	global_load_lds_dwordx4 v146, s[8:9]
	s_add_i32 m0, s54, 0x2000
	s_nop 0
	global_load_lds_dwordx4 v150, s[8:9]
	v_lshl_add_u64 v[224:225], s[42:43], 0, v[144:145]
	s_mov_b32 m0, s47
	s_nop 0
	global_load_lds_dwordx4 v[224:225], off
	s_mov_b32 m0, s48
	s_nop 0
	global_load_lds_dwordx4 v[226:227], off
	s_waitcnt vmcnt(8)
	s_waitcnt lgkmcnt(0)
	s_barrier
	s_setprio 1
	v_mfma_f32_16x16x32_bf16 v[60:63], v[128:131], v[190:193], v[60:63]
	v_mfma_f32_16x16x32_bf16 v[56:59], v[136:139], v[190:193], v[56:59]
	v_mfma_f32_16x16x32_bf16 v[44:47], v[128:131], v[198:201], v[44:47]
	v_mfma_f32_16x16x32_bf16 v[40:43], v[136:139], v[198:201], v[40:43]
	v_mfma_f32_16x16x32_bf16 v[28:31], v[128:131], v[206:209], v[28:31]
	v_mfma_f32_16x16x32_bf16 v[24:27], v[136:139], v[206:209], v[24:27]
	v_mfma_f32_16x16x32_bf16 v[12:15], v[128:131], v[214:217], v[12:15]
	v_mfma_f32_16x16x32_bf16 v[8:11], v[136:139], v[214:217], v[8:11]
	v_mfma_f32_16x16x32_bf16 v[60:63], v[132:135], v[194:197], v[60:63]
	v_mfma_f32_16x16x32_bf16 v[56:59], v[140:143], v[194:197], v[56:59]
	v_mfma_f32_16x16x32_bf16 v[44:47], v[132:135], v[202:205], v[44:47]
	v_mfma_f32_16x16x32_bf16 v[40:43], v[140:143], v[202:205], v[40:43]
	v_mfma_f32_16x16x32_bf16 v[28:31], v[132:135], v[210:213], v[28:31]
	v_mfma_f32_16x16x32_bf16 v[24:27], v[140:143], v[210:213], v[24:27]
	v_mfma_f32_16x16x32_bf16 v[12:15], v[132:135], v[218:221], v[12:15]
	v_mfma_f32_16x16x32_bf16 v[8:11], v[140:143], v[218:221], v[8:11]
	v_mfma_f32_16x16x32_bf16 v[52:55], v[162:165], v[190:193], v[52:55]
	v_mfma_f32_16x16x32_bf16 v[48:51], v[180:183], v[190:193], v[48:51]
	v_mfma_f32_16x16x32_bf16 v[36:39], v[162:165], v[198:201], v[36:39]
	v_mfma_f32_16x16x32_bf16 v[32:35], v[180:183], v[198:201], v[32:35]
	v_mfma_f32_16x16x32_bf16 v[20:23], v[162:165], v[206:209], v[20:23]
	v_mfma_f32_16x16x32_bf16 v[16:19], v[180:183], v[206:209], v[16:19]
	v_mfma_f32_16x16x32_bf16 v[4:7], v[162:165], v[214:217], v[4:7]
	v_mfma_f32_16x16x32_bf16 v[0:3], v[180:183], v[214:217], v[0:3]
	v_mfma_f32_16x16x32_bf16 v[52:55], v[166:169], v[194:197], v[52:55]
	v_mfma_f32_16x16x32_bf16 v[48:51], v[184:187], v[194:197], v[48:51]
	v_mfma_f32_16x16x32_bf16 v[36:39], v[166:169], v[202:205], v[36:39]
	v_mfma_f32_16x16x32_bf16 v[32:35], v[184:187], v[202:205], v[32:35]
	v_mfma_f32_16x16x32_bf16 v[20:23], v[166:169], v[210:213], v[20:23]
	v_mfma_f32_16x16x32_bf16 v[16:19], v[184:187], v[210:213], v[16:19]
	v_mfma_f32_16x16x32_bf16 v[4:7], v[166:169], v[218:221], v[4:7]
	v_mfma_f32_16x16x32_bf16 v[0:3], v[184:187], v[218:221], v[0:3]
	s_add_i32 s54, 0, 0x18000
	s_add_i32 s55, 0, 0x1c000
	v_add_u32_e32 v140, s54, v172
	v_add_u32_e32 v152, s55, v172
	s_setprio 0
	s_barrier
; #define PG8_STAGE(bufoff, gbase, voff) do { _Pragma("unroll") for (int _i = 0; _i < 2; ++_i) \
;         __builtin_amdgcn_global_load_lds((const unsigned*)((const char*)(gbase) + (voff)[_i]), (PG8_LAS unsigned*)(lds + (bufoff) + ldsw + _i * 8192), 16, 0, 0); } while (0)
; #define PG8_LDA(dst, b, h) do { _Pragma("unroll") for (int m = 0; m < 4; ++m) _Pragma("unroll") for (int k = 0; k < 2; ++k) dst[m][k] = *(const PG8_LAS bf16x8*)(lds + PG8_SA(b, h) + aoff + m * 2048 + k * 1024); } while (0)
; #define PG8_LDB(dst, b, h) do { _Pragma("unroll") for (int n = 0; n < 2; ++n) _Pragma("unroll") for (int k = 0; k < 2; ++k) dst[n][k] = *(const PG8_LAS bf16x8*)(lds + PG8_SB(b, h) + boff + n * 2048 + k * 1024); } while (0)
; #define PG8_WAIT_V(n) asm volatile("s_waitcnt vmcnt(" #n ")" ::: "memory")
; #define PG8_WAIT_L(n) asm volatile("s_waitcnt lgkmcnt(" #n ")" ::: "memory")
; #define PG8_BAR __builtin_amdgcn_s_barrier()
; #define PG8_SCHED __builtin_amdgcn_sched_barrier(0)
; template <class Epi, class Sched, bool ALIGN_EPI = false, bool SP2 = false>
; __device__ __forceinline__ void gemm_phase(PG8_LAS unsigned char* lds, const Gemm g, const Sched& S, const Epi& E) {
;     ...
;         for (int t = 0; t < nt; t += 2) {
;             const bool last = (t == nt - 2);
;             const char* a1 = cA + (size_t)(t + 1) * kstep;
;             const char* a2 = last ? nA : cA + (size_t)(t + 2) * kstep; const char* b2 = last ? nB : cB + (size_t)(t + 2) * kstep;
;             const char* a3 = a2 + kstep; const char* b3 = b2 + kstep;
;     ...
;             PG8_LDA(At, 0, 1); PG8_STAGE(PG8_SB(0, 0), b2, voffB); PG8_STAGE(PG8_SB(0, 1), b2 + hstep, voffB); PG8_STAGE(PG8_SA(0, 0), a2, voffA);
;             PG8_WAIT_V(8); PG8_WAIT_L(0); PG8_BAR; PG8_MMA(1, 0, At, B0); PG8_MMA(1, 1, At, B1); PG8_BAR; PG8_SCHED;
;             PG8_LDB(B0, 1, 0); PG8_LDB(B1, 1, 1); PG8_SCHED; PG8_LDA(At, 1, 0); PG8_STAGE(PG8_SA(0, 1), a2 + hstep, voffA);
;             PG8_WAIT_V(8); PG8_WAIT_L(0); PG8_BAR; PG8_MMA(0, 0, At, B0); PG8_MMA(0, 1, At, B1); PG8_BAR; PG8_SCHED;
;             PG8_LDA(At, 1, 1); PG8_STAGE(PG8_SB(1, 0), b3, voffB); PG8_STAGE(PG8_SB(1, 1), b3 + hstep, voffB); PG8_STAGE(PG8_SA(1, 0), a3, voffA);
;             PG8_WAIT_V(8); PG8_WAIT_L(0); PG8_BAR; PG8_MMA(1, 0, At, B0); PG8_MMA(1, 1, At, B1); PG8_BAR; PG8_SCHED;
	ds_read_b128 v[128:131], v140
	ds_read_b128 v[132:135], v140 offset:1024
	ds_read_b128 v[136:139], v140 offset:2048
	ds_read_b128 v[140:143], v140 offset:3072
	ds_read_b128 v[162:165], v152
	ds_read_b128 v[166:169], v152 offset:1024
	ds_read_b128 v[180:183], v152 offset:2048
	ds_read_b128 v[184:187], v152 offset:3072
	s_add_u32 s8, s42, 0x40000
	s_addc_u32 s9, s43, 0
	s_mov_b32 m0, s49
	ds_read_b128 v[190:193], v176 offset:32768
	ds_read_b128 v[194:197], v176 offset:33792
	ds_read_b128 v[198:201], v176 offset:34816
	ds_read_b128 v[202:205], v176 offset:35840
	ds_read_b128 v[206:209], v176 offset:36864
	ds_read_b128 v[210:213], v176 offset:37888
	ds_read_b128 v[214:217], v176 offset:38912
	ds_read_b128 v[218:221], v176 offset:39936
	global_load_lds_dwordx4 v144, s[8:9]
	s_mov_b32 m0, s51
	s_nop 0
	global_load_lds_dwordx4 v148, s[8:9]
	s_waitcnt vmcnt(8)
	s_waitcnt lgkmcnt(0)
	s_barrier
	s_setprio 1
	v_mfma_f32_16x16x32_bf16 v[124:127], v[128:131], v[190:193], v[124:127]
	v_mfma_f32_16x16x32_bf16 v[120:123], v[136:139], v[190:193], v[120:123]
	v_mfma_f32_16x16x32_bf16 v[108:111], v[128:131], v[198:201], v[108:111]
	v_mfma_f32_16x16x32_bf16 v[104:107], v[136:139], v[198:201], v[104:107]
	v_mfma_f32_16x16x32_bf16 v[92:95], v[128:131], v[206:209], v[92:95]
	v_mfma_f32_16x16x32_bf16 v[88:91], v[136:139], v[206:209], v[88:91]
	v_mfma_f32_16x16x32_bf16 v[76:79], v[128:131], v[214:217], v[76:79]
	v_mfma_f32_16x16x32_bf16 v[72:75], v[136:139], v[214:217], v[72:75]
	v_mfma_f32_16x16x32_bf16 v[124:127], v[132:135], v[194:197], v[124:127]
	v_mfma_f32_16x16x32_bf16 v[120:123], v[140:143], v[194:197], v[120:123]
	v_mfma_f32_16x16x32_bf16 v[108:111], v[132:135], v[202:205], v[108:111]
	v_mfma_f32_16x16x32_bf16 v[104:107], v[140:143], v[202:205], v[104:107]
	v_mfma_f32_16x16x32_bf16 v[92:95], v[132:135], v[210:213], v[92:95]
	v_mfma_f32_16x16x32_bf16 v[88:91], v[140:143], v[210:213], v[88:91]
	v_mfma_f32_16x16x32_bf16 v[76:79], v[132:135], v[218:221], v[76:79]
	v_mfma_f32_16x16x32_bf16 v[72:75], v[140:143], v[218:221], v[72:75]
	v_mfma_f32_16x16x32_bf16 v[116:119], v[162:165], v[190:193], v[116:119]
	v_mfma_f32_16x16x32_bf16 v[112:115], v[180:183], v[190:193], v[112:115]
	v_mfma_f32_16x16x32_bf16 v[100:103], v[162:165], v[198:201], v[100:103]
	v_mfma_f32_16x16x32_bf16 v[96:99], v[180:183], v[198:201], v[96:99]
	v_mfma_f32_16x16x32_bf16 v[84:87], v[162:165], v[206:209], v[84:87]
	v_mfma_f32_16x16x32_bf16 v[80:83], v[180:183], v[206:209], v[80:83]
	v_mfma_f32_16x16x32_bf16 v[68:71], v[162:165], v[214:217], v[68:71]
	v_mfma_f32_16x16x32_bf16 v[64:67], v[180:183], v[214:217], v[64:67]
	v_mfma_f32_16x16x32_bf16 v[116:119], v[166:169], v[194:197], v[116:119]
	v_mfma_f32_16x16x32_bf16 v[112:115], v[184:187], v[194:197], v[112:115]
	v_mfma_f32_16x16x32_bf16 v[100:103], v[166:169], v[202:205], v[100:103]
	v_mfma_f32_16x16x32_bf16 v[96:99], v[184:187], v[202:205], v[96:99]
	v_mfma_f32_16x16x32_bf16 v[84:87], v[166:169], v[210:213], v[84:87]
	v_mfma_f32_16x16x32_bf16 v[80:83], v[184:187], v[210:213], v[80:83]
	v_mfma_f32_16x16x32_bf16 v[68:71], v[166:169], v[218:221], v[68:71]
	v_mfma_f32_16x16x32_bf16 v[64:67], v[184:187], v[218:221], v[64:67]
	s_add_i32 s8, s54, s46
	v_lshl_add_u64 v[170:171], v[170:171], 0, s[14:15]
	s_setprio 0
	s_barrier
	s_mov_b32 m0, s8
	ds_read_b128 v[190:193], v176 offset:49152
	ds_read_b128 v[194:197], v176 offset:50176
	ds_read_b128 v[198:201], v176 offset:51200
	ds_read_b128 v[202:205], v176 offset:52224
	ds_read_b128 v[206:209], v176 offset:53248
	ds_read_b128 v[210:213], v176 offset:54272
	ds_read_b128 v[214:217], v176 offset:55296
	ds_read_b128 v[218:221], v176 offset:56320
	global_load_lds_dwordx4 v[170:171], off
	s_add_i32 m0, s8, 0x2000
	s_add_u32 s8, s40, 0x40080
	v_lshl_add_u64 v[170:171], v[222:223], 0, s[14:15]
	s_addc_u32 s9, s41, 0
	s_add_i32 s40, s55, s46
	global_load_lds_dwordx4 v[170:171], off
	s_mov_b32 m0, s40
	s_nop 0
	global_load_lds_dwordx4 v146, s[8:9]
	s_add_i32 m0, s40, 0x2000
	s_nop 0
	global_load_lds_dwordx4 v150, s[8:9]
	v_lshl_add_u64 v[170:171], v[224:225], 0, s[14:15]
	s_mov_b32 m0, s66
	s_nop 0
	global_load_lds_dwordx4 v[170:171], off
	v_lshl_add_u64 v[170:171], v[226:227], 0, s[14:15]
	s_mov_b32 m0, s67
	s_nop 0
	global_load_lds_dwordx4 v[170:171], off
	s_waitcnt vmcnt(8)
	s_waitcnt lgkmcnt(0)
	s_barrier
	s_setprio 1
	v_mfma_f32_16x16x32_bf16 v[60:63], v[128:131], v[190:193], v[60:63]
	v_mfma_f32_16x16x32_bf16 v[56:59], v[136:139], v[190:193], v[56:59]
	v_mfma_f32_16x16x32_bf16 v[44:47], v[128:131], v[198:201], v[44:47]
	v_mfma_f32_16x16x32_bf16 v[40:43], v[136:139], v[198:201], v[40:43]
	v_mfma_f32_16x16x32_bf16 v[28:31], v[128:131], v[206:209], v[28:31]
	v_mfma_f32_16x16x32_bf16 v[24:27], v[136:139], v[206:209], v[24:27]
	v_mfma_f32_16x16x32_bf16 v[12:15], v[128:131], v[214:217], v[12:15]
	v_mfma_f32_16x16x32_bf16 v[8:11], v[136:139], v[214:217], v[8:11]
	v_mfma_f32_16x16x32_bf16 v[60:63], v[132:135], v[194:197], v[60:63]
	v_mfma_f32_16x16x32_bf16 v[56:59], v[140:143], v[194:197], v[56:59]
	v_mfma_f32_16x16x32_bf16 v[44:47], v[132:135], v[202:205], v[44:47]
	v_mfma_f32_16x16x32_bf16 v[40:43], v[140:143], v[202:205], v[40:43]
	v_mfma_f32_16x16x32_bf16 v[28:31], v[132:135], v[210:213], v[28:31]
	v_mfma_f32_16x16x32_bf16 v[24:27], v[140:143], v[210:213], v[24:27]
	v_mfma_f32_16x16x32_bf16 v[12:15], v[132:135], v[218:221], v[12:15]
	v_mfma_f32_16x16x32_bf16 v[8:11], v[140:143], v[218:221], v[8:11]
	v_mfma_f32_16x16x32_bf16 v[52:55], v[162:165], v[190:193], v[52:55]
	v_mfma_f32_16x16x32_bf16 v[48:51], v[180:183], v[190:193], v[48:51]
	v_mfma_f32_16x16x32_bf16 v[36:39], v[162:165], v[198:201], v[36:39]
	v_mfma_f32_16x16x32_bf16 v[32:35], v[180:183], v[198:201], v[32:35]
	v_mfma_f32_16x16x32_bf16 v[20:23], v[162:165], v[206:209], v[20:23]
	v_mfma_f32_16x16x32_bf16 v[16:19], v[180:183], v[206:209], v[16:19]
	v_mfma_f32_16x16x32_bf16 v[4:7], v[162:165], v[214:217], v[4:7]
	v_mfma_f32_16x16x32_bf16 v[0:3], v[180:183], v[214:217], v[0:3]
	v_mfma_f32_16x16x32_bf16 v[52:55], v[166:169], v[194:197], v[52:55]
	v_mfma_f32_16x16x32_bf16 v[48:51], v[184:187], v[194:197], v[48:51]
	v_mfma_f32_16x16x32_bf16 v[36:39], v[166:169], v[202:205], v[36:39]
	v_mfma_f32_16x16x32_bf16 v[32:35], v[184:187], v[202:205], v[32:35]
	v_mfma_f32_16x16x32_bf16 v[20:23], v[166:169], v[210:213], v[20:23]
	v_mfma_f32_16x16x32_bf16 v[16:19], v[184:187], v[210:213], v[16:19]
	v_mfma_f32_16x16x32_bf16 v[4:7], v[166:169], v[218:221], v[4:7]
	v_mfma_f32_16x16x32_bf16 v[0:3], v[184:187], v[218:221], v[0:3]
	s_add_i32 vcc_lo, vcc_lo, 2
	s_add_u32 s0, s0, 0x100
	s_addc_u32 s1, s1, 0
	s_add_u32 s96, s96, 0x100
	s_addc_u32 s97, s97, 0
	s_cmp_gt_u32 vcc_lo, 13
	s_setprio 0
	s_barrier
	s_cbranch_scc0 .LBB0_684
	s_and_b64 vcc, exec, s[18:19]
	s_cbranch_vccz .LBB0_687
	s_barrier

; #define PG8_STAGE(bufoff, gbase, voff) do { _Pragma("unroll") for (int _i = 0; _i < 2; ++_i) \
;         __builtin_amdgcn_global_load_lds((const unsigned*)((const char*)(gbase) + (voff)[_i]), (PG8_LAS unsigned*)(lds + (bufoff) + ldsw + _i * 8192), 16, 0, 0); } while (0)
; #define PG8_LDA(dst, b, h) do { _Pragma("unroll") for (int m = 0; m < 4; ++m) _Pragma("unroll") for (int k = 0; k < 2; ++k) dst[m][k] = *(const PG8_LAS bf16x8*)(lds + PG8_SA(b, h) + aoff + m * 2048 + k * 1024); } while (0)
; #define PG8_LDB(dst, b, h) do { _Pragma("unroll") for (int n = 0; n < 2; ++n) _Pragma("unroll") for (int k = 0; k < 2; ++k) dst[n][k] = *(const PG8_LAS bf16x8*)(lds + PG8_SB(b, h) + boff + n * 2048 + k * 1024); } while (0)
; #define PG8_MMA(ai, bj, At, Bt) do { __builtin_amdgcn_s_setprio(1); _Pragma("unroll") for (int m = 0; m < 4; ++m) _Pragma("unroll") for (int n = 0; n < 2; ++n) _Pragma("unroll") for (int k = 0; k < 2; ++k) \
;         acc[ai][bj][m][n] = __builtin_amdgcn_mfma_f32_16x16x32_bf16(Bt[n][k], At[m][k], acc[ai][bj][m][n], 0, 0, 0); __builtin_amdgcn_s_setprio(0); } while (0)
; #define PG8_WAIT_V(n) asm volatile("s_waitcnt vmcnt(" #n ")" ::: "memory")
; #define PG8_BAR __builtin_amdgcn_s_barrier()
; template <class Epi, class Sched, bool ALIGN_EPI = false, bool SP2 = false>
; __device__ __forceinline__ void gemm_phase(PG8_LAS unsigned char* lds, const Gemm g, const Sched& S, const Epi& E) {
;     ...
;         for (int t = 0; t < nt; t += 2) {
;             const bool last = (t == nt - 2);
;             const char* a1 = cA + (size_t)(t + 1) * kstep;
;             const char* a2 = last ? nA : cA + (size_t)(t + 2) * kstep; const char* b2 = last ? nB : cB + (size_t)(t + 2) * kstep;
;             const char* a3 = a2 + kstep; const char* b3 = b2 + kstep;
;             if (last && has_next) S.a_ready(nxt);
;             if constexpr (SP2) {
;             PG8_LDB(B0, 0, 0); PG8_LDB(B1, 0, 1); PG8_SCHED; PG8_LDA(At, 0, 0); PG8_STAGE(PG8_SA(1, 1), a1 + hstep, voffA);
;             PG8_WAIT_V(8); PG8_WAIT_L(0); PG8_BAR; PG8_MMA(0, 0, At, B0); PG8_MMA(0, 1, At, B1); PG8_BAR; PG8_SCHED;
;             PG8_LDA(At, 0, 1); PG8_STAGE(PG8_SB(0, 0), b2, voffB); PG8_STAGE(PG8_SB(0, 1), b2 + hstep, voffB); PG8_STAGE(PG8_SA(0, 0), a2, voffA);
;             PG8_WAIT_V(8); PG8_WAIT_L(0); PG8_BAR; PG8_MMA(1, 0, At, B0); PG8_MMA(1, 1, At, B1); PG8_BAR; PG8_SCHED;
.LBB0_795:
	v_add_u32_e32 v162, s67, v186
	v_add_u32_e32 v178, s68, v186
	ds_read_b128 v[150:153], v162
	ds_read_b128 v[154:157], v162 offset:1024
	ds_read_b128 v[158:161], v162 offset:2048
	ds_read_b128 v[162:165], v162 offset:3072
	ds_read_b128 v[166:169], v178
	ds_read_b128 v[170:173], v178 offset:1024
	ds_read_b128 v[174:177], v178 offset:2048
	ds_read_b128 v[178:181], v178 offset:3072
	s_add_u32 s54, s46, 0xfff80080
	s_addc_u32 s55, s47, -1
	s_cmp_eq_u32 s82, 12
	s_cselect_b32 s57, s41, s55
	s_cselect_b32 s56, s78, s54
	s_cselect_b32 s55, s39, s81
	s_cselect_b32 s54, s79, s80
	s_add_i32 m0, s61, 0xc000
	ds_read_b128 v[182:185], v187
	ds_read_b128 v[190:193], v187 offset:1024
	ds_read_b128 v[194:197], v187 offset:2048
	ds_read_b128 v[198:201], v187 offset:3072
	ds_read_b128 v[202:205], v187 offset:4096
	ds_read_b128 v[206:209], v187 offset:5120
	ds_read_b128 v[210:213], v187 offset:6144
	ds_read_b128 v[214:217], v187 offset:7168
	global_load_lds_dwordx4 v142, s[46:47]
	s_add_i32 m0, s61, 0xe000
	s_nop 0
	global_load_lds_dwordx4 v144, s[46:47]
	s_waitcnt vmcnt(8)
	s_waitcnt lgkmcnt(0)
	s_barrier
	s_setprio 1
	v_mfma_f32_16x16x32_bf16 v[124:127], v[150:153], v[182:185], v[124:127]
	v_mfma_f32_16x16x32_bf16 v[120:123], v[158:161], v[182:185], v[120:123]
	v_mfma_f32_16x16x32_bf16 v[116:119], v[150:153], v[194:197], v[116:119]
	v_mfma_f32_16x16x32_bf16 v[112:115], v[158:161], v[194:197], v[112:115]
	v_mfma_f32_16x16x32_bf16 v[108:111], v[150:153], v[202:205], v[108:111]
	v_mfma_f32_16x16x32_bf16 v[104:107], v[158:161], v[202:205], v[104:107]
	v_mfma_f32_16x16x32_bf16 v[100:103], v[150:153], v[210:213], v[100:103]
	v_mfma_f32_16x16x32_bf16 v[96:99], v[158:161], v[210:213], v[96:99]
	v_mfma_f32_16x16x32_bf16 v[124:127], v[154:157], v[190:193], v[124:127]
	v_mfma_f32_16x16x32_bf16 v[120:123], v[162:165], v[190:193], v[120:123]
	v_mfma_f32_16x16x32_bf16 v[116:119], v[154:157], v[198:201], v[116:119]
	v_mfma_f32_16x16x32_bf16 v[112:115], v[162:165], v[198:201], v[112:115]
	v_mfma_f32_16x16x32_bf16 v[108:111], v[154:157], v[206:209], v[108:111]
	v_mfma_f32_16x16x32_bf16 v[104:107], v[162:165], v[206:209], v[104:107]
	v_mfma_f32_16x16x32_bf16 v[100:103], v[154:157], v[214:217], v[100:103]
	v_mfma_f32_16x16x32_bf16 v[96:99], v[162:165], v[214:217], v[96:99]
	v_mfma_f32_16x16x32_bf16 v[92:95], v[166:169], v[182:185], v[92:95]
	v_mfma_f32_16x16x32_bf16 v[88:91], v[174:177], v[182:185], v[88:91]
	v_mfma_f32_16x16x32_bf16 v[84:87], v[166:169], v[194:197], v[84:87]
	v_mfma_f32_16x16x32_bf16 v[80:83], v[174:177], v[194:197], v[80:83]
	v_mfma_f32_16x16x32_bf16 v[76:79], v[166:169], v[202:205], v[76:79]
	v_mfma_f32_16x16x32_bf16 v[72:75], v[174:177], v[202:205], v[72:75]
	v_mfma_f32_16x16x32_bf16 v[68:71], v[166:169], v[210:213], v[68:71]
	v_mfma_f32_16x16x32_bf16 v[64:67], v[174:177], v[210:213], v[64:67]
	v_mfma_f32_16x16x32_bf16 v[92:95], v[170:173], v[190:193], v[92:95]
	v_mfma_f32_16x16x32_bf16 v[88:91], v[178:181], v[190:193], v[88:91]
	v_mfma_f32_16x16x32_bf16 v[84:87], v[170:173], v[198:201], v[84:87]
	v_mfma_f32_16x16x32_bf16 v[80:83], v[178:181], v[198:201], v[80:83]
	v_mfma_f32_16x16x32_bf16 v[76:79], v[170:173], v[206:209], v[76:79]
	v_mfma_f32_16x16x32_bf16 v[72:75], v[178:181], v[206:209], v[72:75]
	v_mfma_f32_16x16x32_bf16 v[68:71], v[170:173], v[214:217], v[68:71]
	v_mfma_f32_16x16x32_bf16 v[64:67], v[178:181], v[214:217], v[64:67]
	s_add_i32 s83, s67, s60
	v_lshl_add_u64 v[218:219], s[54:55], 0, v[130:131]
	s_setprio 0
	s_barrier
	s_mov_b32 m0, s83
	ds_read_b128 v[182:185], v187 offset:16384
	ds_read_b128 v[190:193], v187 offset:17408
	ds_read_b128 v[194:197], v187 offset:18432
	ds_read_b128 v[198:201], v187 offset:19456
	ds_read_b128 v[202:205], v187 offset:20480
	ds_read_b128 v[206:209], v187 offset:21504
	ds_read_b128 v[210:213], v187 offset:22528
	ds_read_b128 v[214:217], v187 offset:23552
	global_load_lds_dwordx4 v[218:219], off
	s_add_i32 m0, s83, 0x2000
	s_add_u32 s86, s54, 0x80000
	v_lshl_add_u64 v[220:221], s[54:55], 0, v[134:135]
	s_addc_u32 s87, s55, 0
	s_add_i32 s83, s68, s60
	global_load_lds_dwordx4 v[220:221], off
	s_mov_b32 m0, s83
	v_lshl_add_u64 v[224:225], s[56:57], 0, v[132:133]
	global_load_lds_dwordx4 v130, s[86:87]
	s_add_i32 m0, s83, 0x2000
	s_nop 0
	global_load_lds_dwordx4 v134, s[86:87]
	v_lshl_add_u64 v[222:223], s[56:57], 0, v[128:129]
	s_mov_b32 m0, s61
	s_nop 0
	global_load_lds_dwordx4 v[222:223], off
	s_mov_b32 m0, s62
	s_nop 0
	global_load_lds_dwordx4 v[224:225], off
	s_waitcnt vmcnt(8)
	s_waitcnt lgkmcnt(0)
	s_barrier
; #define PG8_STAGE(bufoff, gbase, voff) do { _Pragma("unroll") for (int _i = 0; _i < 2; ++_i) \
;         __builtin_amdgcn_global_load_lds((const unsigned*)((const char*)(gbase) + (voff)[_i]), (PG8_LAS unsigned*)(lds + (bufoff) + ldsw + _i * 8192), 16, 0, 0); } while (0)
; #define PG8_LDA(dst, b, h) do { _Pragma("unroll") for (int m = 0; m < 4; ++m) _Pragma("unroll") for (int k = 0; k < 2; ++k) dst[m][k] = *(const PG8_LAS bf16x8*)(lds + PG8_SA(b, h) + aoff + m * 2048 + k * 1024); } while (0)
; #define PG8_LDB(dst, b, h) do { _Pragma("unroll") for (int n = 0; n < 2; ++n) _Pragma("unroll") for (int k = 0; k < 2; ++k) dst[n][k] = *(const PG8_LAS bf16x8*)(lds + PG8_SB(b, h) + boff + n * 2048 + k * 1024); } while (0)
; #define PG8_MMA(ai, bj, At, Bt) do { __builtin_amdgcn_s_setprio(1); _Pragma("unroll") for (int m = 0; m < 4; ++m) _Pragma("unroll") for (int n = 0; n < 2; ++n) _Pragma("unroll") for (int k = 0; k < 2; ++k) \
;         acc[ai][bj][m][n] = __builtin_amdgcn_mfma_f32_16x16x32_bf16(Bt[n][k], At[m][k], acc[ai][bj][m][n], 0, 0, 0); __builtin_amdgcn_s_setprio(0); } while (0)
; #define PG8_WAIT_V(n) asm volatile("s_waitcnt vmcnt(" #n ")" ::: "memory")
; #define PG8_WAIT_L(n) asm volatile("s_waitcnt lgkmcnt(" #n ")" ::: "memory")
; #define PG8_BAR __builtin_amdgcn_s_barrier()
; #define PG8_SCHED __builtin_amdgcn_sched_barrier(0)
; template <class Epi, class Sched, bool ALIGN_EPI = false, bool SP2 = false>
; __device__ __forceinline__ void gemm_phase(PG8_LAS unsigned char* lds, const Gemm g, const Sched& S, const Epi& E) {
;     ...
;             PG8_LDA(At, 0, 1); PG8_STAGE(PG8_SB(0, 0), b2, voffB); PG8_STAGE(PG8_SB(0, 1), b2 + hstep, voffB); PG8_STAGE(PG8_SA(0, 0), a2, voffA);
;             PG8_WAIT_V(8); PG8_WAIT_L(0); PG8_BAR; PG8_MMA(1, 0, At, B0); PG8_MMA(1, 1, At, B1); PG8_BAR; PG8_SCHED;
;             PG8_LDB(B0, 1, 0); PG8_LDB(B1, 1, 1); PG8_SCHED; PG8_LDA(At, 1, 0); PG8_STAGE(PG8_SA(0, 1), a2 + hstep, voffA);
;             PG8_WAIT_V(8); PG8_WAIT_L(0); PG8_BAR; PG8_MMA(0, 0, At, B0); PG8_MMA(0, 1, At, B1); PG8_BAR; PG8_SCHED;
;             PG8_LDA(At, 1, 1); PG8_STAGE(PG8_SB(1, 0), b3, voffB); PG8_STAGE(PG8_SB(1, 1), b3 + hstep, voffB); PG8_STAGE(PG8_SA(1, 0), a3, voffA);
;             PG8_WAIT_V(8); PG8_WAIT_L(0); PG8_BAR; PG8_MMA(1, 0, At, B0); PG8_MMA(1, 1, At, B1); PG8_BAR; PG8_SCHED;
	s_setprio 1
	v_mfma_f32_16x16x32_bf16 v[60:63], v[150:153], v[182:185], v[60:63]
	v_mfma_f32_16x16x32_bf16 v[56:59], v[158:161], v[182:185], v[56:59]
	v_mfma_f32_16x16x32_bf16 v[52:55], v[150:153], v[194:197], v[52:55]
	v_mfma_f32_16x16x32_bf16 v[48:51], v[158:161], v[194:197], v[48:51]
	v_mfma_f32_16x16x32_bf16 v[44:47], v[150:153], v[202:205], v[44:47]
	v_mfma_f32_16x16x32_bf16 v[40:43], v[158:161], v[202:205], v[40:43]
	v_mfma_f32_16x16x32_bf16 v[36:39], v[150:153], v[210:213], v[36:39]
	v_mfma_f32_16x16x32_bf16 v[32:35], v[158:161], v[210:213], v[32:35]
	v_mfma_f32_16x16x32_bf16 v[60:63], v[154:157], v[190:193], v[60:63]
	v_mfma_f32_16x16x32_bf16 v[56:59], v[162:165], v[190:193], v[56:59]
	v_mfma_f32_16x16x32_bf16 v[52:55], v[154:157], v[198:201], v[52:55]
	v_mfma_f32_16x16x32_bf16 v[48:51], v[162:165], v[198:201], v[48:51]
	v_mfma_f32_16x16x32_bf16 v[44:47], v[154:157], v[206:209], v[44:47]
	v_mfma_f32_16x16x32_bf16 v[40:43], v[162:165], v[206:209], v[40:43]
	v_mfma_f32_16x16x32_bf16 v[36:39], v[154:157], v[214:217], v[36:39]
	v_mfma_f32_16x16x32_bf16 v[32:35], v[162:165], v[214:217], v[32:35]
	v_mfma_f32_16x16x32_bf16 v[28:31], v[166:169], v[182:185], v[28:31]
	v_mfma_f32_16x16x32_bf16 v[24:27], v[174:177], v[182:185], v[24:27]
	v_mfma_f32_16x16x32_bf16 v[20:23], v[166:169], v[194:197], v[20:23]
	v_mfma_f32_16x16x32_bf16 v[16:19], v[174:177], v[194:197], v[16:19]
	v_mfma_f32_16x16x32_bf16 v[12:15], v[166:169], v[202:205], v[12:15]
	v_mfma_f32_16x16x32_bf16 v[8:11], v[174:177], v[202:205], v[8:11]
	v_mfma_f32_16x16x32_bf16 v[4:7], v[166:169], v[210:213], v[4:7]
	v_mfma_f32_16x16x32_bf16 v[0:3], v[174:177], v[210:213], v[0:3]
	v_mfma_f32_16x16x32_bf16 v[28:31], v[170:173], v[190:193], v[28:31]
	v_mfma_f32_16x16x32_bf16 v[24:27], v[178:181], v[190:193], v[24:27]
	v_mfma_f32_16x16x32_bf16 v[20:23], v[170:173], v[198:201], v[20:23]
	v_mfma_f32_16x16x32_bf16 v[16:19], v[178:181], v[198:201], v[16:19]
	v_mfma_f32_16x16x32_bf16 v[12:15], v[170:173], v[206:209], v[12:15]
	v_mfma_f32_16x16x32_bf16 v[8:11], v[178:181], v[206:209], v[8:11]
	v_mfma_f32_16x16x32_bf16 v[4:7], v[170:173], v[214:217], v[4:7]
	v_mfma_f32_16x16x32_bf16 v[0:3], v[178:181], v[214:217], v[0:3]
	s_add_i32 s83, 0, 0x18000
	s_add_i32 s86, 0, 0x1c000
	v_add_u32_e32 v162, s83, v186
	v_add_u32_e32 v178, s86, v186
	s_setprio 0
	s_barrier
	ds_read_b128 v[150:153], v162
	ds_read_b128 v[154:157], v162 offset:1024
	ds_read_b128 v[158:161], v162 offset:2048
	ds_read_b128 v[162:165], v162 offset:3072
	ds_read_b128 v[166:169], v178
	ds_read_b128 v[170:173], v178 offset:1024
	ds_read_b128 v[174:177], v178 offset:2048
	ds_read_b128 v[178:181], v178 offset:3072
	s_add_u32 s56, s56, 0x80000
	s_addc_u32 s57, s57, 0
	s_mov_b32 m0, s63
	ds_read_b128 v[182:185], v187 offset:32768
	ds_read_b128 v[190:193], v187 offset:33792
	ds_read_b128 v[194:197], v187 offset:34816
	ds_read_b128 v[198:201], v187 offset:35840
	ds_read_b128 v[202:205], v187 offset:36864
	ds_read_b128 v[206:209], v187 offset:37888
	ds_read_b128 v[210:213], v187 offset:38912
	ds_read_b128 v[214:217], v187 offset:39936
	global_load_lds_dwordx4 v128, s[56:57]
	s_mov_b32 m0, s64
	s_nop 0
	global_load_lds_dwordx4 v132, s[56:57]
	s_waitcnt vmcnt(8)
	s_waitcnt lgkmcnt(0)
	s_barrier
	s_setprio 1
	v_mfma_f32_16x16x32_bf16 v[124:127], v[150:153], v[182:185], v[124:127]
	v_mfma_f32_16x16x32_bf16 v[120:123], v[158:161], v[182:185], v[120:123]
	v_mfma_f32_16x16x32_bf16 v[116:119], v[150:153], v[194:197], v[116:119]
	v_mfma_f32_16x16x32_bf16 v[112:115], v[158:161], v[194:197], v[112:115]
	v_mfma_f32_16x16x32_bf16 v[108:111], v[150:153], v[202:205], v[108:111]
	v_mfma_f32_16x16x32_bf16 v[104:107], v[158:161], v[202:205], v[104:107]
	v_mfma_f32_16x16x32_bf16 v[100:103], v[150:153], v[210:213], v[100:103]
	v_mfma_f32_16x16x32_bf16 v[96:99], v[158:161], v[210:213], v[96:99]
	v_mfma_f32_16x16x32_bf16 v[124:127], v[154:157], v[190:193], v[124:127]
	v_mfma_f32_16x16x32_bf16 v[120:123], v[162:165], v[190:193], v[120:123]
	v_mfma_f32_16x16x32_bf16 v[116:119], v[154:157], v[198:201], v[116:119]
	v_mfma_f32_16x16x32_bf16 v[112:115], v[162:165], v[198:201], v[112:115]
	v_mfma_f32_16x16x32_bf16 v[108:111], v[154:157], v[206:209], v[108:111]
	v_mfma_f32_16x16x32_bf16 v[104:107], v[162:165], v[206:209], v[104:107]
	v_mfma_f32_16x16x32_bf16 v[100:103], v[154:157], v[214:217], v[100:103]
	v_mfma_f32_16x16x32_bf16 v[96:99], v[162:165], v[214:217], v[96:99]
	v_mfma_f32_16x16x32_bf16 v[92:95], v[166:169], v[182:185], v[92:95]
	v_mfma_f32_16x16x32_bf16 v[88:91], v[174:177], v[182:185], v[88:91]
	v_mfma_f32_16x16x32_bf16 v[84:87], v[166:169], v[194:197], v[84:87]
	v_mfma_f32_16x16x32_bf16 v[80:83], v[174:177], v[194:197], v[80:83]
	v_mfma_f32_16x16x32_bf16 v[76:79], v[166:169], v[202:205], v[76:79]
	v_mfma_f32_16x16x32_bf16 v[72:75], v[174:177], v[202:205], v[72:75]
	v_mfma_f32_16x16x32_bf16 v[68:71], v[166:169], v[210:213], v[68:71]
	v_mfma_f32_16x16x32_bf16 v[64:67], v[174:177], v[210:213], v[64:67]
	v_mfma_f32_16x16x32_bf16 v[92:95], v[170:173], v[190:193], v[92:95]
	v_mfma_f32_16x16x32_bf16 v[88:91], v[178:181], v[190:193], v[88:91]
	v_mfma_f32_16x16x32_bf16 v[84:87], v[170:173], v[198:201], v[84:87]
	v_mfma_f32_16x16x32_bf16 v[80:83], v[178:181], v[198:201], v[80:83]
	v_mfma_f32_16x16x32_bf16 v[76:79], v[170:173], v[206:209], v[76:79]
	v_mfma_f32_16x16x32_bf16 v[72:75], v[178:181], v[206:209], v[72:75]
	v_mfma_f32_16x16x32_bf16 v[68:71], v[170:173], v[214:217], v[68:71]
	v_mfma_f32_16x16x32_bf16 v[64:67], v[178:181], v[214:217], v[64:67]
	s_add_i32 s56, s83, s60
	v_lshl_add_u64 v[218:219], v[218:219], 0, s[14:15]
	s_setprio 0
	s_barrier
; #define PG8_STAGE(bufoff, gbase, voff) do { _Pragma("unroll") for (int _i = 0; _i < 2; ++_i) \
;         __builtin_amdgcn_global_load_lds((const unsigned*)((const char*)(gbase) + (voff)[_i]), (PG8_LAS unsigned*)(lds + (bufoff) + ldsw + _i * 8192), 16, 0, 0); } while (0)
; #define PG8_LDA(dst, b, h) do { _Pragma("unroll") for (int m = 0; m < 4; ++m) _Pragma("unroll") for (int k = 0; k < 2; ++k) dst[m][k] = *(const PG8_LAS bf16x8*)(lds + PG8_SA(b, h) + aoff + m * 2048 + k * 1024); } while (0)
; #define PG8_MMA(ai, bj, At, Bt) do { __builtin_amdgcn_s_setprio(1); _Pragma("unroll") for (int m = 0; m < 4; ++m) _Pragma("unroll") for (int n = 0; n < 2; ++n) _Pragma("unroll") for (int k = 0; k < 2; ++k) \
;         acc[ai][bj][m][n] = __builtin_amdgcn_mfma_f32_16x16x32_bf16(Bt[n][k], At[m][k], acc[ai][bj][m][n], 0, 0, 0); __builtin_amdgcn_s_setprio(0); } while (0)
; #define PG8_WAIT_V(n) asm volatile("s_waitcnt vmcnt(" #n ")" ::: "memory")
; #define PG8_WAIT_L(n) asm volatile("s_waitcnt lgkmcnt(" #n ")" ::: "memory")
; #define PG8_BAR __builtin_amdgcn_s_barrier()
; #define PG8_SCHED __builtin_amdgcn_sched_barrier(0)
; template <class Epi, class Sched, bool ALIGN_EPI = false, bool SP2 = false>
; __device__ __forceinline__ void gemm_phase(PG8_LAS unsigned char* lds, const Gemm g, const Sched& S, const Epi& E) {
;     ...
;         for (int t = 0; t < nt; t += 2) {
;             const bool last = (t == nt - 2);
;             const char* a1 = cA + (size_t)(t + 1) * kstep;
;             const char* a2 = last ? nA : cA + (size_t)(t + 2) * kstep; const char* b2 = last ? nB : cB + (size_t)(t + 2) * kstep;
;             const char* a3 = a2 + kstep; const char* b3 = b2 + kstep;
;     ...
;             PG8_LDA(At, 1, 1); PG8_STAGE(PG8_SB(1, 0), b3, voffB); PG8_STAGE(PG8_SB(1, 1), b3 + hstep, voffB); PG8_STAGE(PG8_SA(1, 0), a3, voffA);
;             PG8_WAIT_V(8); PG8_WAIT_L(0); PG8_BAR; PG8_MMA(1, 0, At, B0); PG8_MMA(1, 1, At, B1); PG8_BAR; PG8_SCHED;
	s_mov_b32 m0, s56
	ds_read_b128 v[182:185], v187 offset:49152
	ds_read_b128 v[190:193], v187 offset:50176
	ds_read_b128 v[194:197], v187 offset:51200
	ds_read_b128 v[198:201], v187 offset:52224
	ds_read_b128 v[202:205], v187 offset:53248
	ds_read_b128 v[206:209], v187 offset:54272
	ds_read_b128 v[210:213], v187 offset:55296
	ds_read_b128 v[214:217], v187 offset:56320
	global_load_lds_dwordx4 v[218:219], off
	s_add_i32 m0, s56, 0x2000
	s_add_u32 s54, s54, 0x80080
	v_lshl_add_u64 v[218:219], v[220:221], 0, s[14:15]
	s_addc_u32 s55, s55, 0
	s_add_i32 s56, s86, s60
	global_load_lds_dwordx4 v[218:219], off
	s_mov_b32 m0, s56
	s_nop 0
	global_load_lds_dwordx4 v130, s[54:55]
	s_add_i32 m0, s56, 0x2000
	s_nop 0
	global_load_lds_dwordx4 v134, s[54:55]
	v_lshl_add_u64 v[218:219], v[222:223], 0, s[14:15]
	s_mov_b32 m0, s65
	s_nop 0
	global_load_lds_dwordx4 v[218:219], off
	v_lshl_add_u64 v[218:219], v[224:225], 0, s[14:15]
	s_mov_b32 m0, s66
	s_nop 0
	global_load_lds_dwordx4 v[218:219], off
	s_waitcnt vmcnt(8)
	s_waitcnt lgkmcnt(0)
	s_barrier
	s_setprio 1
	v_mfma_f32_16x16x32_bf16 v[60:63], v[150:153], v[182:185], v[60:63]
	v_mfma_f32_16x16x32_bf16 v[56:59], v[158:161], v[182:185], v[56:59]
	v_mfma_f32_16x16x32_bf16 v[52:55], v[150:153], v[194:197], v[52:55]
	v_mfma_f32_16x16x32_bf16 v[48:51], v[158:161], v[194:197], v[48:51]
	v_mfma_f32_16x16x32_bf16 v[44:47], v[150:153], v[202:205], v[44:47]
	v_mfma_f32_16x16x32_bf16 v[40:43], v[158:161], v[202:205], v[40:43]
	v_mfma_f32_16x16x32_bf16 v[36:39], v[150:153], v[210:213], v[36:39]
	v_mfma_f32_16x16x32_bf16 v[32:35], v[158:161], v[210:213], v[32:35]
	v_mfma_f32_16x16x32_bf16 v[60:63], v[154:157], v[190:193], v[60:63]
	v_mfma_f32_16x16x32_bf16 v[56:59], v[162:165], v[190:193], v[56:59]
	v_mfma_f32_16x16x32_bf16 v[52:55], v[154:157], v[198:201], v[52:55]
	v_mfma_f32_16x16x32_bf16 v[48:51], v[162:165], v[198:201], v[48:51]
	v_mfma_f32_16x16x32_bf16 v[44:47], v[154:157], v[206:209], v[44:47]
	v_mfma_f32_16x16x32_bf16 v[40:43], v[162:165], v[206:209], v[40:43]
	v_mfma_f32_16x16x32_bf16 v[36:39], v[154:157], v[214:217], v[36:39]
	v_mfma_f32_16x16x32_bf16 v[32:35], v[162:165], v[214:217], v[32:35]
	v_mfma_f32_16x16x32_bf16 v[28:31], v[166:169], v[182:185], v[28:31]
	v_mfma_f32_16x16x32_bf16 v[24:27], v[174:177], v[182:185], v[24:27]
	v_mfma_f32_16x16x32_bf16 v[20:23], v[166:169], v[194:197], v[20:23]
	v_mfma_f32_16x16x32_bf16 v[16:19], v[174:177], v[194:197], v[16:19]
	v_mfma_f32_16x16x32_bf16 v[12:15], v[166:169], v[202:205], v[12:15]
	v_mfma_f32_16x16x32_bf16 v[8:11], v[174:177], v[202:205], v[8:11]
	v_mfma_f32_16x16x32_bf16 v[4:7], v[166:169], v[210:213], v[4:7]
	v_mfma_f32_16x16x32_bf16 v[0:3], v[174:177], v[210:213], v[0:3]
	v_mfma_f32_16x16x32_bf16 v[28:31], v[170:173], v[190:193], v[28:31]
	v_mfma_f32_16x16x32_bf16 v[24:27], v[178:181], v[190:193], v[24:27]
	v_mfma_f32_16x16x32_bf16 v[20:23], v[170:173], v[198:201], v[20:23]
	v_mfma_f32_16x16x32_bf16 v[16:19], v[178:181], v[198:201], v[16:19]
	v_mfma_f32_16x16x32_bf16 v[12:15], v[170:173], v[206:209], v[12:15]
	v_mfma_f32_16x16x32_bf16 v[8:11], v[178:181], v[206:209], v[8:11]
	v_mfma_f32_16x16x32_bf16 v[4:7], v[170:173], v[214:217], v[4:7]
	v_mfma_f32_16x16x32_bf16 v[0:3], v[178:181], v[214:217], v[0:3]
	s_add_i32 s82, s82, 2
	s_add_u32 s46, s46, 0x100
	s_addc_u32 s47, s47, 0
	s_add_u32 s80, s80, 0x100
	s_addc_u32 s81, s81, 0
	s_cmp_gt_u32 s82, 13
	s_setprio 0
	s_barrier
	s_cbranch_scc0 .LBB0_795
	s_and_b64 vcc, exec, s[16:17]
	s_cbranch_vccz .LBB0_798
	s_barrier

; #define PG8_STAGE(bufoff, gbase, voff) do { _Pragma("unroll") for (int _i = 0; _i < 2; ++_i) \
;         __builtin_amdgcn_global_load_lds((const unsigned*)((const char*)(gbase) + (voff)[_i]), (PG8_LAS unsigned*)(lds + (bufoff) + ldsw + _i * 8192), 16, 0, 0); } while (0)
; #define PG8_LDA(dst, b, h) do { _Pragma("unroll") for (int m = 0; m < 4; ++m) _Pragma("unroll") for (int k = 0; k < 2; ++k) dst[m][k] = *(const PG8_LAS bf16x8*)(lds + PG8_SA(b, h) + aoff + m * 2048 + k * 1024); } while (0)
; #define PG8_LDB(dst, b, h) do { _Pragma("unroll") for (int n = 0; n < 2; ++n) _Pragma("unroll") for (int k = 0; k < 2; ++k) dst[n][k] = *(const PG8_LAS bf16x8*)(lds + PG8_SB(b, h) + boff + n * 2048 + k * 1024); } while (0)
; #define PG8_MMA(ai, bj, At, Bt) do { __builtin_amdgcn_s_setprio(1); _Pragma("unroll") for (int m = 0; m < 4; ++m) _Pragma("unroll") for (int n = 0; n < 2; ++n) _Pragma("unroll") for (int k = 0; k < 2; ++k) \
;         acc[ai][bj][m][n] = __builtin_amdgcn_mfma_f32_16x16x32_bf16(Bt[n][k], At[m][k], acc[ai][bj][m][n], 0, 0, 0); __builtin_amdgcn_s_setprio(0); } while (0)
; #define PG8_WAIT_V(n) asm volatile("s_waitcnt vmcnt(" #n ")" ::: "memory")
; #define PG8_BAR __builtin_amdgcn_s_barrier()
; template <class Epi, class Sched, bool ALIGN_EPI = false, bool SP2 = false>
; __device__ __forceinline__ void gemm_phase(PG8_LAS unsigned char* lds, const Gemm g, const Sched& S, const Epi& E) {
;     ...
;         for (int t = 0; t < nt; t += 2) {
;             const bool last = (t == nt - 2);
;             const char* a1 = cA + (size_t)(t + 1) * kstep;
;             const char* a2 = last ? nA : cA + (size_t)(t + 2) * kstep; const char* b2 = last ? nB : cB + (size_t)(t + 2) * kstep;
;             const char* a3 = a2 + kstep; const char* b3 = b2 + kstep;
;             if (last && has_next) S.a_ready(nxt);
;             if constexpr (SP2) {
;             PG8_LDB(B0, 0, 0); PG8_LDB(B1, 0, 1); PG8_SCHED; PG8_LDA(At, 0, 0); PG8_STAGE(PG8_SA(1, 1), a1 + hstep, voffA);
;             PG8_WAIT_V(8); PG8_WAIT_L(0); PG8_BAR; PG8_MMA(0, 0, At, B0); PG8_MMA(0, 1, At, B1); PG8_BAR; PG8_SCHED;
;             PG8_LDA(At, 0, 1); PG8_STAGE(PG8_SB(0, 0), b2, voffB); PG8_STAGE(PG8_SB(0, 1), b2 + hstep, voffB); PG8_STAGE(PG8_SA(0, 0), a2, voffA);
;             PG8_WAIT_V(8); PG8_WAIT_L(0); PG8_BAR; PG8_MMA(1, 0, At, B0); PG8_MMA(1, 1, At, B1); PG8_BAR; PG8_SCHED;
.LBB0_882:
	ds_read_b128 v[128:131], v173
	ds_read_b128 v[132:135], v173 offset:1024
	ds_read_b128 v[136:139], v173 offset:2048
	ds_read_b128 v[140:143], v173 offset:3072
	ds_read_b128 v[164:167], v174
	ds_read_b128 v[168:171], v174 offset:1024
	ds_read_b128 v[178:181], v174 offset:2048
	ds_read_b128 v[182:185], v174 offset:3072
	s_add_u32 s34, s30, 0xfffc0080
	s_addc_u32 s35, s31, -1
	s_cmp_eq_u32 s61, 12
	s_cselect_b32 s37, s23, s35
	s_cselect_b32 s36, s29, s34
	s_cselect_b32 s35, s21, s60
	s_cselect_b32 s34, s58, s59
	s_add_i32 m0, s43, 0xc000
	ds_read_b128 v[190:193], v175
	ds_read_b128 v[194:197], v175 offset:1024
	ds_read_b128 v[198:201], v175 offset:2048
	ds_read_b128 v[202:205], v175 offset:3072
	ds_read_b128 v[206:209], v175 offset:4096
	ds_read_b128 v[210:213], v175 offset:5120
	ds_read_b128 v[214:217], v175 offset:6144
	ds_read_b128 v[218:221], v175 offset:7168
	global_load_lds_dwordx4 v156, s[30:31]
	s_add_i32 m0, s43, 0xe000
	s_nop 0
	global_load_lds_dwordx4 v158, s[30:31]
	s_waitcnt vmcnt(8)
	s_waitcnt lgkmcnt(0)
	s_barrier
	s_setprio 1
	v_mfma_f32_16x16x32_bf16 v[124:127], v[128:131], v[190:193], v[124:127]
	v_mfma_f32_16x16x32_bf16 v[120:123], v[136:139], v[190:193], v[120:123]
	v_mfma_f32_16x16x32_bf16 v[108:111], v[128:131], v[198:201], v[108:111]
	v_mfma_f32_16x16x32_bf16 v[104:107], v[136:139], v[198:201], v[104:107]
	v_mfma_f32_16x16x32_bf16 v[92:95], v[128:131], v[206:209], v[92:95]
	v_mfma_f32_16x16x32_bf16 v[88:91], v[136:139], v[206:209], v[88:91]
	v_mfma_f32_16x16x32_bf16 v[76:79], v[128:131], v[214:217], v[76:79]
	v_mfma_f32_16x16x32_bf16 v[72:75], v[136:139], v[214:217], v[72:75]
	v_mfma_f32_16x16x32_bf16 v[124:127], v[132:135], v[194:197], v[124:127]
	v_mfma_f32_16x16x32_bf16 v[120:123], v[140:143], v[194:197], v[120:123]
	v_mfma_f32_16x16x32_bf16 v[108:111], v[132:135], v[202:205], v[108:111]
	v_mfma_f32_16x16x32_bf16 v[104:107], v[140:143], v[202:205], v[104:107]
	v_mfma_f32_16x16x32_bf16 v[92:95], v[132:135], v[210:213], v[92:95]
	v_mfma_f32_16x16x32_bf16 v[88:91], v[140:143], v[210:213], v[88:91]
	v_mfma_f32_16x16x32_bf16 v[76:79], v[132:135], v[218:221], v[76:79]
	v_mfma_f32_16x16x32_bf16 v[72:75], v[140:143], v[218:221], v[72:75]
	v_mfma_f32_16x16x32_bf16 v[116:119], v[164:167], v[190:193], v[116:119]
	v_mfma_f32_16x16x32_bf16 v[112:115], v[178:181], v[190:193], v[112:115]
	v_mfma_f32_16x16x32_bf16 v[100:103], v[164:167], v[198:201], v[100:103]
	v_mfma_f32_16x16x32_bf16 v[96:99], v[178:181], v[198:201], v[96:99]
	v_mfma_f32_16x16x32_bf16 v[84:87], v[164:167], v[206:209], v[84:87]
	v_mfma_f32_16x16x32_bf16 v[80:83], v[178:181], v[206:209], v[80:83]
	v_mfma_f32_16x16x32_bf16 v[68:71], v[164:167], v[214:217], v[68:71]
	v_mfma_f32_16x16x32_bf16 v[64:67], v[178:181], v[214:217], v[64:67]
	v_mfma_f32_16x16x32_bf16 v[116:119], v[168:171], v[194:197], v[116:119]
	v_mfma_f32_16x16x32_bf16 v[112:115], v[182:185], v[194:197], v[112:115]
	v_mfma_f32_16x16x32_bf16 v[100:103], v[168:171], v[202:205], v[100:103]
	v_mfma_f32_16x16x32_bf16 v[96:99], v[182:185], v[202:205], v[96:99]
	v_mfma_f32_16x16x32_bf16 v[84:87], v[168:171], v[210:213], v[84:87]
	v_mfma_f32_16x16x32_bf16 v[80:83], v[182:185], v[210:213], v[80:83]
	v_mfma_f32_16x16x32_bf16 v[68:71], v[168:171], v[218:221], v[68:71]
	v_mfma_f32_16x16x32_bf16 v[64:67], v[182:185], v[218:221], v[64:67]
	s_add_i32 s62, s55, s42
	v_lshl_add_u64 v[186:187], s[34:35], 0, v[146:147]
	s_setprio 0
	s_barrier
	s_mov_b32 m0, s62
	ds_read_b128 v[190:193], v175 offset:16384
	ds_read_b128 v[194:197], v175 offset:17408
	ds_read_b128 v[198:201], v175 offset:18432
	ds_read_b128 v[202:205], v175 offset:19456
	ds_read_b128 v[206:209], v175 offset:20480
	ds_read_b128 v[210:213], v175 offset:21504
	ds_read_b128 v[214:217], v175 offset:22528
	ds_read_b128 v[218:221], v175 offset:23552
	global_load_lds_dwordx4 v[186:187], off
	s_add_i32 m0, s62, 0x2000
	s_add_u32 s62, s34, 0x40000
	v_lshl_add_u64 v[222:223], s[34:35], 0, v[150:151]
	s_addc_u32 s63, s35, 0
	s_add_i32 s64, s56, s42
	global_load_lds_dwordx4 v[222:223], off
	s_mov_b32 m0, s64
	v_lshl_add_u64 v[226:227], s[36:37], 0, v[148:149]
	global_load_lds_dwordx4 v146, s[62:63]
	s_add_i32 m0, s64, 0x2000
	s_nop 0
	global_load_lds_dwordx4 v150, s[62:63]
	v_lshl_add_u64 v[224:225], s[36:37], 0, v[144:145]
	s_mov_b32 m0, s43
	s_nop 0
	global_load_lds_dwordx4 v[224:225], off
	s_mov_b32 m0, s44
	s_nop 0
	global_load_lds_dwordx4 v[226:227], off
	s_waitcnt vmcnt(8)
	s_waitcnt lgkmcnt(0)
	s_barrier
; #define PG8_STAGE(bufoff, gbase, voff) do { _Pragma("unroll") for (int _i = 0; _i < 2; ++_i) \
;         __builtin_amdgcn_global_load_lds((const unsigned*)((const char*)(gbase) + (voff)[_i]), (PG8_LAS unsigned*)(lds + (bufoff) + ldsw + _i * 8192), 16, 0, 0); } while (0)
; #define PG8_LDA(dst, b, h) do { _Pragma("unroll") for (int m = 0; m < 4; ++m) _Pragma("unroll") for (int k = 0; k < 2; ++k) dst[m][k] = *(const PG8_LAS bf16x8*)(lds + PG8_SA(b, h) + aoff + m * 2048 + k * 1024); } while (0)
; #define PG8_LDB(dst, b, h) do { _Pragma("unroll") for (int n = 0; n < 2; ++n) _Pragma("unroll") for (int k = 0; k < 2; ++k) dst[n][k] = *(const PG8_LAS bf16x8*)(lds + PG8_SB(b, h) + boff + n * 2048 + k * 1024); } while (0)
; #define PG8_MMA(ai, bj, At, Bt) do { __builtin_amdgcn_s_setprio(1); _Pragma("unroll") for (int m = 0; m < 4; ++m) _Pragma("unroll") for (int n = 0; n < 2; ++n) _Pragma("unroll") for (int k = 0; k < 2; ++k) \
;         acc[ai][bj][m][n] = __builtin_amdgcn_mfma_f32_16x16x32_bf16(Bt[n][k], At[m][k], acc[ai][bj][m][n], 0, 0, 0); __builtin_amdgcn_s_setprio(0); } while (0)
; #define PG8_WAIT_V(n) asm volatile("s_waitcnt vmcnt(" #n ")" ::: "memory")
; #define PG8_WAIT_L(n) asm volatile("s_waitcnt lgkmcnt(" #n ")" ::: "memory")
; #define PG8_BAR __builtin_amdgcn_s_barrier()
; #define PG8_SCHED __builtin_amdgcn_sched_barrier(0)
; template <class Epi, class Sched, bool ALIGN_EPI = false, bool SP2 = false>
; __device__ __forceinline__ void gemm_phase(PG8_LAS unsigned char* lds, const Gemm g, const Sched& S, const Epi& E) {
;     ...
;             PG8_LDA(At, 0, 1); PG8_STAGE(PG8_SB(0, 0), b2, voffB); PG8_STAGE(PG8_SB(0, 1), b2 + hstep, voffB); PG8_STAGE(PG8_SA(0, 0), a2, voffA);
;             PG8_WAIT_V(8); PG8_WAIT_L(0); PG8_BAR; PG8_MMA(1, 0, At, B0); PG8_MMA(1, 1, At, B1); PG8_BAR; PG8_SCHED;
;             PG8_LDB(B0, 1, 0); PG8_LDB(B1, 1, 1); PG8_SCHED; PG8_LDA(At, 1, 0); PG8_STAGE(PG8_SA(0, 1), a2 + hstep, voffA);
;             PG8_WAIT_V(8); PG8_WAIT_L(0); PG8_BAR; PG8_MMA(0, 0, At, B0); PG8_MMA(0, 1, At, B1); PG8_BAR; PG8_SCHED;
;             PG8_LDA(At, 1, 1); PG8_STAGE(PG8_SB(1, 0), b3, voffB); PG8_STAGE(PG8_SB(1, 1), b3 + hstep, voffB); PG8_STAGE(PG8_SA(1, 0), a3, voffA);
;             PG8_WAIT_V(8); PG8_WAIT_L(0); PG8_BAR; PG8_MMA(1, 0, At, B0); PG8_MMA(1, 1, At, B1); PG8_BAR; PG8_SCHED;
	s_setprio 1
	v_mfma_f32_16x16x32_bf16 v[60:63], v[128:131], v[190:193], v[60:63]
	v_mfma_f32_16x16x32_bf16 v[56:59], v[136:139], v[190:193], v[56:59]
	v_mfma_f32_16x16x32_bf16 v[44:47], v[128:131], v[198:201], v[44:47]
	v_mfma_f32_16x16x32_bf16 v[40:43], v[136:139], v[198:201], v[40:43]
	v_mfma_f32_16x16x32_bf16 v[28:31], v[128:131], v[206:209], v[28:31]
	v_mfma_f32_16x16x32_bf16 v[24:27], v[136:139], v[206:209], v[24:27]
	v_mfma_f32_16x16x32_bf16 v[12:15], v[128:131], v[214:217], v[12:15]
	v_mfma_f32_16x16x32_bf16 v[8:11], v[136:139], v[214:217], v[8:11]
	v_mfma_f32_16x16x32_bf16 v[60:63], v[132:135], v[194:197], v[60:63]
	v_mfma_f32_16x16x32_bf16 v[56:59], v[140:143], v[194:197], v[56:59]
	v_mfma_f32_16x16x32_bf16 v[44:47], v[132:135], v[202:205], v[44:47]
	v_mfma_f32_16x16x32_bf16 v[40:43], v[140:143], v[202:205], v[40:43]
	v_mfma_f32_16x16x32_bf16 v[28:31], v[132:135], v[210:213], v[28:31]
	v_mfma_f32_16x16x32_bf16 v[24:27], v[140:143], v[210:213], v[24:27]
	v_mfma_f32_16x16x32_bf16 v[12:15], v[132:135], v[218:221], v[12:15]
	v_mfma_f32_16x16x32_bf16 v[8:11], v[140:143], v[218:221], v[8:11]
	v_mfma_f32_16x16x32_bf16 v[52:55], v[164:167], v[190:193], v[52:55]
	v_mfma_f32_16x16x32_bf16 v[48:51], v[178:181], v[190:193], v[48:51]
	v_mfma_f32_16x16x32_bf16 v[36:39], v[164:167], v[198:201], v[36:39]
	v_mfma_f32_16x16x32_bf16 v[32:35], v[178:181], v[198:201], v[32:35]
	v_mfma_f32_16x16x32_bf16 v[20:23], v[164:167], v[206:209], v[20:23]
	v_mfma_f32_16x16x32_bf16 v[16:19], v[178:181], v[206:209], v[16:19]
	v_mfma_f32_16x16x32_bf16 v[4:7], v[164:167], v[214:217], v[4:7]
	v_mfma_f32_16x16x32_bf16 v[0:3], v[178:181], v[214:217], v[0:3]
	v_mfma_f32_16x16x32_bf16 v[52:55], v[168:171], v[194:197], v[52:55]
	v_mfma_f32_16x16x32_bf16 v[48:51], v[182:185], v[194:197], v[48:51]
	v_mfma_f32_16x16x32_bf16 v[36:39], v[168:171], v[202:205], v[36:39]
	v_mfma_f32_16x16x32_bf16 v[32:35], v[182:185], v[202:205], v[32:35]
	v_mfma_f32_16x16x32_bf16 v[20:23], v[168:171], v[210:213], v[20:23]
	v_mfma_f32_16x16x32_bf16 v[16:19], v[182:185], v[210:213], v[16:19]
	v_mfma_f32_16x16x32_bf16 v[4:7], v[168:171], v[218:221], v[4:7]
	v_mfma_f32_16x16x32_bf16 v[0:3], v[182:185], v[218:221], v[0:3]
	s_add_i32 s62, 0, 0x18000
	s_add_i32 s63, 0, 0x1c000
	v_add_u32_e32 v140, s62, v172
	v_add_u32_e32 v177, s63, v172
	s_setprio 0
	s_barrier
	ds_read_b128 v[128:131], v140
	ds_read_b128 v[132:135], v140 offset:1024
	ds_read_b128 v[136:139], v140 offset:2048
	ds_read_b128 v[140:143], v140 offset:3072
	ds_read_b128 v[164:167], v177
	ds_read_b128 v[168:171], v177 offset:1024
	ds_read_b128 v[178:181], v177 offset:2048
	ds_read_b128 v[182:185], v177 offset:3072
	s_add_u32 s36, s36, 0x40000
	s_addc_u32 s37, s37, 0
	s_mov_b32 m0, s45
	ds_read_b128 v[190:193], v175 offset:32768
	ds_read_b128 v[194:197], v175 offset:33792
	ds_read_b128 v[198:201], v175 offset:34816
	ds_read_b128 v[202:205], v175 offset:35840
	ds_read_b128 v[206:209], v175 offset:36864
	ds_read_b128 v[210:213], v175 offset:37888
	ds_read_b128 v[214:217], v175 offset:38912
	ds_read_b128 v[218:221], v175 offset:39936
	global_load_lds_dwordx4 v144, s[36:37]
	s_mov_b32 m0, s46
	s_nop 0
	global_load_lds_dwordx4 v148, s[36:37]
	s_waitcnt vmcnt(8)
	s_waitcnt lgkmcnt(0)
	s_barrier
	s_setprio 1
	v_mfma_f32_16x16x32_bf16 v[124:127], v[128:131], v[190:193], v[124:127]
	v_mfma_f32_16x16x32_bf16 v[120:123], v[136:139], v[190:193], v[120:123]
	v_mfma_f32_16x16x32_bf16 v[108:111], v[128:131], v[198:201], v[108:111]
	v_mfma_f32_16x16x32_bf16 v[104:107], v[136:139], v[198:201], v[104:107]
	v_mfma_f32_16x16x32_bf16 v[92:95], v[128:131], v[206:209], v[92:95]
	v_mfma_f32_16x16x32_bf16 v[88:91], v[136:139], v[206:209], v[88:91]
	v_mfma_f32_16x16x32_bf16 v[76:79], v[128:131], v[214:217], v[76:79]
	v_mfma_f32_16x16x32_bf16 v[72:75], v[136:139], v[214:217], v[72:75]
	v_mfma_f32_16x16x32_bf16 v[124:127], v[132:135], v[194:197], v[124:127]
	v_mfma_f32_16x16x32_bf16 v[120:123], v[140:143], v[194:197], v[120:123]
	v_mfma_f32_16x16x32_bf16 v[108:111], v[132:135], v[202:205], v[108:111]
	v_mfma_f32_16x16x32_bf16 v[104:107], v[140:143], v[202:205], v[104:107]
	v_mfma_f32_16x16x32_bf16 v[92:95], v[132:135], v[210:213], v[92:95]
	v_mfma_f32_16x16x32_bf16 v[88:91], v[140:143], v[210:213], v[88:91]
	v_mfma_f32_16x16x32_bf16 v[76:79], v[132:135], v[218:221], v[76:79]
	v_mfma_f32_16x16x32_bf16 v[72:75], v[140:143], v[218:221], v[72:75]
	v_mfma_f32_16x16x32_bf16 v[116:119], v[164:167], v[190:193], v[116:119]
	v_mfma_f32_16x16x32_bf16 v[112:115], v[178:181], v[190:193], v[112:115]
	v_mfma_f32_16x16x32_bf16 v[100:103], v[164:167], v[198:201], v[100:103]
	v_mfma_f32_16x16x32_bf16 v[96:99], v[178:181], v[198:201], v[96:99]
	v_mfma_f32_16x16x32_bf16 v[84:87], v[164:167], v[206:209], v[84:87]
	v_mfma_f32_16x16x32_bf16 v[80:83], v[178:181], v[206:209], v[80:83]
	v_mfma_f32_16x16x32_bf16 v[68:71], v[164:167], v[214:217], v[68:71]
	v_mfma_f32_16x16x32_bf16 v[64:67], v[178:181], v[214:217], v[64:67]
	v_mfma_f32_16x16x32_bf16 v[116:119], v[168:171], v[194:197], v[116:119]
	v_mfma_f32_16x16x32_bf16 v[112:115], v[182:185], v[194:197], v[112:115]
	v_mfma_f32_16x16x32_bf16 v[100:103], v[168:171], v[202:205], v[100:103]
	v_mfma_f32_16x16x32_bf16 v[96:99], v[182:185], v[202:205], v[96:99]
	v_mfma_f32_16x16x32_bf16 v[84:87], v[168:171], v[210:213], v[84:87]
	v_mfma_f32_16x16x32_bf16 v[80:83], v[182:185], v[210:213], v[80:83]
	v_mfma_f32_16x16x32_bf16 v[68:71], v[168:171], v[218:221], v[68:71]
	v_mfma_f32_16x16x32_bf16 v[64:67], v[182:185], v[218:221], v[64:67]
	s_add_i32 s36, s62, s42
	v_lshl_add_u64 v[186:187], v[186:187], 0, s[16:17]
	s_setprio 0
	s_barrier
; #define PG8_STAGE(bufoff, gbase, voff) do { _Pragma("unroll") for (int _i = 0; _i < 2; ++_i) \
;         __builtin_amdgcn_global_load_lds((const unsigned*)((const char*)(gbase) + (voff)[_i]), (PG8_LAS unsigned*)(lds + (bufoff) + ldsw + _i * 8192), 16, 0, 0); } while (0)
; #define PG8_LDA(dst, b, h) do { _Pragma("unroll") for (int m = 0; m < 4; ++m) _Pragma("unroll") for (int k = 0; k < 2; ++k) dst[m][k] = *(const PG8_LAS bf16x8*)(lds + PG8_SA(b, h) + aoff + m * 2048 + k * 1024); } while (0)
; #define PG8_MMA(ai, bj, At, Bt) do { __builtin_amdgcn_s_setprio(1); _Pragma("unroll") for (int m = 0; m < 4; ++m) _Pragma("unroll") for (int n = 0; n < 2; ++n) _Pragma("unroll") for (int k = 0; k < 2; ++k) \
;         acc[ai][bj][m][n] = __builtin_amdgcn_mfma_f32_16x16x32_bf16(Bt[n][k], At[m][k], acc[ai][bj][m][n], 0, 0, 0); __builtin_amdgcn_s_setprio(0); } while (0)
; #define PG8_WAIT_V(n) asm volatile("s_waitcnt vmcnt(" #n ")" ::: "memory")
; #define PG8_WAIT_L(n) asm volatile("s_waitcnt lgkmcnt(" #n ")" ::: "memory")
; #define PG8_BAR __builtin_amdgcn_s_barrier()
; #define PG8_SCHED __builtin_amdgcn_sched_barrier(0)
; template <class Epi, class Sched, bool ALIGN_EPI = false, bool SP2 = false>
; __device__ __forceinline__ void gemm_phase(PG8_LAS unsigned char* lds, const Gemm g, const Sched& S, const Epi& E) {
;     ...
;         for (int t = 0; t < nt; t += 2) {
;             const bool last = (t == nt - 2);
;             const char* a1 = cA + (size_t)(t + 1) * kstep;
;             const char* a2 = last ? nA : cA + (size_t)(t + 2) * kstep; const char* b2 = last ? nB : cB + (size_t)(t + 2) * kstep;
;             const char* a3 = a2 + kstep; const char* b3 = b2 + kstep;
;     ...
;             PG8_LDA(At, 1, 1); PG8_STAGE(PG8_SB(1, 0), b3, voffB); PG8_STAGE(PG8_SB(1, 1), b3 + hstep, voffB); PG8_STAGE(PG8_SA(1, 0), a3, voffA);
;             PG8_WAIT_V(8); PG8_WAIT_L(0); PG8_BAR; PG8_MMA(1, 0, At, B0); PG8_MMA(1, 1, At, B1); PG8_BAR; PG8_SCHED;
	s_mov_b32 m0, s36
	ds_read_b128 v[190:193], v175 offset:49152
	ds_read_b128 v[194:197], v175 offset:50176
	ds_read_b128 v[198:201], v175 offset:51200
	ds_read_b128 v[202:205], v175 offset:52224
	ds_read_b128 v[206:209], v175 offset:53248
	ds_read_b128 v[210:213], v175 offset:54272
	ds_read_b128 v[214:217], v175 offset:55296
	ds_read_b128 v[218:221], v175 offset:56320
	global_load_lds_dwordx4 v[186:187], off
	s_add_i32 m0, s36, 0x2000
	s_add_u32 s34, s34, 0x40080
	v_lshl_add_u64 v[186:187], v[222:223], 0, s[16:17]
	s_addc_u32 s35, s35, 0
	s_add_i32 s36, s63, s42
	global_load_lds_dwordx4 v[186:187], off
	s_mov_b32 m0, s36
	s_nop 0
	global_load_lds_dwordx4 v146, s[34:35]
	s_add_i32 m0, s36, 0x2000
	s_nop 0
	global_load_lds_dwordx4 v150, s[34:35]
	v_lshl_add_u64 v[186:187], v[224:225], 0, s[16:17]
	s_mov_b32 m0, s48
	s_nop 0
	global_load_lds_dwordx4 v[186:187], off
	v_lshl_add_u64 v[186:187], v[226:227], 0, s[16:17]
	s_mov_b32 m0, s49
	s_nop 0
	global_load_lds_dwordx4 v[186:187], off
	s_waitcnt vmcnt(8)
	s_waitcnt lgkmcnt(0)
	s_barrier
	s_setprio 1
	v_mfma_f32_16x16x32_bf16 v[60:63], v[128:131], v[190:193], v[60:63]
	v_mfma_f32_16x16x32_bf16 v[56:59], v[136:139], v[190:193], v[56:59]
	v_mfma_f32_16x16x32_bf16 v[44:47], v[128:131], v[198:201], v[44:47]
	v_mfma_f32_16x16x32_bf16 v[40:43], v[136:139], v[198:201], v[40:43]
	v_mfma_f32_16x16x32_bf16 v[28:31], v[128:131], v[206:209], v[28:31]
	v_mfma_f32_16x16x32_bf16 v[24:27], v[136:139], v[206:209], v[24:27]
	v_mfma_f32_16x16x32_bf16 v[12:15], v[128:131], v[214:217], v[12:15]
	v_mfma_f32_16x16x32_bf16 v[8:11], v[136:139], v[214:217], v[8:11]
	v_mfma_f32_16x16x32_bf16 v[60:63], v[132:135], v[194:197], v[60:63]
	v_mfma_f32_16x16x32_bf16 v[56:59], v[140:143], v[194:197], v[56:59]
	v_mfma_f32_16x16x32_bf16 v[44:47], v[132:135], v[202:205], v[44:47]
	v_mfma_f32_16x16x32_bf16 v[40:43], v[140:143], v[202:205], v[40:43]
	v_mfma_f32_16x16x32_bf16 v[28:31], v[132:135], v[210:213], v[28:31]
	v_mfma_f32_16x16x32_bf16 v[24:27], v[140:143], v[210:213], v[24:27]
	v_mfma_f32_16x16x32_bf16 v[12:15], v[132:135], v[218:221], v[12:15]
	v_mfma_f32_16x16x32_bf16 v[8:11], v[140:143], v[218:221], v[8:11]
	v_mfma_f32_16x16x32_bf16 v[52:55], v[164:167], v[190:193], v[52:55]
	v_mfma_f32_16x16x32_bf16 v[48:51], v[178:181], v[190:193], v[48:51]
	v_mfma_f32_16x16x32_bf16 v[36:39], v[164:167], v[198:201], v[36:39]
	v_mfma_f32_16x16x32_bf16 v[32:35], v[178:181], v[198:201], v[32:35]
	v_mfma_f32_16x16x32_bf16 v[20:23], v[164:167], v[206:209], v[20:23]
	v_mfma_f32_16x16x32_bf16 v[16:19], v[178:181], v[206:209], v[16:19]
	v_mfma_f32_16x16x32_bf16 v[4:7], v[164:167], v[214:217], v[4:7]
	v_mfma_f32_16x16x32_bf16 v[0:3], v[178:181], v[214:217], v[0:3]
	v_mfma_f32_16x16x32_bf16 v[52:55], v[168:171], v[194:197], v[52:55]
	v_mfma_f32_16x16x32_bf16 v[48:51], v[182:185], v[194:197], v[48:51]
	v_mfma_f32_16x16x32_bf16 v[36:39], v[168:171], v[202:205], v[36:39]
	v_mfma_f32_16x16x32_bf16 v[32:35], v[182:185], v[202:205], v[32:35]
	v_mfma_f32_16x16x32_bf16 v[20:23], v[168:171], v[210:213], v[20:23]
	v_mfma_f32_16x16x32_bf16 v[16:19], v[182:185], v[210:213], v[16:19]
	v_mfma_f32_16x16x32_bf16 v[4:7], v[168:171], v[218:221], v[4:7]
	v_mfma_f32_16x16x32_bf16 v[0:3], v[182:185], v[218:221], v[0:3]
	s_add_i32 s61, s61, 2
	s_add_u32 s30, s30, 0x100
	s_addc_u32 s31, s31, 0
	s_add_u32 s59, s59, 0x100
	s_addc_u32 s60, s60, 0
	s_cmp_gt_u32 s61, 13
	s_setprio 0
	s_barrier
	s_cbranch_scc0 .LBB0_882
	s_and_b64 vcc, exec, s[18:19]
	s_cbranch_vccz .LBB0_885
	s_barrier

; #define PG8_STAGE(bufoff, gbase, voff) do { _Pragma("unroll") for (int _i = 0; _i < 2; ++_i) \
;         __builtin_amdgcn_global_load_lds((const unsigned*)((const char*)(gbase) + (voff)[_i]), (PG8_LAS unsigned*)(lds + (bufoff) + ldsw + _i * 8192), 16, 0, 0); } while (0)
; #define PG8_LDA(dst, b, h) do { _Pragma("unroll") for (int m = 0; m < 4; ++m) _Pragma("unroll") for (int k = 0; k < 2; ++k) dst[m][k] = *(const PG8_LAS bf16x8*)(lds + PG8_SA(b, h) + aoff + m * 2048 + k * 1024); } while (0)
; #define PG8_LDB(dst, b, h) do { _Pragma("unroll") for (int n = 0; n < 2; ++n) _Pragma("unroll") for (int k = 0; k < 2; ++k) dst[n][k] = *(const PG8_LAS bf16x8*)(lds + PG8_SB(b, h) + boff + n * 2048 + k * 1024); } while (0)
; #define PG8_MMA(ai, bj, At, Bt) do { __builtin_amdgcn_s_setprio(1); _Pragma("unroll") for (int m = 0; m < 4; ++m) _Pragma("unroll") for (int n = 0; n < 2; ++n) _Pragma("unroll") for (int k = 0; k < 2; ++k) \
;         acc[ai][bj][m][n] = __builtin_amdgcn_mfma_f32_16x16x32_bf16(Bt[n][k], At[m][k], acc[ai][bj][m][n], 0, 0, 0); __builtin_amdgcn_s_setprio(0); } while (0)
; #define PG8_WAIT_V(n) asm volatile("s_waitcnt vmcnt(" #n ")" ::: "memory")
; #define PG8_BAR __builtin_amdgcn_s_barrier()
; template <class Epi, class Sched, bool ALIGN_EPI = false, bool SP2 = false>
; __device__ __forceinline__ void gemm_phase(PG8_LAS unsigned char* lds, const Gemm g, const Sched& S, const Epi& E) {
;     ...
;         for (int t = 0; t < nt; t += 2) {
;             const bool last = (t == nt - 2);
;             const char* a1 = cA + (size_t)(t + 1) * kstep;
;             const char* a2 = last ? nA : cA + (size_t)(t + 2) * kstep; const char* b2 = last ? nB : cB + (size_t)(t + 2) * kstep;
;             const char* a3 = a2 + kstep; const char* b3 = b2 + kstep;
;             if (last && has_next) S.a_ready(nxt);
;             if constexpr (SP2) {
;             PG8_LDB(B0, 0, 0); PG8_LDB(B1, 0, 1); PG8_SCHED; PG8_LDA(At, 0, 0); PG8_STAGE(PG8_SA(1, 1), a1 + hstep, voffA);
;             PG8_WAIT_V(8); PG8_WAIT_L(0); PG8_BAR; PG8_MMA(0, 0, At, B0); PG8_MMA(0, 1, At, B1); PG8_BAR; PG8_SCHED;
;             PG8_LDA(At, 0, 1); PG8_STAGE(PG8_SB(0, 0), b2, voffB); PG8_STAGE(PG8_SB(0, 1), b2 + hstep, voffB); PG8_STAGE(PG8_SA(0, 0), a2, voffA);
;             PG8_WAIT_V(8); PG8_WAIT_L(0); PG8_BAR; PG8_MMA(1, 0, At, B0); PG8_MMA(1, 1, At, B1); PG8_BAR; PG8_SCHED;
.LBB0_969:
	ds_read_b128 v[128:131], v191
	ds_read_b128 v[132:135], v191 offset:1024
	ds_read_b128 v[136:139], v191 offset:2048
	ds_read_b128 v[140:143], v191 offset:3072
	ds_read_b128 v[144:147], v192
	ds_read_b128 v[148:151], v192 offset:1024
	ds_read_b128 v[172:175], v192 offset:2048
	ds_read_b128 v[176:179], v192 offset:3072
	s_add_u32 s26, s24, 0xfffc0080
	s_addc_u32 s27, s25, -1
	s_cmp_eq_u32 s57, 12
	s_cselect_b32 s29, s17, s27
	s_cselect_b32 s28, s51, s26
	s_cselect_b32 s27, s15, s56
	s_cselect_b32 s26, s54, s55
	s_add_i32 m0, s39, 0xc000
	ds_read_b128 v[180:183], v193
	ds_read_b128 v[184:187], v193 offset:1024
	ds_read_b128 v[196:199], v193 offset:2048
	ds_read_b128 v[200:203], v193 offset:3072
	ds_read_b128 v[204:207], v193 offset:4096
	ds_read_b128 v[208:211], v193 offset:5120
	ds_read_b128 v[212:215], v193 offset:6144
	ds_read_b128 v[216:219], v193 offset:7168
	global_load_lds_dwordx4 v164, s[24:25]
	s_add_i32 m0, s39, 0xe000
	s_nop 0
	global_load_lds_dwordx4 v166, s[24:25]
	s_waitcnt vmcnt(8)
	s_waitcnt lgkmcnt(0)
	s_barrier
	s_setprio 1
	v_mfma_f32_16x16x32_bf16 v[124:127], v[128:131], v[180:183], v[124:127]
	v_mfma_f32_16x16x32_bf16 v[120:123], v[136:139], v[180:183], v[120:123]
	v_mfma_f32_16x16x32_bf16 v[108:111], v[128:131], v[196:199], v[108:111]
	v_mfma_f32_16x16x32_bf16 v[104:107], v[136:139], v[196:199], v[104:107]
	v_mfma_f32_16x16x32_bf16 v[92:95], v[128:131], v[204:207], v[92:95]
	v_mfma_f32_16x16x32_bf16 v[84:87], v[136:139], v[204:207], v[84:87]
	v_mfma_f32_16x16x32_bf16 v[76:79], v[128:131], v[212:215], v[76:79]
	v_mfma_f32_16x16x32_bf16 v[72:75], v[136:139], v[212:215], v[72:75]
	v_mfma_f32_16x16x32_bf16 v[124:127], v[132:135], v[184:187], v[124:127]
	v_mfma_f32_16x16x32_bf16 v[120:123], v[140:143], v[184:187], v[120:123]
	v_mfma_f32_16x16x32_bf16 v[108:111], v[132:135], v[200:203], v[108:111]
	v_mfma_f32_16x16x32_bf16 v[104:107], v[140:143], v[200:203], v[104:107]
	v_mfma_f32_16x16x32_bf16 v[92:95], v[132:135], v[208:211], v[92:95]
	v_mfma_f32_16x16x32_bf16 v[84:87], v[140:143], v[208:211], v[84:87]
	v_mfma_f32_16x16x32_bf16 v[76:79], v[132:135], v[216:219], v[76:79]
	v_mfma_f32_16x16x32_bf16 v[72:75], v[140:143], v[216:219], v[72:75]
	v_mfma_f32_16x16x32_bf16 v[116:119], v[144:147], v[180:183], v[116:119]
	v_mfma_f32_16x16x32_bf16 v[112:115], v[172:175], v[180:183], v[112:115]
	v_mfma_f32_16x16x32_bf16 v[100:103], v[144:147], v[196:199], v[100:103]
	v_mfma_f32_16x16x32_bf16 v[96:99], v[172:175], v[196:199], v[96:99]
	v_mfma_f32_16x16x32_bf16 v[88:91], v[144:147], v[204:207], v[88:91]
	v_mfma_f32_16x16x32_bf16 v[80:83], v[172:175], v[204:207], v[80:83]
	v_mfma_f32_16x16x32_bf16 v[68:71], v[144:147], v[212:215], v[68:71]
	v_mfma_f32_16x16x32_bf16 v[64:67], v[172:175], v[212:215], v[64:67]
	v_mfma_f32_16x16x32_bf16 v[116:119], v[148:151], v[184:187], v[116:119]
	v_mfma_f32_16x16x32_bf16 v[112:115], v[176:179], v[184:187], v[112:115]
	v_mfma_f32_16x16x32_bf16 v[100:103], v[148:151], v[200:203], v[100:103]
	v_mfma_f32_16x16x32_bf16 v[96:99], v[176:179], v[200:203], v[96:99]
	v_mfma_f32_16x16x32_bf16 v[88:91], v[148:151], v[208:211], v[88:91]
	v_mfma_f32_16x16x32_bf16 v[80:83], v[176:179], v[208:211], v[80:83]
	v_mfma_f32_16x16x32_bf16 v[68:71], v[148:151], v[216:219], v[68:71]
	v_mfma_f32_16x16x32_bf16 v[64:67], v[176:179], v[216:219], v[64:67]
	s_add_i32 s58, s47, s36
	v_lshl_add_u64 v[220:221], s[26:27], 0, v[156:157]
	s_setprio 0
	s_barrier
	s_mov_b32 m0, s58
	ds_read_b128 v[180:183], v193 offset:16384
	ds_read_b128 v[184:187], v193 offset:17408
	ds_read_b128 v[196:199], v193 offset:18432
	ds_read_b128 v[200:203], v193 offset:19456
	ds_read_b128 v[204:207], v193 offset:20480
	ds_read_b128 v[208:211], v193 offset:21504
	ds_read_b128 v[212:215], v193 offset:22528
	ds_read_b128 v[216:219], v193 offset:23552
	global_load_lds_dwordx4 v[220:221], off
	s_add_i32 m0, s58, 0x2000
	s_add_u32 s58, s26, 0x40000
	v_lshl_add_u64 v[222:223], s[26:27], 0, v[152:153]
	s_addc_u32 s59, s27, 0
	s_add_i32 s60, s48, s36
	global_load_lds_dwordx4 v[222:223], off
	s_mov_b32 m0, s60
	v_lshl_add_u64 v[226:227], s[28:29], 0, v[154:155]
	global_load_lds_dwordx4 v156, s[58:59]
	s_add_i32 m0, s60, 0x2000
	s_nop 0
	global_load_lds_dwordx4 v152, s[58:59]
	v_lshl_add_u64 v[224:225], s[28:29], 0, v[158:159]
	s_mov_b32 m0, s39
	s_nop 0
	global_load_lds_dwordx4 v[224:225], off
	s_mov_b32 m0, s40
	s_nop 0
	global_load_lds_dwordx4 v[226:227], off
	s_waitcnt vmcnt(8)
	s_waitcnt lgkmcnt(0)
	s_barrier
; #define PG8_STAGE(bufoff, gbase, voff) do { _Pragma("unroll") for (int _i = 0; _i < 2; ++_i) \
;         __builtin_amdgcn_global_load_lds((const unsigned*)((const char*)(gbase) + (voff)[_i]), (PG8_LAS unsigned*)(lds + (bufoff) + ldsw + _i * 8192), 16, 0, 0); } while (0)
; #define PG8_LDA(dst, b, h) do { _Pragma("unroll") for (int m = 0; m < 4; ++m) _Pragma("unroll") for (int k = 0; k < 2; ++k) dst[m][k] = *(const PG8_LAS bf16x8*)(lds + PG8_SA(b, h) + aoff + m * 2048 + k * 1024); } while (0)
; #define PG8_LDB(dst, b, h) do { _Pragma("unroll") for (int n = 0; n < 2; ++n) _Pragma("unroll") for (int k = 0; k < 2; ++k) dst[n][k] = *(const PG8_LAS bf16x8*)(lds + PG8_SB(b, h) + boff + n * 2048 + k * 1024); } while (0)
; #define PG8_MMA(ai, bj, At, Bt) do { __builtin_amdgcn_s_setprio(1); _Pragma("unroll") for (int m = 0; m < 4; ++m) _Pragma("unroll") for (int n = 0; n < 2; ++n) _Pragma("unroll") for (int k = 0; k < 2; ++k) \
;         acc[ai][bj][m][n] = __builtin_amdgcn_mfma_f32_16x16x32_bf16(Bt[n][k], At[m][k], acc[ai][bj][m][n], 0, 0, 0); __builtin_amdgcn_s_setprio(0); } while (0)
; #define PG8_WAIT_V(n) asm volatile("s_waitcnt vmcnt(" #n ")" ::: "memory")
; #define PG8_WAIT_L(n) asm volatile("s_waitcnt lgkmcnt(" #n ")" ::: "memory")
; #define PG8_BAR __builtin_amdgcn_s_barrier()
; #define PG8_SCHED __builtin_amdgcn_sched_barrier(0)
; template <class Epi, class Sched, bool ALIGN_EPI = false, bool SP2 = false>
; __device__ __forceinline__ void gemm_phase(PG8_LAS unsigned char* lds, const Gemm g, const Sched& S, const Epi& E) {
;     ...
;             PG8_LDA(At, 0, 1); PG8_STAGE(PG8_SB(0, 0), b2, voffB); PG8_STAGE(PG8_SB(0, 1), b2 + hstep, voffB); PG8_STAGE(PG8_SA(0, 0), a2, voffA);
;             PG8_WAIT_V(8); PG8_WAIT_L(0); PG8_BAR; PG8_MMA(1, 0, At, B0); PG8_MMA(1, 1, At, B1); PG8_BAR; PG8_SCHED;
;             PG8_LDB(B0, 1, 0); PG8_LDB(B1, 1, 1); PG8_SCHED; PG8_LDA(At, 1, 0); PG8_STAGE(PG8_SA(0, 1), a2 + hstep, voffA);
;             PG8_WAIT_V(8); PG8_WAIT_L(0); PG8_BAR; PG8_MMA(0, 0, At, B0); PG8_MMA(0, 1, At, B1); PG8_BAR; PG8_SCHED;
;             PG8_LDA(At, 1, 1); PG8_STAGE(PG8_SB(1, 0), b3, voffB); PG8_STAGE(PG8_SB(1, 1), b3 + hstep, voffB); PG8_STAGE(PG8_SA(1, 0), a3, voffA);
;             PG8_WAIT_V(8); PG8_WAIT_L(0); PG8_BAR; PG8_MMA(1, 0, At, B0); PG8_MMA(1, 1, At, B1); PG8_BAR; PG8_SCHED;
	s_setprio 1
	v_mfma_f32_16x16x32_bf16 v[60:63], v[128:131], v[180:183], v[60:63]
	v_mfma_f32_16x16x32_bf16 v[52:55], v[136:139], v[180:183], v[52:55]
	v_mfma_f32_16x16x32_bf16 v[44:47], v[128:131], v[196:199], v[44:47]
	v_mfma_f32_16x16x32_bf16 v[40:43], v[136:139], v[196:199], v[40:43]
	v_mfma_f32_16x16x32_bf16 v[28:31], v[128:131], v[204:207], v[28:31]
	v_mfma_f32_16x16x32_bf16 v[20:23], v[136:139], v[204:207], v[20:23]
	v_mfma_f32_16x16x32_bf16 v[12:15], v[128:131], v[212:215], v[12:15]
	v_mfma_f32_16x16x32_bf16 v[8:11], v[136:139], v[212:215], v[8:11]
	v_mfma_f32_16x16x32_bf16 v[60:63], v[132:135], v[184:187], v[60:63]
	v_mfma_f32_16x16x32_bf16 v[52:55], v[140:143], v[184:187], v[52:55]
	v_mfma_f32_16x16x32_bf16 v[44:47], v[132:135], v[200:203], v[44:47]
	v_mfma_f32_16x16x32_bf16 v[40:43], v[140:143], v[200:203], v[40:43]
	v_mfma_f32_16x16x32_bf16 v[28:31], v[132:135], v[208:211], v[28:31]
	v_mfma_f32_16x16x32_bf16 v[20:23], v[140:143], v[208:211], v[20:23]
	v_mfma_f32_16x16x32_bf16 v[12:15], v[132:135], v[216:219], v[12:15]
	v_mfma_f32_16x16x32_bf16 v[8:11], v[140:143], v[216:219], v[8:11]
	v_mfma_f32_16x16x32_bf16 v[56:59], v[144:147], v[180:183], v[56:59]
	v_mfma_f32_16x16x32_bf16 v[48:51], v[172:175], v[180:183], v[48:51]
	v_mfma_f32_16x16x32_bf16 v[36:39], v[144:147], v[196:199], v[36:39]
	v_mfma_f32_16x16x32_bf16 v[32:35], v[172:175], v[196:199], v[32:35]
	v_mfma_f32_16x16x32_bf16 v[24:27], v[144:147], v[204:207], v[24:27]
	v_mfma_f32_16x16x32_bf16 v[16:19], v[172:175], v[204:207], v[16:19]
	v_mfma_f32_16x16x32_bf16 v[4:7], v[144:147], v[212:215], v[4:7]
	v_mfma_f32_16x16x32_bf16 v[0:3], v[172:175], v[212:215], v[0:3]
	v_mfma_f32_16x16x32_bf16 v[56:59], v[148:151], v[184:187], v[56:59]
	v_mfma_f32_16x16x32_bf16 v[48:51], v[176:179], v[184:187], v[48:51]
	v_mfma_f32_16x16x32_bf16 v[36:39], v[148:151], v[200:203], v[36:39]
	v_mfma_f32_16x16x32_bf16 v[32:35], v[176:179], v[200:203], v[32:35]
	v_mfma_f32_16x16x32_bf16 v[24:27], v[148:151], v[208:211], v[24:27]
	v_mfma_f32_16x16x32_bf16 v[16:19], v[176:179], v[208:211], v[16:19]
	v_mfma_f32_16x16x32_bf16 v[4:7], v[148:151], v[216:219], v[4:7]
	v_mfma_f32_16x16x32_bf16 v[0:3], v[176:179], v[216:219], v[0:3]
	s_add_i32 s58, 0, 0x18000
	s_add_i32 s59, 0, 0x1c000
	v_add_u32_e32 v140, s58, v190
	v_add_u32_e32 v176, s59, v190
	s_setprio 0
	s_barrier
	ds_read_b128 v[128:131], v140
	ds_read_b128 v[132:135], v140 offset:1024
	ds_read_b128 v[136:139], v140 offset:2048
	ds_read_b128 v[140:143], v140 offset:3072
	ds_read_b128 v[144:147], v176
	ds_read_b128 v[148:151], v176 offset:1024
	ds_read_b128 v[172:175], v176 offset:2048
	ds_read_b128 v[176:179], v176 offset:3072
	s_add_u32 s28, s28, 0x40000
	s_addc_u32 s29, s29, 0
	s_mov_b32 m0, s41
	ds_read_b128 v[180:183], v193 offset:32768
	ds_read_b128 v[184:187], v193 offset:33792
	ds_read_b128 v[196:199], v193 offset:34816
	ds_read_b128 v[200:203], v193 offset:35840
	ds_read_b128 v[204:207], v193 offset:36864
	ds_read_b128 v[208:211], v193 offset:37888
	ds_read_b128 v[212:215], v193 offset:38912
	ds_read_b128 v[216:219], v193 offset:39936
	global_load_lds_dwordx4 v158, s[28:29]
	s_mov_b32 m0, s42
	s_nop 0
	global_load_lds_dwordx4 v154, s[28:29]
	s_waitcnt vmcnt(8)
	s_waitcnt lgkmcnt(0)
	s_barrier
	s_setprio 1
	v_mfma_f32_16x16x32_bf16 v[124:127], v[128:131], v[180:183], v[124:127]
	v_mfma_f32_16x16x32_bf16 v[120:123], v[136:139], v[180:183], v[120:123]
	v_mfma_f32_16x16x32_bf16 v[108:111], v[128:131], v[196:199], v[108:111]
	v_mfma_f32_16x16x32_bf16 v[104:107], v[136:139], v[196:199], v[104:107]
	v_mfma_f32_16x16x32_bf16 v[92:95], v[128:131], v[204:207], v[92:95]
	v_mfma_f32_16x16x32_bf16 v[84:87], v[136:139], v[204:207], v[84:87]
	v_mfma_f32_16x16x32_bf16 v[76:79], v[128:131], v[212:215], v[76:79]
	v_mfma_f32_16x16x32_bf16 v[72:75], v[136:139], v[212:215], v[72:75]
	v_mfma_f32_16x16x32_bf16 v[124:127], v[132:135], v[184:187], v[124:127]
	v_mfma_f32_16x16x32_bf16 v[120:123], v[140:143], v[184:187], v[120:123]
	v_mfma_f32_16x16x32_bf16 v[108:111], v[132:135], v[200:203], v[108:111]
	v_mfma_f32_16x16x32_bf16 v[104:107], v[140:143], v[200:203], v[104:107]
	v_mfma_f32_16x16x32_bf16 v[92:95], v[132:135], v[208:211], v[92:95]
	v_mfma_f32_16x16x32_bf16 v[84:87], v[140:143], v[208:211], v[84:87]
	v_mfma_f32_16x16x32_bf16 v[76:79], v[132:135], v[216:219], v[76:79]
	v_mfma_f32_16x16x32_bf16 v[72:75], v[140:143], v[216:219], v[72:75]
	v_mfma_f32_16x16x32_bf16 v[116:119], v[144:147], v[180:183], v[116:119]
	v_mfma_f32_16x16x32_bf16 v[112:115], v[172:175], v[180:183], v[112:115]
	v_mfma_f32_16x16x32_bf16 v[100:103], v[144:147], v[196:199], v[100:103]
	v_mfma_f32_16x16x32_bf16 v[96:99], v[172:175], v[196:199], v[96:99]
	v_mfma_f32_16x16x32_bf16 v[88:91], v[144:147], v[204:207], v[88:91]
	v_mfma_f32_16x16x32_bf16 v[80:83], v[172:175], v[204:207], v[80:83]
	v_mfma_f32_16x16x32_bf16 v[68:71], v[144:147], v[212:215], v[68:71]
	v_mfma_f32_16x16x32_bf16 v[64:67], v[172:175], v[212:215], v[64:67]
	v_mfma_f32_16x16x32_bf16 v[116:119], v[148:151], v[184:187], v[116:119]
	v_mfma_f32_16x16x32_bf16 v[112:115], v[176:179], v[184:187], v[112:115]
	v_mfma_f32_16x16x32_bf16 v[100:103], v[148:151], v[200:203], v[100:103]
	v_mfma_f32_16x16x32_bf16 v[96:99], v[176:179], v[200:203], v[96:99]
	v_mfma_f32_16x16x32_bf16 v[88:91], v[148:151], v[208:211], v[88:91]
	v_mfma_f32_16x16x32_bf16 v[80:83], v[176:179], v[208:211], v[80:83]
	v_mfma_f32_16x16x32_bf16 v[68:71], v[148:151], v[216:219], v[68:71]
	v_mfma_f32_16x16x32_bf16 v[64:67], v[176:179], v[216:219], v[64:67]
	s_add_i32 s28, s58, s36
	v_lshl_add_u64 v[220:221], v[220:221], 0, s[10:11]
	s_setprio 0
	s_barrier
; #define PG8_STAGE(bufoff, gbase, voff) do { _Pragma("unroll") for (int _i = 0; _i < 2; ++_i) \
;         __builtin_amdgcn_global_load_lds((const unsigned*)((const char*)(gbase) + (voff)[_i]), (PG8_LAS unsigned*)(lds + (bufoff) + ldsw + _i * 8192), 16, 0, 0); } while (0)
; #define PG8_LDA(dst, b, h) do { _Pragma("unroll") for (int m = 0; m < 4; ++m) _Pragma("unroll") for (int k = 0; k < 2; ++k) dst[m][k] = *(const PG8_LAS bf16x8*)(lds + PG8_SA(b, h) + aoff + m * 2048 + k * 1024); } while (0)
; #define PG8_MMA(ai, bj, At, Bt) do { __builtin_amdgcn_s_setprio(1); _Pragma("unroll") for (int m = 0; m < 4; ++m) _Pragma("unroll") for (int n = 0; n < 2; ++n) _Pragma("unroll") for (int k = 0; k < 2; ++k) \
;         acc[ai][bj][m][n] = __builtin_amdgcn_mfma_f32_16x16x32_bf16(Bt[n][k], At[m][k], acc[ai][bj][m][n], 0, 0, 0); __builtin_amdgcn_s_setprio(0); } while (0)
; #define PG8_WAIT_V(n) asm volatile("s_waitcnt vmcnt(" #n ")" ::: "memory")
; #define PG8_WAIT_L(n) asm volatile("s_waitcnt lgkmcnt(" #n ")" ::: "memory")
; #define PG8_BAR __builtin_amdgcn_s_barrier()
; #define PG8_SCHED __builtin_amdgcn_sched_barrier(0)
; template <class Epi, class Sched, bool ALIGN_EPI = false, bool SP2 = false>
; __device__ __forceinline__ void gemm_phase(PG8_LAS unsigned char* lds, const Gemm g, const Sched& S, const Epi& E) {
;     ...
;         for (int t = 0; t < nt; t += 2) {
;             const bool last = (t == nt - 2);
;             const char* a1 = cA + (size_t)(t + 1) * kstep;
;             const char* a2 = last ? nA : cA + (size_t)(t + 2) * kstep; const char* b2 = last ? nB : cB + (size_t)(t + 2) * kstep;
;             const char* a3 = a2 + kstep; const char* b3 = b2 + kstep;
;     ...
;             PG8_LDA(At, 1, 1); PG8_STAGE(PG8_SB(1, 0), b3, voffB); PG8_STAGE(PG8_SB(1, 1), b3 + hstep, voffB); PG8_STAGE(PG8_SA(1, 0), a3, voffA);
;             PG8_WAIT_V(8); PG8_WAIT_L(0); PG8_BAR; PG8_MMA(1, 0, At, B0); PG8_MMA(1, 1, At, B1); PG8_BAR; PG8_SCHED;
	s_mov_b32 m0, s28
	ds_read_b128 v[180:183], v193 offset:49152
	ds_read_b128 v[184:187], v193 offset:50176
	ds_read_b128 v[196:199], v193 offset:51200
	ds_read_b128 v[200:203], v193 offset:52224
	ds_read_b128 v[204:207], v193 offset:53248
	ds_read_b128 v[208:211], v193 offset:54272
	ds_read_b128 v[212:215], v193 offset:55296
	ds_read_b128 v[216:219], v193 offset:56320
	global_load_lds_dwordx4 v[220:221], off
	s_add_i32 m0, s28, 0x2000
	s_add_u32 s26, s26, 0x40080
	v_lshl_add_u64 v[220:221], v[222:223], 0, s[10:11]
	s_addc_u32 s27, s27, 0
	s_add_i32 s28, s59, s36
	global_load_lds_dwordx4 v[220:221], off
	s_mov_b32 m0, s28
	s_nop 0
	global_load_lds_dwordx4 v156, s[26:27]
	s_add_i32 m0, s28, 0x2000
	s_nop 0
	global_load_lds_dwordx4 v152, s[26:27]
	v_lshl_add_u64 v[220:221], v[224:225], 0, s[10:11]
	s_mov_b32 m0, s43
	s_nop 0
	global_load_lds_dwordx4 v[220:221], off
	v_lshl_add_u64 v[220:221], v[226:227], 0, s[10:11]
	s_mov_b32 m0, s44
	s_nop 0
	global_load_lds_dwordx4 v[220:221], off
	s_waitcnt vmcnt(8)
	s_waitcnt lgkmcnt(0)
	s_barrier
	s_setprio 1
	v_mfma_f32_16x16x32_bf16 v[60:63], v[128:131], v[180:183], v[60:63]
	v_mfma_f32_16x16x32_bf16 v[52:55], v[136:139], v[180:183], v[52:55]
	v_mfma_f32_16x16x32_bf16 v[44:47], v[128:131], v[196:199], v[44:47]
	v_mfma_f32_16x16x32_bf16 v[40:43], v[136:139], v[196:199], v[40:43]
	v_mfma_f32_16x16x32_bf16 v[28:31], v[128:131], v[204:207], v[28:31]
	v_mfma_f32_16x16x32_bf16 v[20:23], v[136:139], v[204:207], v[20:23]
	v_mfma_f32_16x16x32_bf16 v[12:15], v[128:131], v[212:215], v[12:15]
	v_mfma_f32_16x16x32_bf16 v[8:11], v[136:139], v[212:215], v[8:11]
	v_mfma_f32_16x16x32_bf16 v[60:63], v[132:135], v[184:187], v[60:63]
	v_mfma_f32_16x16x32_bf16 v[52:55], v[140:143], v[184:187], v[52:55]
	v_mfma_f32_16x16x32_bf16 v[44:47], v[132:135], v[200:203], v[44:47]
	v_mfma_f32_16x16x32_bf16 v[40:43], v[140:143], v[200:203], v[40:43]
	v_mfma_f32_16x16x32_bf16 v[28:31], v[132:135], v[208:211], v[28:31]
	v_mfma_f32_16x16x32_bf16 v[20:23], v[140:143], v[208:211], v[20:23]
	v_mfma_f32_16x16x32_bf16 v[12:15], v[132:135], v[216:219], v[12:15]
	v_mfma_f32_16x16x32_bf16 v[8:11], v[140:143], v[216:219], v[8:11]
	v_mfma_f32_16x16x32_bf16 v[56:59], v[144:147], v[180:183], v[56:59]
	v_mfma_f32_16x16x32_bf16 v[48:51], v[172:175], v[180:183], v[48:51]
	v_mfma_f32_16x16x32_bf16 v[36:39], v[144:147], v[196:199], v[36:39]
	v_mfma_f32_16x16x32_bf16 v[32:35], v[172:175], v[196:199], v[32:35]
	v_mfma_f32_16x16x32_bf16 v[24:27], v[144:147], v[204:207], v[24:27]
	v_mfma_f32_16x16x32_bf16 v[16:19], v[172:175], v[204:207], v[16:19]
	v_mfma_f32_16x16x32_bf16 v[4:7], v[144:147], v[212:215], v[4:7]
	v_mfma_f32_16x16x32_bf16 v[0:3], v[172:175], v[212:215], v[0:3]
	v_mfma_f32_16x16x32_bf16 v[56:59], v[148:151], v[184:187], v[56:59]
	v_mfma_f32_16x16x32_bf16 v[48:51], v[176:179], v[184:187], v[48:51]
	v_mfma_f32_16x16x32_bf16 v[36:39], v[148:151], v[200:203], v[36:39]
	v_mfma_f32_16x16x32_bf16 v[32:35], v[176:179], v[200:203], v[32:35]
	v_mfma_f32_16x16x32_bf16 v[24:27], v[148:151], v[208:211], v[24:27]
	v_mfma_f32_16x16x32_bf16 v[16:19], v[176:179], v[208:211], v[16:19]
	v_mfma_f32_16x16x32_bf16 v[4:7], v[148:151], v[216:219], v[4:7]
	v_mfma_f32_16x16x32_bf16 v[0:3], v[176:179], v[216:219], v[0:3]
	s_add_i32 s57, s57, 2
	s_add_u32 s24, s24, 0x100
	s_addc_u32 s25, s25, 0
	s_add_u32 s55, s55, 0x100
	s_addc_u32 s56, s56, 0
	s_cmp_gt_u32 s57, 13
	s_setprio 0
	s_barrier
	s_cbranch_scc0 .LBB0_969
	s_and_b64 vcc, exec, s[12:13]
	s_cbranch_vccz .LBB0_972
	s_barrier

; #define PG8_STAGE(bufoff, gbase, voff) do { _Pragma("unroll") for (int _i = 0; _i < 2; ++_i) \
;         __builtin_amdgcn_global_load_lds((const unsigned*)((const char*)(gbase) + (voff)[_i]), (PG8_LAS unsigned*)(lds + (bufoff) + ldsw + _i * 8192), 16, 0, 0); } while (0)
; #define PG8_LDA(dst, b, h) do { _Pragma("unroll") for (int m = 0; m < 4; ++m) _Pragma("unroll") for (int k = 0; k < 2; ++k) dst[m][k] = *(const PG8_LAS bf16x8*)(lds + PG8_SA(b, h) + aoff + m * 2048 + k * 1024); } while (0)
; #define PG8_LDB(dst, b, h) do { _Pragma("unroll") for (int n = 0; n < 2; ++n) _Pragma("unroll") for (int k = 0; k < 2; ++k) dst[n][k] = *(const PG8_LAS bf16x8*)(lds + PG8_SB(b, h) + boff + n * 2048 + k * 1024); } while (0)
; #define PG8_MMA(ai, bj, At, Bt) do { __builtin_amdgcn_s_setprio(1); _Pragma("unroll") for (int m = 0; m < 4; ++m) _Pragma("unroll") for (int n = 0; n < 2; ++n) _Pragma("unroll") for (int k = 0; k < 2; ++k) \
;         acc[ai][bj][m][n] = __builtin_amdgcn_mfma_f32_16x16x32_bf16(Bt[n][k], At[m][k], acc[ai][bj][m][n], 0, 0, 0); __builtin_amdgcn_s_setprio(0); } while (0)
; #define PG8_WAIT_V(n) asm volatile("s_waitcnt vmcnt(" #n ")" ::: "memory")
; #define PG8_BAR __builtin_amdgcn_s_barrier()
; template <class Epi, class Sched, bool ALIGN_EPI = false, bool SP2 = false>
; __device__ __forceinline__ void gemm_phase(PG8_LAS unsigned char* lds, const Gemm g, const Sched& S, const Epi& E) {
;     ...
;         for (int t = 0; t < nt; t += 2) {
;             const bool last = (t == nt - 2);
;             const char* a1 = cA + (size_t)(t + 1) * kstep;
;             const char* a2 = last ? nA : cA + (size_t)(t + 2) * kstep; const char* b2 = last ? nB : cB + (size_t)(t + 2) * kstep;
;             const char* a3 = a2 + kstep; const char* b3 = b2 + kstep;
;             if (last && has_next) S.a_ready(nxt);
;             if constexpr (SP2) {
;             PG8_LDB(B0, 0, 0); PG8_LDB(B1, 0, 1); PG8_SCHED; PG8_LDA(At, 0, 0); PG8_STAGE(PG8_SA(1, 1), a1 + hstep, voffA);
;             PG8_WAIT_V(8); PG8_WAIT_L(0); PG8_BAR; PG8_MMA(0, 0, At, B0); PG8_MMA(0, 1, At, B1); PG8_BAR; PG8_SCHED;
;             PG8_LDA(At, 0, 1); PG8_STAGE(PG8_SB(0, 0), b2, voffB); PG8_STAGE(PG8_SB(0, 1), b2 + hstep, voffB); PG8_STAGE(PG8_SA(0, 0), a2, voffA);
;             PG8_WAIT_V(8); PG8_WAIT_L(0); PG8_BAR; PG8_MMA(1, 0, At, B0); PG8_MMA(1, 1, At, B1); PG8_BAR; PG8_SCHED;
.LBB0_1052:
	ds_read_b128 v[146:149], v153
	ds_read_b128 v[156:159], v153 offset:1024
	ds_read_b128 v[160:163], v153 offset:2048
	ds_read_b128 v[164:167], v153 offset:3072
	ds_read_b128 v[168:171], v154
	ds_read_b128 v[172:175], v154 offset:1024
	ds_read_b128 v[176:179], v154 offset:2048
	ds_read_b128 v[180:183], v154 offset:3072
	s_add_u32 s24, s22, 0x100
	s_addc_u32 s25, s23, 0
	s_cmp_eq_u32 s56, 40
	s_cselect_b32 s29, s3, s25
	s_cselect_b32 s28, s2, s24
	s_cselect_b32 s27, s21, s55
	s_cselect_b32 s26, s20, s54
	s_add_i32 m0, s38, 0xc000
	ds_read_b128 v[184:187], v155
	ds_read_b128 v[188:191], v155 offset:1024
	ds_read_b128 v[192:195], v155 offset:2048
	ds_read_b128 v[196:199], v155 offset:3072
	ds_read_b128 v[200:203], v155 offset:4096
	ds_read_b128 v[204:207], v155 offset:5120
	ds_read_b128 v[208:211], v155 offset:6144
	ds_read_b128 v[212:215], v155 offset:7168
	global_load_lds_dwordx4 v138, s[22:23]
	s_add_i32 m0, s38, 0xe000
	s_nop 0
	global_load_lds_dwordx4 v140, s[22:23]
	s_waitcnt vmcnt(8)
	s_waitcnt lgkmcnt(0)
	s_barrier
	s_setprio 1
	v_mfma_f32_16x16x32_bf16 v[124:127], v[146:149], v[184:187], v[124:127]
	v_mfma_f32_16x16x32_bf16 v[120:123], v[160:163], v[184:187], v[120:123]
	v_mfma_f32_16x16x32_bf16 v[116:119], v[146:149], v[192:195], v[116:119]
	v_mfma_f32_16x16x32_bf16 v[112:115], v[160:163], v[192:195], v[112:115]
	v_mfma_f32_16x16x32_bf16 v[92:95], v[146:149], v[200:203], v[92:95]
	v_mfma_f32_16x16x32_bf16 v[88:91], v[160:163], v[200:203], v[88:91]
	v_mfma_f32_16x16x32_bf16 v[76:79], v[146:149], v[208:211], v[76:79]
	v_mfma_f32_16x16x32_bf16 v[72:75], v[160:163], v[208:211], v[72:75]
	v_mfma_f32_16x16x32_bf16 v[124:127], v[156:159], v[188:191], v[124:127]
	v_mfma_f32_16x16x32_bf16 v[120:123], v[164:167], v[188:191], v[120:123]
	v_mfma_f32_16x16x32_bf16 v[116:119], v[156:159], v[196:199], v[116:119]
	v_mfma_f32_16x16x32_bf16 v[112:115], v[164:167], v[196:199], v[112:115]
	v_mfma_f32_16x16x32_bf16 v[92:95], v[156:159], v[204:207], v[92:95]
	v_mfma_f32_16x16x32_bf16 v[88:91], v[164:167], v[204:207], v[88:91]
	v_mfma_f32_16x16x32_bf16 v[76:79], v[156:159], v[212:215], v[76:79]
	v_mfma_f32_16x16x32_bf16 v[72:75], v[164:167], v[212:215], v[72:75]
	v_mfma_f32_16x16x32_bf16 v[108:111], v[168:171], v[184:187], v[108:111]
	v_mfma_f32_16x16x32_bf16 v[104:107], v[176:179], v[184:187], v[104:107]
	v_mfma_f32_16x16x32_bf16 v[100:103], v[168:171], v[192:195], v[100:103]
	v_mfma_f32_16x16x32_bf16 v[96:99], v[176:179], v[192:195], v[96:99]
	v_mfma_f32_16x16x32_bf16 v[84:87], v[168:171], v[200:203], v[84:87]
	v_mfma_f32_16x16x32_bf16 v[80:83], v[176:179], v[200:203], v[80:83]
	v_mfma_f32_16x16x32_bf16 v[68:71], v[168:171], v[208:211], v[68:71]
	v_mfma_f32_16x16x32_bf16 v[64:67], v[176:179], v[208:211], v[64:67]
	v_mfma_f32_16x16x32_bf16 v[108:111], v[172:175], v[188:191], v[108:111]
	v_mfma_f32_16x16x32_bf16 v[104:107], v[180:183], v[188:191], v[104:107]
	v_mfma_f32_16x16x32_bf16 v[100:103], v[172:175], v[196:199], v[100:103]
	v_mfma_f32_16x16x32_bf16 v[96:99], v[180:183], v[196:199], v[96:99]
	v_mfma_f32_16x16x32_bf16 v[84:87], v[172:175], v[204:207], v[84:87]
	v_mfma_f32_16x16x32_bf16 v[80:83], v[180:183], v[204:207], v[80:83]
	v_mfma_f32_16x16x32_bf16 v[68:71], v[172:175], v[212:215], v[68:71]
	v_mfma_f32_16x16x32_bf16 v[64:67], v[180:183], v[212:215], v[64:67]
	s_add_i32 s22, s46, s37
	v_lshl_add_u64 v[150:151], s[26:27], 0, v[130:131]
	s_setprio 0
	s_barrier
	s_mov_b32 m0, s22
	ds_read_b128 v[184:187], v155 offset:16384
	ds_read_b128 v[188:191], v155 offset:17408
	ds_read_b128 v[192:195], v155 offset:18432
	ds_read_b128 v[196:199], v155 offset:19456
	ds_read_b128 v[200:203], v155 offset:20480
	ds_read_b128 v[204:207], v155 offset:21504
	ds_read_b128 v[208:211], v155 offset:22528
	ds_read_b128 v[212:215], v155 offset:23552
	global_load_lds_dwordx4 v[150:151], off
	s_add_i32 m0, s22, 0x2000
	s_add_u32 s22, s26, 0xb0000
	v_lshl_add_u64 v[216:217], s[26:27], 0, v[134:135]
	s_addc_u32 s23, s27, 0
	s_add_i32 s57, s47, s37
	global_load_lds_dwordx4 v[216:217], off
	s_mov_b32 m0, s57
	v_lshl_add_u64 v[220:221], s[28:29], 0, v[132:133]
	global_load_lds_dwordx4 v130, s[22:23]
	s_add_i32 m0, s57, 0x2000
	s_nop 0
	global_load_lds_dwordx4 v134, s[22:23]
	v_lshl_add_u64 v[218:219], s[28:29], 0, v[128:129]
	s_mov_b32 m0, s38
	s_nop 0
	global_load_lds_dwordx4 v[218:219], off
	s_mov_b32 m0, s39
	s_nop 0
	global_load_lds_dwordx4 v[220:221], off
	s_waitcnt vmcnt(8)
	s_waitcnt lgkmcnt(0)
	s_barrier
	s_setprio 1
	v_mfma_f32_16x16x32_bf16 v[60:63], v[146:149], v[184:187], v[60:63]
	v_mfma_f32_16x16x32_bf16 v[56:59], v[160:163], v[184:187], v[56:59]
	v_mfma_f32_16x16x32_bf16 v[44:47], v[146:149], v[192:195], v[44:47]
	v_mfma_f32_16x16x32_bf16 v[40:43], v[160:163], v[192:195], v[40:43]
	v_mfma_f32_16x16x32_bf16 v[28:31], v[146:149], v[200:203], v[28:31]
	v_mfma_f32_16x16x32_bf16 v[24:27], v[160:163], v[200:203], v[24:27]
	v_mfma_f32_16x16x32_bf16 v[12:15], v[146:149], v[208:211], v[12:15]
	v_mfma_f32_16x16x32_bf16 v[8:11], v[160:163], v[208:211], v[8:11]
	v_mfma_f32_16x16x32_bf16 v[60:63], v[156:159], v[188:191], v[60:63]
	v_mfma_f32_16x16x32_bf16 v[56:59], v[164:167], v[188:191], v[56:59]
	v_mfma_f32_16x16x32_bf16 v[44:47], v[156:159], v[196:199], v[44:47]
	v_mfma_f32_16x16x32_bf16 v[40:43], v[164:167], v[196:199], v[40:43]
	v_mfma_f32_16x16x32_bf16 v[28:31], v[156:159], v[204:207], v[28:31]
	v_mfma_f32_16x16x32_bf16 v[24:27], v[164:167], v[204:207], v[24:27]
	v_mfma_f32_16x16x32_bf16 v[12:15], v[156:159], v[212:215], v[12:15]
	v_mfma_f32_16x16x32_bf16 v[8:11], v[164:167], v[212:215], v[8:11]
	v_mfma_f32_16x16x32_bf16 v[52:55], v[168:171], v[184:187], v[52:55]
	v_mfma_f32_16x16x32_bf16 v[48:51], v[176:179], v[184:187], v[48:51]
	v_mfma_f32_16x16x32_bf16 v[36:39], v[168:171], v[192:195], v[36:39]
	v_mfma_f32_16x16x32_bf16 v[32:35], v[176:179], v[192:195], v[32:35]
	v_mfma_f32_16x16x32_bf16 v[20:23], v[168:171], v[200:203], v[20:23]
	v_mfma_f32_16x16x32_bf16 v[16:19], v[176:179], v[200:203], v[16:19]
	v_mfma_f32_16x16x32_bf16 v[4:7], v[168:171], v[208:211], v[4:7]
	v_mfma_f32_16x16x32_bf16 v[0:3], v[176:179], v[208:211], v[0:3]
	v_mfma_f32_16x16x32_bf16 v[52:55], v[172:175], v[188:191], v[52:55]
	v_mfma_f32_16x16x32_bf16 v[48:51], v[180:183], v[188:191], v[48:51]
	v_mfma_f32_16x16x32_bf16 v[36:39], v[172:175], v[196:199], v[36:39]
	v_mfma_f32_16x16x32_bf16 v[32:35], v[180:183], v[196:199], v[32:35]
	v_mfma_f32_16x16x32_bf16 v[20:23], v[172:175], v[204:207], v[20:23]
	v_mfma_f32_16x16x32_bf16 v[16:19], v[180:183], v[204:207], v[16:19]
	v_mfma_f32_16x16x32_bf16 v[4:7], v[172:175], v[212:215], v[4:7]
	v_mfma_f32_16x16x32_bf16 v[0:3], v[180:183], v[212:215], v[0:3]
	s_add_i32 s57, 0, 0x18000
	s_add_i32 s58, 0, 0x1c000
	v_add_u32_e32 v164, s57, v152
	v_add_u32_e32 v180, s58, v152
	s_setprio 0
	s_barrier
; #define PG8_STAGE(bufoff, gbase, voff) do { _Pragma("unroll") for (int _i = 0; _i < 2; ++_i) \
;         __builtin_amdgcn_global_load_lds((const unsigned*)((const char*)(gbase) + (voff)[_i]), (PG8_LAS unsigned*)(lds + (bufoff) + ldsw + _i * 8192), 16, 0, 0); } while (0)
; #define PG8_LDA(dst, b, h) do { _Pragma("unroll") for (int m = 0; m < 4; ++m) _Pragma("unroll") for (int k = 0; k < 2; ++k) dst[m][k] = *(const PG8_LAS bf16x8*)(lds + PG8_SA(b, h) + aoff + m * 2048 + k * 1024); } while (0)
; #define PG8_LDB(dst, b, h) do { _Pragma("unroll") for (int n = 0; n < 2; ++n) _Pragma("unroll") for (int k = 0; k < 2; ++k) dst[n][k] = *(const PG8_LAS bf16x8*)(lds + PG8_SB(b, h) + boff + n * 2048 + k * 1024); } while (0)
; #define PG8_WAIT_V(n) asm volatile("s_waitcnt vmcnt(" #n ")" ::: "memory")
; #define PG8_WAIT_L(n) asm volatile("s_waitcnt lgkmcnt(" #n ")" ::: "memory")
; #define PG8_BAR __builtin_amdgcn_s_barrier()
; #define PG8_SCHED __builtin_amdgcn_sched_barrier(0)
; template <class Epi, class Sched, bool ALIGN_EPI = false, bool SP2 = false>
; __device__ __forceinline__ void gemm_phase(PG8_LAS unsigned char* lds, const Gemm g, const Sched& S, const Epi& E) {
;     ...
;         for (int t = 0; t < nt; t += 2) {
;             const bool last = (t == nt - 2);
;             const char* a1 = cA + (size_t)(t + 1) * kstep;
;             const char* a2 = last ? nA : cA + (size_t)(t + 2) * kstep; const char* b2 = last ? nB : cB + (size_t)(t + 2) * kstep;
;             const char* a3 = a2 + kstep; const char* b3 = b2 + kstep;
;     ...
;             PG8_LDA(At, 0, 1); PG8_STAGE(PG8_SB(0, 0), b2, voffB); PG8_STAGE(PG8_SB(0, 1), b2 + hstep, voffB); PG8_STAGE(PG8_SA(0, 0), a2, voffA);
;             PG8_WAIT_V(8); PG8_WAIT_L(0); PG8_BAR; PG8_MMA(1, 0, At, B0); PG8_MMA(1, 1, At, B1); PG8_BAR; PG8_SCHED;
;             PG8_LDB(B0, 1, 0); PG8_LDB(B1, 1, 1); PG8_SCHED; PG8_LDA(At, 1, 0); PG8_STAGE(PG8_SA(0, 1), a2 + hstep, voffA);
;             PG8_WAIT_V(8); PG8_WAIT_L(0); PG8_BAR; PG8_MMA(0, 0, At, B0); PG8_MMA(0, 1, At, B1); PG8_BAR; PG8_SCHED;
;             PG8_LDA(At, 1, 1); PG8_STAGE(PG8_SB(1, 0), b3, voffB); PG8_STAGE(PG8_SB(1, 1), b3 + hstep, voffB); PG8_STAGE(PG8_SA(1, 0), a3, voffA);
;             PG8_WAIT_V(8); PG8_WAIT_L(0); PG8_BAR; PG8_MMA(1, 0, At, B0); PG8_MMA(1, 1, At, B1); PG8_BAR; PG8_SCHED;
	ds_read_b128 v[146:149], v164
	ds_read_b128 v[156:159], v164 offset:1024
	ds_read_b128 v[160:163], v164 offset:2048
	ds_read_b128 v[164:167], v164 offset:3072
	ds_read_b128 v[168:171], v180
	ds_read_b128 v[172:175], v180 offset:1024
	ds_read_b128 v[176:179], v180 offset:2048
	ds_read_b128 v[180:183], v180 offset:3072
	s_add_u32 s22, s28, 0xb0000
	s_addc_u32 s23, s29, 0
	s_mov_b32 m0, s40
	ds_read_b128 v[184:187], v155 offset:32768
	ds_read_b128 v[188:191], v155 offset:33792
	ds_read_b128 v[192:195], v155 offset:34816
	ds_read_b128 v[196:199], v155 offset:35840
	ds_read_b128 v[200:203], v155 offset:36864
	ds_read_b128 v[204:207], v155 offset:37888
	ds_read_b128 v[208:211], v155 offset:38912
	ds_read_b128 v[212:215], v155 offset:39936
	global_load_lds_dwordx4 v128, s[22:23]
	s_mov_b32 m0, s41
	s_nop 0
	global_load_lds_dwordx4 v132, s[22:23]
	s_waitcnt vmcnt(8)
	s_waitcnt lgkmcnt(0)
	s_barrier
	s_setprio 1
	v_mfma_f32_16x16x32_bf16 v[124:127], v[146:149], v[184:187], v[124:127]
	v_mfma_f32_16x16x32_bf16 v[120:123], v[160:163], v[184:187], v[120:123]
	v_mfma_f32_16x16x32_bf16 v[116:119], v[146:149], v[192:195], v[116:119]
	v_mfma_f32_16x16x32_bf16 v[112:115], v[160:163], v[192:195], v[112:115]
	v_mfma_f32_16x16x32_bf16 v[92:95], v[146:149], v[200:203], v[92:95]
	v_mfma_f32_16x16x32_bf16 v[88:91], v[160:163], v[200:203], v[88:91]
	v_mfma_f32_16x16x32_bf16 v[76:79], v[146:149], v[208:211], v[76:79]
	v_mfma_f32_16x16x32_bf16 v[72:75], v[160:163], v[208:211], v[72:75]
	v_mfma_f32_16x16x32_bf16 v[124:127], v[156:159], v[188:191], v[124:127]
	v_mfma_f32_16x16x32_bf16 v[120:123], v[164:167], v[188:191], v[120:123]
	v_mfma_f32_16x16x32_bf16 v[116:119], v[156:159], v[196:199], v[116:119]
	v_mfma_f32_16x16x32_bf16 v[112:115], v[164:167], v[196:199], v[112:115]
	v_mfma_f32_16x16x32_bf16 v[92:95], v[156:159], v[204:207], v[92:95]
	v_mfma_f32_16x16x32_bf16 v[88:91], v[164:167], v[204:207], v[88:91]
	v_mfma_f32_16x16x32_bf16 v[76:79], v[156:159], v[212:215], v[76:79]
	v_mfma_f32_16x16x32_bf16 v[72:75], v[164:167], v[212:215], v[72:75]
	v_mfma_f32_16x16x32_bf16 v[108:111], v[168:171], v[184:187], v[108:111]
	v_mfma_f32_16x16x32_bf16 v[104:107], v[176:179], v[184:187], v[104:107]
	v_mfma_f32_16x16x32_bf16 v[100:103], v[168:171], v[192:195], v[100:103]
	v_mfma_f32_16x16x32_bf16 v[96:99], v[176:179], v[192:195], v[96:99]
	v_mfma_f32_16x16x32_bf16 v[84:87], v[168:171], v[200:203], v[84:87]
	v_mfma_f32_16x16x32_bf16 v[80:83], v[176:179], v[200:203], v[80:83]
	v_mfma_f32_16x16x32_bf16 v[68:71], v[168:171], v[208:211], v[68:71]
	v_mfma_f32_16x16x32_bf16 v[64:67], v[176:179], v[208:211], v[64:67]
	v_mfma_f32_16x16x32_bf16 v[108:111], v[172:175], v[188:191], v[108:111]
	v_mfma_f32_16x16x32_bf16 v[104:107], v[180:183], v[188:191], v[104:107]
	v_mfma_f32_16x16x32_bf16 v[100:103], v[172:175], v[196:199], v[100:103]
	v_mfma_f32_16x16x32_bf16 v[96:99], v[180:183], v[196:199], v[96:99]
	v_mfma_f32_16x16x32_bf16 v[84:87], v[172:175], v[204:207], v[84:87]
	v_mfma_f32_16x16x32_bf16 v[80:83], v[180:183], v[204:207], v[80:83]
	v_mfma_f32_16x16x32_bf16 v[68:71], v[172:175], v[212:215], v[68:71]
	v_mfma_f32_16x16x32_bf16 v[64:67], v[180:183], v[212:215], v[64:67]
	s_add_i32 s22, s57, s37
	v_lshl_add_u64 v[150:151], v[150:151], 0, s[8:9]
	s_setprio 0
	s_barrier
	s_mov_b32 m0, s22
	ds_read_b128 v[184:187], v155 offset:49152
	ds_read_b128 v[188:191], v155 offset:50176
	ds_read_b128 v[192:195], v155 offset:51200
	ds_read_b128 v[196:199], v155 offset:52224
	ds_read_b128 v[200:203], v155 offset:53248
	ds_read_b128 v[204:207], v155 offset:54272
	ds_read_b128 v[208:211], v155 offset:55296
	ds_read_b128 v[212:215], v155 offset:56320
	global_load_lds_dwordx4 v[150:151], off
	s_add_i32 m0, s22, 0x2000
	s_add_u32 s22, s26, 0xb0080
	v_lshl_add_u64 v[150:151], v[216:217], 0, s[8:9]
	s_addc_u32 s23, s27, 0
	s_add_i32 s26, s58, s37
	global_load_lds_dwordx4 v[150:151], off
	s_mov_b32 m0, s26
	s_nop 0
	global_load_lds_dwordx4 v130, s[22:23]
	s_add_i32 m0, s26, 0x2000
	s_nop 0
	global_load_lds_dwordx4 v134, s[22:23]
	v_lshl_add_u64 v[150:151], v[218:219], 0, s[8:9]
	s_mov_b32 m0, s43
	s_nop 0
	global_load_lds_dwordx4 v[150:151], off
	v_lshl_add_u64 v[150:151], v[220:221], 0, s[8:9]
	s_mov_b32 m0, s44
	s_nop 0
	global_load_lds_dwordx4 v[150:151], off
	s_waitcnt vmcnt(8)
	s_waitcnt lgkmcnt(0)
	s_barrier
	s_setprio 1
	v_mfma_f32_16x16x32_bf16 v[60:63], v[146:149], v[184:187], v[60:63]
	v_mfma_f32_16x16x32_bf16 v[56:59], v[160:163], v[184:187], v[56:59]
	v_mfma_f32_16x16x32_bf16 v[44:47], v[146:149], v[192:195], v[44:47]
	v_mfma_f32_16x16x32_bf16 v[40:43], v[160:163], v[192:195], v[40:43]
	v_mfma_f32_16x16x32_bf16 v[28:31], v[146:149], v[200:203], v[28:31]
	v_mfma_f32_16x16x32_bf16 v[24:27], v[160:163], v[200:203], v[24:27]
	v_mfma_f32_16x16x32_bf16 v[12:15], v[146:149], v[208:211], v[12:15]
	v_mfma_f32_16x16x32_bf16 v[8:11], v[160:163], v[208:211], v[8:11]
	v_mfma_f32_16x16x32_bf16 v[60:63], v[156:159], v[188:191], v[60:63]
	v_mfma_f32_16x16x32_bf16 v[56:59], v[164:167], v[188:191], v[56:59]
	v_mfma_f32_16x16x32_bf16 v[44:47], v[156:159], v[196:199], v[44:47]
	v_mfma_f32_16x16x32_bf16 v[40:43], v[164:167], v[196:199], v[40:43]
	v_mfma_f32_16x16x32_bf16 v[28:31], v[156:159], v[204:207], v[28:31]
	v_mfma_f32_16x16x32_bf16 v[24:27], v[164:167], v[204:207], v[24:27]
	v_mfma_f32_16x16x32_bf16 v[12:15], v[156:159], v[212:215], v[12:15]
	v_mfma_f32_16x16x32_bf16 v[8:11], v[164:167], v[212:215], v[8:11]
	v_mfma_f32_16x16x32_bf16 v[52:55], v[168:171], v[184:187], v[52:55]
	v_mfma_f32_16x16x32_bf16 v[48:51], v[176:179], v[184:187], v[48:51]
	v_mfma_f32_16x16x32_bf16 v[36:39], v[168:171], v[192:195], v[36:39]
	v_mfma_f32_16x16x32_bf16 v[32:35], v[176:179], v[192:195], v[32:35]
	v_mfma_f32_16x16x32_bf16 v[20:23], v[168:171], v[200:203], v[20:23]
	v_mfma_f32_16x16x32_bf16 v[16:19], v[176:179], v[200:203], v[16:19]
	v_mfma_f32_16x16x32_bf16 v[4:7], v[168:171], v[208:211], v[4:7]
	v_mfma_f32_16x16x32_bf16 v[0:3], v[176:179], v[208:211], v[0:3]
	v_mfma_f32_16x16x32_bf16 v[52:55], v[172:175], v[188:191], v[52:55]
	v_mfma_f32_16x16x32_bf16 v[48:51], v[180:183], v[188:191], v[48:51]
	v_mfma_f32_16x16x32_bf16 v[36:39], v[172:175], v[196:199], v[36:39]
	v_mfma_f32_16x16x32_bf16 v[32:35], v[180:183], v[196:199], v[32:35]
	v_mfma_f32_16x16x32_bf16 v[20:23], v[172:175], v[204:207], v[20:23]
	v_mfma_f32_16x16x32_bf16 v[16:19], v[180:183], v[204:207], v[16:19]
	v_mfma_f32_16x16x32_bf16 v[4:7], v[172:175], v[212:215], v[4:7]
	v_mfma_f32_16x16x32_bf16 v[0:3], v[180:183], v[212:215], v[0:3]
	s_add_i32 s56, s56, 2
	s_add_u32 s54, s54, 0x100
	s_addc_u32 s55, s55, 0
	s_cmp_gt_u32 s56, 41
	s_mov_b64 s[22:23], s[24:25]
	s_setprio 0
	s_barrier
	s_cbranch_scc0 .LBB0_1052
	s_and_b64 vcc, exec, s[10:11]
	s_cbranch_vccz .LBB0_1055
	s_barrier
